# bf16 residual-stream (H) stores in the residual epilogues made non-temporal (re-read only two phases later); HB operand stores stay cached
# speedup vs baseline: 1.0021x; 1.0021x over previous
;     __device__ __forceinline__ void operator()(const f32x4 (&acc)[2][2][4][2], const Unit& u, int wr, int wc, int fr, int fq) const {
;         const int row0 = u.pm * 256 + wr * 64 + fr, col0 = u.pn * 256 + wc * 32 + 8 * fq;
;         const int mb = u.pm < 64 ? (u.pm >> 4) : 4;
;         float* SSn = (float*)(ws + WS_SS) + ss_off;
;         const float* gate = (const float*)(ws + WS_MOD) + gate_off + (size_t)mb * 9216; const float* gn = (const float*)(ws + WS_NG) + gn_off; const float* scn = (const float*)(ws + WS_MOD) + scn_off + (size_t)mb * 9216;
;         f32x4 gv[2][2], bv[2][2], wv[2][2];
; #pragma unroll
;         for (int bj = 0; bj < 2; ++bj)
; #pragma unroll
;             for (int n = 0; n < 2; ++n) { const int cc = col0 + bj * 128 + 4 * n;
;                 gv[bj][n] = *(const f32x4*)(gate + cc) * gmul;
;                 bv[bj][n] = HASBIAS ? *(const f32x4*)(bias + cc) : (f32x4){0.f, 0.f, 0.f, 0.f};
;                 wv[bj][n] = FUSE ? *(const f32x4*)(gn + cc) * (*(const f32x4*)(scn + cc) + 1.0f) : (f32x4){0.f, 0.f, 0.f, 0.f}; }
;         const unsigned e0 = (unsigned)(row0 * D + col0);
;         const char* bsc = (const char*)base0; char* Hc = (char*)(ws + WS_H); char* HBc = (char*)(ws + WS_XN);
;         constexpr int RGB = 2;
; #pragma unroll
;         for (int rg = 0; rg < 8 / RGB; ++rg) {
;             u32x4 braw[INPLACE ? RGB : 1][2]; f32x4 bb[INPLACE ? 1 : RGB][2][2];
; #pragma unroll
;             for (int mm = 0; mm < RGB; ++mm) { const int q = rg * RGB + mm, ai = q >> 2, m = q & 3;
; #pragma unroll
;                 for (int bj = 0; bj < 2; ++bj) { const unsigned e = e0 + (unsigned)((ai * 128 + m * 16) * D + bj * 128);
;                     if constexpr (INPLACE) braw[mm][bj] = *(const u32x4*)(Hc + (size_t)(e * 2u));
;                     else { bb[mm][bj][0] = *(const f32x4*)(bsc + (size_t)(e * 4u)); bb[mm][bj][1] = *(const f32x4*)(bsc + (size_t)(e * 4u + 16u)); } } }
; #pragma unroll
;             for (int mm = 0; mm < RGB; ++mm) { const int q = rg * RGB + mm, ai = q >> 2, m = q & 3; float ssum = 0.f;
; #pragma unroll
;                 for (int bj = 0; bj < 2; ++bj) { const unsigned e = e0 + (unsigned)((ai * 128 + m * 16) * D + bj * 128);
;                     f32x4 r0, r1;
;                     if constexpr (INPLACE) { const u32x4 q4 = braw[mm][bj];
.LBB0_313:
	s_ashr_i32 s38, s66, 4
	v_lshl_or_b32 v20, s65, 8, v195
	s_mul_i32 s40, s38, 0x9000
	s_mul_hi_i32 s41, s38, 0x9000
	s_add_u32 s38, s57, s40
	v_ashrrev_i32_e32 v21, 31, v20
	s_addc_u32 s39, s58, s41
	v_lshlrev_b64 v[12:13], 2, v[20:21]
	v_lshl_add_u64 v[22:23], s[38:39], 0, v[12:13]
	s_waitcnt lgkmcnt(0)
	global_load_dwordx4 v[0:3], v[22:23], off offset:16
	global_load_dwordx4 v[4:7], v[22:23], off
	s_add_u32 s40, s59, s40
	s_addc_u32 s41, s60, s41
	v_lshl_add_u64 v[8:9], s[22:23], 0, v[12:13]
	v_lshl_add_u64 v[72:73], s[40:41], 0, v[12:13]
	v_lshl_add_u32 v136, s66, 8, v183
	v_lshl_add_u32 v233, v136, 10, v20
	v_lshlrev_b32_e32 v231, 2, v233
	v_add_u32_e32 v232, 0x10000, v231
	s_waitcnt vmcnt(0)
	v_pk_mul_f32 v[102:103], v[2:3], 0.5 op_sel_hi:[1,0]
	v_pk_mul_f32 v[100:101], v[6:7], 0.5 op_sel_hi:[1,0]
	v_pk_mul_f32 v[98:99], v[4:5], 0.5 op_sel_hi:[1,0]
	global_load_dwordx4 v[4:7], v[8:9], off offset:16
	s_nop 0
	global_load_dwordx4 v[8:11], v[8:9], off
	s_nop 0
	global_load_dwordx4 v[12:15], v[72:73], off offset:16
	global_load_dwordx4 v[16:19], v[72:73], off
	v_pk_mul_f32 v[96:97], v[0:1], 0.5 op_sel_hi:[1,0]
	s_waitcnt vmcnt(0)
	v_pk_add_f32 v[0:1], v[14:15], 1.0 op_sel_hi:[1,0]
	v_pk_add_f32 v[2:3], v[12:13], 1.0 op_sel_hi:[1,0]
	v_pk_mul_f32 v[78:79], v[6:7], v[0:1]
	v_pk_mul_f32 v[80:81], v[4:5], v[2:3]
	global_load_dwordx4 v[0:3], v[22:23], off offset:528
	global_load_dwordx4 v[4:7], v[22:23], off offset:512
	v_pk_add_f32 v[16:17], v[16:17], 1.0 op_sel_hi:[1,0]
	v_pk_add_f32 v[18:19], v[18:19], 1.0 op_sel_hi:[1,0]
	v_pk_mul_f32 v[76:77], v[8:9], v[16:17]
	v_or_b32_e32 v8, 0x80, v20
	v_ashrrev_i32_e32 v9, 31, v8
	v_lshl_add_u64 v[8:9], v[8:9], 2, s[22:23]
	v_pk_mul_f32 v[74:75], v[10:11], v[18:19]
	s_waitcnt vmcnt(0)
	v_pk_mul_f32 v[118:119], v[2:3], 0.5 op_sel_hi:[1,0]
	v_pk_mul_f32 v[116:117], v[6:7], 0.5 op_sel_hi:[1,0]
	v_pk_mul_f32 v[114:115], v[4:5], 0.5 op_sel_hi:[1,0]
	global_load_dwordx4 v[4:7], v[8:9], off offset:16
	s_nop 0
	global_load_dwordx4 v[8:11], v[8:9], off
	s_nop 0
	global_load_dwordx4 v[12:15], v[72:73], off offset:528
	global_load_dwordx4 v[16:19], v[72:73], off offset:512
	v_pk_mul_f32 v[112:113], v[0:1], 0.5 op_sel_hi:[1,0]
	s_waitcnt vmcnt(0)
	v_pk_add_f32 v[2:3], v[12:13], 1.0 op_sel_hi:[1,0]
	v_pk_add_f32 v[18:19], v[18:19], 1.0 op_sel_hi:[1,0]
	v_pk_add_f32 v[16:17], v[16:17], 1.0 op_sel_hi:[1,0]
	v_pk_mul_f32 v[90:91], v[10:11], v[18:19]
	v_pk_mul_f32 v[72:73], v[8:9], v[16:17]
	global_load_dwordx4 v[234:237], v231, s[16:17] offset:16
	global_load_dwordx4 v[238:241], v231, s[16:17]
	global_load_dwordx4 v[16:19], v231, s[16:17] offset:528
	global_load_dwordx4 v[20:23], v231, s[16:17] offset:512
	v_pk_add_f32 v[0:1], v[14:15], 1.0 op_sel_hi:[1,0]
	v_pk_mul_f32 v[84:85], v[4:5], v[2:3]
	v_add_u32_e32 v4, 0x10200, v231
	v_pk_mul_f32 v[82:83], v[6:7], v[0:1]
	global_load_dwordx4 v[8:11], v232, s[16:17] offset:16
	global_load_dwordx4 v[12:15], v232, s[16:17]
	global_load_dwordx4 v[0:3], v4, s[16:17] offset:16
	s_nop 0
	global_load_dwordx4 v[4:7], v4, s[16:17]
	s_waitcnt vmcnt(0)
	v_pk_fma_f32 v[236:237], v[214:215], v[102:103], v[236:237]
	v_pk_fma_f32 v[240:241], v[210:211], v[100:101], v[240:241]
	v_pk_fma_f32 v[238:239], v[212:213], v[98:99], v[238:239]
	v_lshlrev_b32_e32 v210, 1, v233
	v_cvt_pk_bf16_f32 v212, v238, v239
	v_pk_fma_f32 v[216:217], v[216:217], v[96:97], v[234:235]
	v_cvt_pk_bf16_f32 v213, v240, v241
	v_mul_f32_e32 v211, v239, v239
	v_cvt_pk_bf16_f32 v214, v216, v217
	v_cvt_pk_bf16_f32 v215, v236, v237
	global_store_dwordx4 v210, v[212:215], s[26:27] nt
	v_fmac_f32_e32 v211, v238, v238
	v_pk_mul_f32 v[234:235], v[78:79], v[236:237]
	v_mul_f32_e32 v212, v241, v241
	v_fmac_f32_e32 v212, v240, v240
	v_add_f32_e32 v211, v211, v212
	v_mul_f32_e32 v212, v217, v217
	v_mul_f32_e32 v213, v237, v237
	v_fmac_f32_e32 v212, v216, v216
	v_fmac_f32_e32 v213, v236, v236
	v_add_f32_e32 v212, v212, v213
	v_add_f32_e32 v211, v211, v212
	v_pk_mul_f32 v[214:215], v[74:75], v[240:241]
	v_pk_mul_f32 v[212:213], v[76:77], v[238:239]
	v_pk_mul_f32 v[216:217], v[80:81], v[216:217]
	v_cvt_pk_bf16_f32 v212, v212, v213
	v_cvt_pk_bf16_f32 v213, v214, v215
	v_pk_fma_f32 v[22:23], v[208:209], v[116:117], v[22:23]
	v_cvt_pk_bf16_f32 v214, v216, v217
	v_cvt_pk_bf16_f32 v215, v234, v235
	global_store_dwordx4 v210, v[212:215], s[72:73]
	v_pk_fma_f32 v[20:21], v[206:207], v[114:115], v[20:21]
	v_pk_fma_f32 v[202:203], v[202:203], v[112:113], v[16:17]
	v_cvt_pk_bf16_f32 v16, v20, v21
	v_cvt_pk_bf16_f32 v17, v22, v23
	v_or_b32_e32 v206, 0x100, v210
	v_pk_fma_f32 v[204:205], v[204:205], v[118:119], v[18:19]
	v_cvt_pk_bf16_f32 v18, v202, v203
	s_nop 0
	v_cvt_pk_bf16_f32 v19, v204, v205
	global_store_dwordx4 v206, v[16:19], s[26:27] nt
	s_nop 1
	v_mul_f32_e32 v16, v21, v21
	v_mul_f32_e32 v17, v23, v23
	v_fmac_f32_e32 v16, v20, v20
	v_fmac_f32_e32 v17, v22, v22
	v_add_f32_e32 v16, v16, v17
	v_mul_f32_e32 v17, v203, v203
	v_mul_f32_e32 v18, v205, v205
	v_fmac_f32_e32 v17, v202, v202
	v_fmac_f32_e32 v18, v204, v204
	v_add_f32_e32 v17, v17, v18
	v_add_f32_e32 v16, v16, v17
	v_add_f32_e32 v207, v211, v16
	v_pk_mul_f32 v[16:17], v[72:73], v[20:21]
	v_pk_mul_f32 v[18:19], v[90:91], v[22:23]
	v_cvt_pk_bf16_f32 v16, v16, v17
	v_pk_mul_f32 v[20:21], v[82:83], v[204:205]
	v_cvt_pk_bf16_f32 v17, v18, v19
	v_pk_mul_f32 v[22:23], v[84:85], v[202:203]
	s_nop 0
	v_cvt_pk_bf16_f32 v18, v22, v23
	v_cvt_pk_bf16_f32 v19, v20, v21
	global_store_dwordx4 v206, v[16:19], s[72:73]
	s_nop 1
	v_and_b32_e32 v17, 64, v230
	v_xor_b32_e32 v16, 16, v230
	v_add_u32_e32 v17, 64, v17
	v_cmp_lt_i32_e32 vcc, v16, v17
	v_xor_b32_e32 v19, 32, v230
	s_nop 0
	v_cndmask_b32_e32 v16, v230, v16, vcc
	v_lshlrev_b32_e32 v16, 2, v16
	ds_bpermute_b32 v18, v16, v207
	v_cmp_lt_i32_e32 vcc, v19, v17
	s_waitcnt lgkmcnt(0)
	v_add_f32_e32 v18, v207, v18
	v_cndmask_b32_e32 v17, v230, v19, vcc
	v_lshlrev_b32_e32 v17, 2, v17
	ds_bpermute_b32 v19, v17, v18
	s_and_saveexec_b64 s[38:39], s[0:1]
	s_cbranch_execz .LBB0_315
	v_lshl_add_u64 v[20:21], v[136:137], 2, s[24:25]
	s_waitcnt lgkmcnt(0)
	v_add_f32_e32 v18, v18, v19
	global_atomic_add_f32 v[20:21], v18, off
;     __device__ __forceinline__ void operator()(const f32x4 (&acc)[2][2][4][2], const Unit& u, int wr, int wc, int fr, int fq) const {
;     ...
;         for (int rg = 0; rg < 8 / RGB; ++rg) {
;             u32x4 braw[INPLACE ? RGB : 1][2]; f32x4 bb[INPLACE ? 1 : RGB][2][2];
; #pragma unroll
;             for (int mm = 0; mm < RGB; ++mm) { const int q = rg * RGB + mm, ai = q >> 2, m = q & 3;
; #pragma unroll
;                 for (int bj = 0; bj < 2; ++bj) { const unsigned e = e0 + (unsigned)((ai * 128 + m * 16) * D + bj * 128);
;                     if constexpr (INPLACE) braw[mm][bj] = *(const u32x4*)(Hc + (size_t)(e * 2u));
;                     else { bb[mm][bj][0] = *(const f32x4*)(bsc + (size_t)(e * 4u)); bb[mm][bj][1] = *(const f32x4*)(bsc + (size_t)(e * 4u + 16u)); } } }
; #pragma unroll
;             for (int mm = 0; mm < RGB; ++mm) { const int q = rg * RGB + mm, ai = q >> 2, m = q & 3; float ssum = 0.f;
; #pragma unroll
;                 for (int bj = 0; bj < 2; ++bj) { const unsigned e = e0 + (unsigned)((ai * 128 + m * 16) * D + bj * 128);
;                     f32x4 r0, r1;
;                     if constexpr (INPLACE) { const u32x4 q4 = braw[mm][bj];
;                         r0 = (f32x4){__uint_as_float(q4[0] << 16), __uint_as_float(q4[0] & 0xffff0000u), __uint_as_float(q4[1] << 16), __uint_as_float(q4[1] & 0xffff0000u)};
;                         r1 = (f32x4){__uint_as_float(q4[2] << 16), __uint_as_float(q4[2] & 0xffff0000u), __uint_as_float(q4[3] << 16), __uint_as_float(q4[3] & 0xffff0000u)}; }
;                     else { r0 = bb[mm][bj][0]; r1 = bb[mm][bj][1]; }
;                     const f32x4 h0 = r0 + gv[bj][0] * (acc[ai][bj][m][0] + bv[bj][0]), h1 = r1 + gv[bj][1] * (acc[ai][bj][m][1] + bv[bj][1]);
;                     { u32x4 w; w.x = cvt_pk_bf16(h0[0], h0[1]); w.y = cvt_pk_bf16(h0[2], h0[3]); w.z = cvt_pk_bf16(h1[0], h1[1]); w.w = cvt_pk_bf16(h1[2], h1[3]); ST16(1, Hc + (size_t)(e * 2u), w); }
;                     if (FUSE) { ssum += ((h0[0] * h0[0] + h0[1] * h0[1]) + (h0[2] * h0[2] + h0[3] * h0[3])) + ((h1[0] * h1[0] + h1[1] * h1[1]) + (h1[2] * h1[2] + h1[3] * h1[3]));
;                         const f32x4 z0 = h0 * wv[bj][0], z1 = h1 * wv[bj][1];
;                         u32x4 w; w.x = cvt_pk_bf16(z0[0], z0[1]); w.y = cvt_pk_bf16(z0[2], z0[3]); w.z = cvt_pk_bf16(z1[0], z1[1]); w.w = cvt_pk_bf16(z1[2], z1[3]);
.LBB0_315:
	s_or_b64 exec, exec, s[38:39]
	v_pk_fma_f32 v[14:15], v[200:201], v[100:101], v[14:15]
	v_pk_fma_f32 v[12:13], v[198:199], v[98:99], v[12:13]
	v_pk_fma_f32 v[20:21], v[174:175], v[96:97], v[8:9]
	v_cvt_pk_bf16_f32 v8, v12, v13
	v_cvt_pk_bf16_f32 v9, v14, v15
	v_add_u32_e32 v22, 0x8000, v210
	s_waitcnt lgkmcnt(0)
	v_pk_fma_f32 v[18:19], v[196:197], v[102:103], v[10:11]
	v_cvt_pk_bf16_f32 v10, v20, v21
	v_pk_fma_f32 v[6:7], v[172:173], v[116:117], v[6:7]
	v_cvt_pk_bf16_f32 v11, v18, v19
	global_store_dwordx4 v22, v[8:11], s[26:27] nt
	v_pk_fma_f32 v[4:5], v[170:171], v[114:115], v[4:5]
	s_nop 0
	v_mul_f32_e32 v8, v13, v13
	v_mul_f32_e32 v9, v15, v15
	v_fmac_f32_e32 v8, v12, v12
	v_fmac_f32_e32 v9, v14, v14
	v_add_f32_e32 v8, v8, v9
	v_mul_f32_e32 v9, v21, v21
	v_mul_f32_e32 v10, v19, v19
	v_fmac_f32_e32 v9, v20, v20
	v_fmac_f32_e32 v10, v18, v18
	v_add_f32_e32 v9, v9, v10
	v_add_f32_e32 v23, v8, v9
	v_pk_mul_f32 v[10:11], v[74:75], v[14:15]
	v_pk_mul_f32 v[8:9], v[76:77], v[12:13]
	v_pk_mul_f32 v[12:13], v[78:79], v[18:19]
	v_pk_mul_f32 v[14:15], v[80:81], v[20:21]
	v_cvt_pk_bf16_f32 v8, v8, v9
	v_cvt_pk_bf16_f32 v9, v10, v11
	s_nop 0
	v_cvt_pk_bf16_f32 v10, v14, v15
	v_cvt_pk_bf16_f32 v11, v12, v13
	global_store_dwordx4 v22, v[8:11], s[72:73]
	v_add_u32_e32 v12, 0x8100, v210
	s_nop 0
	v_pk_fma_f32 v[10:11], v[166:167], v[112:113], v[0:1]
	v_cvt_pk_bf16_f32 v0, v4, v5
	v_cvt_pk_bf16_f32 v1, v6, v7
	v_pk_fma_f32 v[8:9], v[168:169], v[118:119], v[2:3]
	v_cvt_pk_bf16_f32 v2, v10, v11
	s_nop 0
	v_cvt_pk_bf16_f32 v3, v8, v9
	global_store_dwordx4 v12, v[0:3], s[26:27] nt
	s_nop 1
	v_mul_f32_e32 v0, v5, v5
	v_mul_f32_e32 v1, v7, v7
	v_fmac_f32_e32 v0, v4, v4
	v_fmac_f32_e32 v1, v6, v6
	v_add_f32_e32 v0, v0, v1
	v_mul_f32_e32 v1, v11, v11
	v_mul_f32_e32 v2, v9, v9
	v_fmac_f32_e32 v1, v10, v10
	v_fmac_f32_e32 v2, v8, v8
	v_add_f32_e32 v1, v1, v2
	v_add_f32_e32 v0, v0, v1
	v_add_f32_e32 v3, v23, v0
	ds_bpermute_b32 v13, v16, v3
	v_pk_mul_f32 v[0:1], v[72:73], v[4:5]
	v_pk_mul_f32 v[4:5], v[84:85], v[10:11]
	v_cvt_pk_bf16_f32 v2, v0, v1
	v_pk_mul_f32 v[6:7], v[90:91], v[6:7]
	s_waitcnt lgkmcnt(0)
	v_add_f32_e32 v0, v3, v13
	ds_bpermute_b32 v1, v17, v0
	v_pk_mul_f32 v[8:9], v[82:83], v[8:9]
	v_cvt_pk_bf16_f32 v3, v6, v7
	v_cvt_pk_bf16_f32 v4, v4, v5
	s_nop 0
	v_cvt_pk_bf16_f32 v5, v8, v9
	global_store_dwordx4 v12, v[2:5], s[72:73]
	s_and_saveexec_b64 s[38:39], s[0:1]
	s_cbranch_execz .LBB0_317
	v_or_b32_e32 v2, 16, v136
	v_mov_b32_e32 v3, v137
	v_lshl_add_u64 v[2:3], v[2:3], 2, s[24:25]
	s_waitcnt lgkmcnt(0)
	v_add_f32_e32 v0, v0, v1
	global_atomic_add_f32 v[2:3], v0, off
.LBB0_317:
	s_or_b64 exec, exec, s[38:39]
	v_add_u32_e32 v0, 0x20000, v231
	global_load_dwordx4 v[18:21], v0, s[16:17]
	global_load_dwordx4 v[166:169], v0, s[16:17] offset:16
	v_add_u32_e32 v0, 0x20200, v231
	global_load_dwordx4 v[170:173], v0, s[16:17]
	global_load_dwordx4 v[196:199], v0, s[16:17] offset:16
	v_add_u32_e32 v0, 0x30000, v231
	v_add_u32_e32 v4, 0x30200, v231
	global_load_dwordx4 v[8:11], v0, s[16:17] offset:16
	global_load_dwordx4 v[12:15], v0, s[16:17]
	s_waitcnt lgkmcnt(0)
	global_load_dwordx4 v[0:3], v4, s[16:17] offset:16
	s_nop 0
	global_load_dwordx4 v[4:7], v4, s[16:17]
	v_sub_u32_e32 v174, v232, v210
	v_add_u32_e32 v175, 0x10100, v210
	s_waitcnt vmcnt(7)
	v_pk_fma_f32 v[22:23], v[150:151], v[100:101], v[20:21]
	v_pk_fma_f32 v[150:151], v[152:153], v[98:99], v[18:19]
	s_waitcnt vmcnt(6)
	v_pk_fma_f32 v[152:153], v[154:155], v[102:103], v[168:169]
	v_pk_fma_f32 v[154:155], v[156:157], v[96:97], v[166:167]
	s_waitcnt vmcnt(5)
	v_pk_fma_f32 v[156:157], v[158:159], v[116:117], v[172:173]
	v_pk_fma_f32 v[158:159], v[160:161], v[114:115], v[170:171]
	s_waitcnt vmcnt(4)
	v_pk_fma_f32 v[160:161], v[162:163], v[118:119], v[198:199]
	v_pk_fma_f32 v[162:163], v[164:165], v[112:113], v[196:197]
	v_cvt_pk_bf16_f32 v18, v150, v151
	v_cvt_pk_bf16_f32 v19, v22, v23
	v_cvt_pk_bf16_f32 v20, v154, v155
	v_cvt_pk_bf16_f32 v21, v152, v153
	v_mul_f32_e32 v172, v151, v151
	v_mul_f32_e32 v173, v23, v23
	v_mul_f32_e32 v196, v155, v155
	v_mul_f32_e32 v197, v153, v153
	v_pk_mul_f32 v[164:165], v[74:75], v[22:23]
	v_pk_mul_f32 v[166:167], v[76:77], v[150:151]
	v_pk_mul_f32 v[168:169], v[78:79], v[152:153]
	v_pk_mul_f32 v[170:171], v[80:81], v[154:155]
	v_mul_f32_e32 v23, v159, v159
	v_mul_f32_e32 v151, v157, v157
	v_mul_f32_e32 v153, v163, v163
	v_mul_f32_e32 v155, v161, v161
	global_store_dwordx4 v174, v[18:21], s[26:27] nt
	v_fmac_f32_e32 v172, v150, v150
	v_fmac_f32_e32 v173, v22, v22
	v_fmac_f32_e32 v196, v154, v154
	v_fmac_f32_e32 v197, v152, v152
	v_cvt_pk_bf16_f32 v18, v166, v167
	v_fmac_f32_e32 v23, v158, v158
	v_fmac_f32_e32 v151, v156, v156
	v_fmac_f32_e32 v153, v162, v162
	v_fmac_f32_e32 v155, v160, v160
	v_cvt_pk_bf16_f32 v19, v164, v165
	v_cvt_pk_bf16_f32 v20, v170, v171
	v_cvt_pk_bf16_f32 v21, v168, v169
	v_add_f32_e32 v22, v172, v173
	v_add_f32_e32 v150, v196, v197
	global_store_dwordx4 v174, v[18:21], s[72:73]
	v_add_f32_e32 v23, v23, v151
	v_add_f32_e32 v151, v153, v155
	v_cvt_pk_bf16_f32 v18, v158, v159
	v_cvt_pk_bf16_f32 v19, v156, v157
	v_cvt_pk_bf16_f32 v20, v162, v163
	v_cvt_pk_bf16_f32 v21, v160, v161
	v_add_f32_e32 v22, v22, v150
	global_store_dwordx4 v175, v[18:21], s[26:27] nt
	v_pk_mul_f32 v[152:153], v[84:85], v[162:163]
	s_nop 0
	v_add_f32_e32 v18, v23, v151
	v_add_f32_e32 v21, v22, v18
	ds_bpermute_b32 v154, v16, v21
	v_pk_mul_f32 v[18:19], v[72:73], v[158:159]
	v_pk_mul_f32 v[22:23], v[90:91], v[156:157]
	v_cvt_pk_bf16_f32 v20, v18, v19
	v_pk_mul_f32 v[150:151], v[82:83], v[160:161]
	s_waitcnt lgkmcnt(0)
	v_add_f32_e32 v18, v21, v154
	ds_bpermute_b32 v19, v17, v18
	v_cvt_pk_bf16_f32 v21, v22, v23
	v_cvt_pk_bf16_f32 v22, v152, v153
	v_cvt_pk_bf16_f32 v23, v150, v151
	global_store_dwordx4 v175, v[20:23], s[72:73]
	s_and_saveexec_b64 s[38:39], s[0:1]
	s_cbranch_execz .LBB0_319
	v_or_b32_e32 v20, 32, v136
	v_mov_b32_e32 v21, v137
	v_lshl_add_u64 v[20:21], v[20:21], 2, s[24:25]
	s_waitcnt lgkmcnt(0)
	v_add_f32_e32 v18, v18, v19
	global_atomic_add_f32 v[20:21], v18, off
;     __device__ __forceinline__ void operator()(const f32x4 (&acc)[2][2][4][2], const Unit& u, int wr, int wc, int fr, int fq) const {
;     ...
;         for (int rg = 0; rg < 8 / RGB; ++rg) {
;             u32x4 braw[INPLACE ? RGB : 1][2]; f32x4 bb[INPLACE ? 1 : RGB][2][2];
; #pragma unroll
;             for (int mm = 0; mm < RGB; ++mm) { const int q = rg * RGB + mm, ai = q >> 2, m = q & 3;
; #pragma unroll
;                 for (int bj = 0; bj < 2; ++bj) { const unsigned e = e0 + (unsigned)((ai * 128 + m * 16) * D + bj * 128);
;                     if constexpr (INPLACE) braw[mm][bj] = *(const u32x4*)(Hc + (size_t)(e * 2u));
;                     else { bb[mm][bj][0] = *(const f32x4*)(bsc + (size_t)(e * 4u)); bb[mm][bj][1] = *(const f32x4*)(bsc + (size_t)(e * 4u + 16u)); } } }
; #pragma unroll
;             for (int mm = 0; mm < RGB; ++mm) { const int q = rg * RGB + mm, ai = q >> 2, m = q & 3; float ssum = 0.f;
; #pragma unroll
;                 for (int bj = 0; bj < 2; ++bj) { const unsigned e = e0 + (unsigned)((ai * 128 + m * 16) * D + bj * 128);
;                     f32x4 r0, r1;
;                     if constexpr (INPLACE) { const u32x4 q4 = braw[mm][bj];
;                         r0 = (f32x4){__uint_as_float(q4[0] << 16), __uint_as_float(q4[0] & 0xffff0000u), __uint_as_float(q4[1] << 16), __uint_as_float(q4[1] & 0xffff0000u)};
;                         r1 = (f32x4){__uint_as_float(q4[2] << 16), __uint_as_float(q4[2] & 0xffff0000u), __uint_as_float(q4[3] << 16), __uint_as_float(q4[3] & 0xffff0000u)}; }
;                     else { r0 = bb[mm][bj][0]; r1 = bb[mm][bj][1]; }
;                     const f32x4 h0 = r0 + gv[bj][0] * (acc[ai][bj][m][0] + bv[bj][0]), h1 = r1 + gv[bj][1] * (acc[ai][bj][m][1] + bv[bj][1]);
;                     { u32x4 w; w.x = cvt_pk_bf16(h0[0], h0[1]); w.y = cvt_pk_bf16(h0[2], h0[3]); w.z = cvt_pk_bf16(h1[0], h1[1]); w.w = cvt_pk_bf16(h1[2], h1[3]); ST16(1, Hc + (size_t)(e * 2u), w); }
;                     if (FUSE) { ssum += ((h0[0] * h0[0] + h0[1] * h0[1]) + (h0[2] * h0[2] + h0[3] * h0[3])) + ((h1[0] * h1[0] + h1[1] * h1[1]) + (h1[2] * h1[2] + h1[3] * h1[3]));
;                         const f32x4 z0 = h0 * wv[bj][0], z1 = h1 * wv[bj][1];
;                         u32x4 w; w.x = cvt_pk_bf16(z0[0], z0[1]); w.y = cvt_pk_bf16(z0[2], z0[3]); w.z = cvt_pk_bf16(z1[0], z1[1]); w.w = cvt_pk_bf16(z1[2], z1[3]);
.LBB0_319:
	s_or_b64 exec, exec, s[38:39]
	s_waitcnt vmcnt(6)
	v_pk_fma_f32 v[14:15], v[148:149], v[100:101], v[14:15]
	v_pk_fma_f32 v[12:13], v[146:147], v[98:99], v[12:13]
	v_pk_fma_f32 v[20:21], v[142:143], v[96:97], v[8:9]
	v_cvt_pk_bf16_f32 v8, v12, v13
	v_cvt_pk_bf16_f32 v9, v14, v15
	v_add_u32_e32 v22, 0x18000, v210
	s_waitcnt lgkmcnt(0)
	v_pk_fma_f32 v[18:19], v[144:145], v[102:103], v[10:11]
	v_cvt_pk_bf16_f32 v10, v20, v21
	s_waitcnt vmcnt(4)
	v_pk_fma_f32 v[6:7], v[126:127], v[116:117], v[6:7]
	v_cvt_pk_bf16_f32 v11, v18, v19
	global_store_dwordx4 v22, v[8:11], s[26:27] nt
	v_pk_fma_f32 v[4:5], v[124:125], v[114:115], v[4:5]
	s_nop 0
	v_mul_f32_e32 v8, v13, v13
	v_mul_f32_e32 v9, v15, v15
	v_fmac_f32_e32 v8, v12, v12
	v_fmac_f32_e32 v9, v14, v14
	v_add_f32_e32 v8, v8, v9
	v_mul_f32_e32 v9, v21, v21
	v_mul_f32_e32 v10, v19, v19
	v_fmac_f32_e32 v9, v20, v20
	v_fmac_f32_e32 v10, v18, v18
	v_add_f32_e32 v9, v9, v10
	v_add_f32_e32 v23, v8, v9
	v_pk_mul_f32 v[10:11], v[74:75], v[14:15]
	v_pk_mul_f32 v[8:9], v[76:77], v[12:13]
	v_pk_mul_f32 v[12:13], v[78:79], v[18:19]
	v_pk_mul_f32 v[14:15], v[80:81], v[20:21]
	v_cvt_pk_bf16_f32 v8, v8, v9
	v_cvt_pk_bf16_f32 v9, v10, v11
	s_nop 0
	v_cvt_pk_bf16_f32 v10, v14, v15
	v_cvt_pk_bf16_f32 v11, v12, v13
	global_store_dwordx4 v22, v[8:11], s[72:73]
	v_add_u32_e32 v12, 0x18100, v210
	s_nop 0
	v_pk_fma_f32 v[10:11], v[120:121], v[112:113], v[0:1]
	v_cvt_pk_bf16_f32 v0, v4, v5
	v_cvt_pk_bf16_f32 v1, v6, v7
	v_pk_fma_f32 v[8:9], v[122:123], v[118:119], v[2:3]
	v_cvt_pk_bf16_f32 v2, v10, v11
	s_nop 0
	v_cvt_pk_bf16_f32 v3, v8, v9
	global_store_dwordx4 v12, v[0:3], s[26:27] nt
	s_nop 1
	v_mul_f32_e32 v0, v5, v5
	v_mul_f32_e32 v1, v7, v7
	v_fmac_f32_e32 v0, v4, v4
	v_fmac_f32_e32 v1, v6, v6
	v_add_f32_e32 v0, v0, v1
	v_mul_f32_e32 v1, v11, v11
	v_mul_f32_e32 v2, v9, v9
	v_fmac_f32_e32 v1, v10, v10
	v_fmac_f32_e32 v2, v8, v8
	v_add_f32_e32 v1, v1, v2
	v_add_f32_e32 v0, v0, v1
	v_add_f32_e32 v3, v23, v0
	ds_bpermute_b32 v13, v16, v3
	v_pk_mul_f32 v[0:1], v[72:73], v[4:5]
	v_pk_mul_f32 v[4:5], v[84:85], v[10:11]
	v_cvt_pk_bf16_f32 v2, v0, v1
	v_pk_mul_f32 v[6:7], v[90:91], v[6:7]
	s_waitcnt lgkmcnt(0)
	v_add_f32_e32 v0, v3, v13
	ds_bpermute_b32 v1, v17, v0
	v_pk_mul_f32 v[8:9], v[82:83], v[8:9]
	v_cvt_pk_bf16_f32 v3, v6, v7
	v_cvt_pk_bf16_f32 v4, v4, v5
	s_nop 0
	v_cvt_pk_bf16_f32 v5, v8, v9
	global_store_dwordx4 v12, v[2:5], s[72:73]
	s_and_saveexec_b64 s[38:39], s[0:1]
	s_cbranch_execz .LBB0_321
	v_or_b32_e32 v2, 48, v136
	v_mov_b32_e32 v3, v137
	v_lshl_add_u64 v[2:3], v[2:3], 2, s[24:25]
	s_waitcnt lgkmcnt(0)
	v_add_f32_e32 v0, v0, v1
	global_atomic_add_f32 v[2:3], v0, off
.LBB0_321:
	s_or_b64 exec, exec, s[38:39]
	v_add_u32_e32 v0, 0x80000, v231
	global_load_dwordx4 v[18:21], v0, s[16:17]
	global_load_dwordx4 v[120:123], v0, s[16:17] offset:16
	v_add_u32_e32 v0, 0x80200, v231
	global_load_dwordx4 v[124:127], v0, s[16:17]
	global_load_dwordx4 v[142:145], v0, s[16:17] offset:16
	v_add_u32_e32 v0, 0x90000, v231
	v_add_u32_e32 v4, 0x90200, v231
	global_load_dwordx4 v[8:11], v0, s[16:17] offset:16
	global_load_dwordx4 v[12:15], v0, s[16:17]
	s_waitcnt lgkmcnt(0)
	global_load_dwordx4 v[0:3], v4, s[16:17] offset:16
	s_nop 0
	global_load_dwordx4 v[4:7], v4, s[16:17]
	v_add_u32_e32 v146, 0x40000, v210
	v_add_u32_e32 v147, 0x40100, v210
	s_waitcnt vmcnt(7)
	v_pk_fma_f32 v[22:23], v[86:87], v[100:101], v[20:21]
	v_pk_fma_f32 v[86:87], v[88:89], v[98:99], v[18:19]
	s_waitcnt vmcnt(6)
	v_pk_fma_f32 v[88:89], v[92:93], v[102:103], v[122:123]
	v_pk_fma_f32 v[92:93], v[94:95], v[96:97], v[120:121]
	s_waitcnt vmcnt(5)
	v_pk_fma_f32 v[94:95], v[104:105], v[116:117], v[126:127]
	v_pk_fma_f32 v[104:105], v[106:107], v[114:115], v[124:125]
	s_waitcnt vmcnt(4)
	v_pk_fma_f32 v[106:107], v[108:109], v[118:119], v[144:145]
	v_pk_fma_f32 v[108:109], v[110:111], v[112:113], v[142:143]
	v_cvt_pk_bf16_f32 v18, v86, v87
	v_cvt_pk_bf16_f32 v19, v22, v23
	v_cvt_pk_bf16_f32 v20, v92, v93
	v_cvt_pk_bf16_f32 v21, v88, v89
	v_mul_f32_e32 v126, v87, v87
	v_mul_f32_e32 v127, v23, v23
	v_mul_f32_e32 v142, v93, v93
	v_mul_f32_e32 v143, v89, v89
	v_pk_mul_f32 v[110:111], v[74:75], v[22:23]
	v_pk_mul_f32 v[120:121], v[76:77], v[86:87]
	v_pk_mul_f32 v[122:123], v[78:79], v[88:89]
	v_pk_mul_f32 v[124:125], v[80:81], v[92:93]
	v_mul_f32_e32 v23, v105, v105
	v_mul_f32_e32 v87, v95, v95
	v_mul_f32_e32 v89, v109, v109
	v_mul_f32_e32 v93, v107, v107
	global_store_dwordx4 v146, v[18:21], s[26:27] nt
	v_fmac_f32_e32 v126, v86, v86
	v_fmac_f32_e32 v127, v22, v22
	v_fmac_f32_e32 v142, v92, v92
	v_fmac_f32_e32 v143, v88, v88
	v_cvt_pk_bf16_f32 v18, v120, v121
	v_fmac_f32_e32 v23, v104, v104
	v_fmac_f32_e32 v87, v94, v94
	v_fmac_f32_e32 v89, v108, v108
	v_fmac_f32_e32 v93, v106, v106
	v_cvt_pk_bf16_f32 v19, v110, v111
	v_cvt_pk_bf16_f32 v20, v124, v125
	v_cvt_pk_bf16_f32 v21, v122, v123
	v_add_f32_e32 v22, v126, v127
	v_add_f32_e32 v86, v142, v143
	global_store_dwordx4 v146, v[18:21], s[72:73]
	v_add_f32_e32 v23, v23, v87
	v_add_f32_e32 v87, v89, v93
	v_cvt_pk_bf16_f32 v18, v104, v105
	v_cvt_pk_bf16_f32 v19, v94, v95
	v_cvt_pk_bf16_f32 v20, v108, v109
	v_cvt_pk_bf16_f32 v21, v106, v107
	v_add_f32_e32 v22, v22, v86
	global_store_dwordx4 v147, v[18:21], s[26:27] nt
	v_pk_mul_f32 v[88:89], v[84:85], v[108:109]
	s_nop 0
	v_add_f32_e32 v18, v23, v87
	v_add_f32_e32 v21, v22, v18
	ds_bpermute_b32 v92, v16, v21
	v_pk_mul_f32 v[18:19], v[72:73], v[104:105]
	v_pk_mul_f32 v[22:23], v[90:91], v[94:95]
	v_cvt_pk_bf16_f32 v20, v18, v19
	v_pk_mul_f32 v[86:87], v[82:83], v[106:107]
	s_waitcnt lgkmcnt(0)
	v_add_f32_e32 v18, v21, v92
	ds_bpermute_b32 v19, v17, v18
	v_cvt_pk_bf16_f32 v21, v22, v23
	v_cvt_pk_bf16_f32 v22, v88, v89
	v_cvt_pk_bf16_f32 v23, v86, v87
	global_store_dwordx4 v147, v[20:23], s[72:73]
	s_and_saveexec_b64 s[38:39], s[0:1]
	s_cbranch_execz .LBB0_323
	v_add_u32_e32 v20, 0x80, v136
	v_mov_b32_e32 v21, v137
	v_lshl_add_u64 v[20:21], v[20:21], 2, s[24:25]
	s_waitcnt lgkmcnt(0)
	v_add_f32_e32 v18, v18, v19
	global_atomic_add_f32 v[20:21], v18, off
;     __device__ __forceinline__ void operator()(const f32x4 (&acc)[2][2][4][2], const Unit& u, int wr, int wc, int fr, int fq) const {
;     ...
;         for (int rg = 0; rg < 8 / RGB; ++rg) {
;             u32x4 braw[INPLACE ? RGB : 1][2]; f32x4 bb[INPLACE ? 1 : RGB][2][2];
; #pragma unroll
;             for (int mm = 0; mm < RGB; ++mm) { const int q = rg * RGB + mm, ai = q >> 2, m = q & 3;
; #pragma unroll
;                 for (int bj = 0; bj < 2; ++bj) { const unsigned e = e0 + (unsigned)((ai * 128 + m * 16) * D + bj * 128);
;                     if constexpr (INPLACE) braw[mm][bj] = *(const u32x4*)(Hc + (size_t)(e * 2u));
;                     else { bb[mm][bj][0] = *(const f32x4*)(bsc + (size_t)(e * 4u)); bb[mm][bj][1] = *(const f32x4*)(bsc + (size_t)(e * 4u + 16u)); } } }
; #pragma unroll
;             for (int mm = 0; mm < RGB; ++mm) { const int q = rg * RGB + mm, ai = q >> 2, m = q & 3; float ssum = 0.f;
; #pragma unroll
;                 for (int bj = 0; bj < 2; ++bj) { const unsigned e = e0 + (unsigned)((ai * 128 + m * 16) * D + bj * 128);
;                     f32x4 r0, r1;
;                     if constexpr (INPLACE) { const u32x4 q4 = braw[mm][bj];
;                         r0 = (f32x4){__uint_as_float(q4[0] << 16), __uint_as_float(q4[0] & 0xffff0000u), __uint_as_float(q4[1] << 16), __uint_as_float(q4[1] & 0xffff0000u)};
;                         r1 = (f32x4){__uint_as_float(q4[2] << 16), __uint_as_float(q4[2] & 0xffff0000u), __uint_as_float(q4[3] << 16), __uint_as_float(q4[3] & 0xffff0000u)}; }
;                     else { r0 = bb[mm][bj][0]; r1 = bb[mm][bj][1]; }
;                     const f32x4 h0 = r0 + gv[bj][0] * (acc[ai][bj][m][0] + bv[bj][0]), h1 = r1 + gv[bj][1] * (acc[ai][bj][m][1] + bv[bj][1]);
;                     { u32x4 w; w.x = cvt_pk_bf16(h0[0], h0[1]); w.y = cvt_pk_bf16(h0[2], h0[3]); w.z = cvt_pk_bf16(h1[0], h1[1]); w.w = cvt_pk_bf16(h1[2], h1[3]); ST16(1, Hc + (size_t)(e * 2u), w); }
;                     if (FUSE) { ssum += ((h0[0] * h0[0] + h0[1] * h0[1]) + (h0[2] * h0[2] + h0[3] * h0[3])) + ((h1[0] * h1[0] + h1[1] * h1[1]) + (h1[2] * h1[2] + h1[3] * h1[3]));
;                         const f32x4 z0 = h0 * wv[bj][0], z1 = h1 * wv[bj][1];
;                         u32x4 w; w.x = cvt_pk_bf16(z0[0], z0[1]); w.y = cvt_pk_bf16(z0[2], z0[3]); w.z = cvt_pk_bf16(z1[0], z1[1]); w.w = cvt_pk_bf16(z1[2], z1[3]);
.LBB0_323:
	s_or_b64 exec, exec, s[38:39]
	s_waitcnt vmcnt(6)
	v_pk_fma_f32 v[14:15], v[70:71], v[100:101], v[14:15]
	v_pk_fma_f32 v[12:13], v[68:69], v[98:99], v[12:13]
	v_pk_fma_f32 v[20:21], v[64:65], v[96:97], v[8:9]
	v_cvt_pk_bf16_f32 v8, v12, v13
	v_cvt_pk_bf16_f32 v9, v14, v15
	v_add_u32_e32 v22, 0x48000, v210
	s_waitcnt lgkmcnt(0)
	v_pk_fma_f32 v[18:19], v[66:67], v[102:103], v[10:11]
	v_cvt_pk_bf16_f32 v10, v20, v21
	s_waitcnt vmcnt(4)
	v_pk_fma_f32 v[6:7], v[62:63], v[116:117], v[6:7]
	v_cvt_pk_bf16_f32 v11, v18, v19
	global_store_dwordx4 v22, v[8:11], s[26:27] nt
	v_pk_fma_f32 v[4:5], v[60:61], v[114:115], v[4:5]
	s_nop 0
	v_mul_f32_e32 v8, v13, v13
	v_mul_f32_e32 v9, v15, v15
	v_fmac_f32_e32 v8, v12, v12
	v_fmac_f32_e32 v9, v14, v14
	v_add_f32_e32 v8, v8, v9
	v_mul_f32_e32 v9, v21, v21
	v_mul_f32_e32 v10, v19, v19
	v_fmac_f32_e32 v9, v20, v20
	v_fmac_f32_e32 v10, v18, v18
	v_add_f32_e32 v9, v9, v10
	v_add_f32_e32 v23, v8, v9
	v_pk_mul_f32 v[10:11], v[74:75], v[14:15]
	v_pk_mul_f32 v[8:9], v[76:77], v[12:13]
	v_pk_mul_f32 v[12:13], v[78:79], v[18:19]
	v_pk_mul_f32 v[14:15], v[80:81], v[20:21]
	v_cvt_pk_bf16_f32 v8, v8, v9
	v_cvt_pk_bf16_f32 v9, v10, v11
	s_nop 0
	v_cvt_pk_bf16_f32 v10, v14, v15
	v_cvt_pk_bf16_f32 v11, v12, v13
	global_store_dwordx4 v22, v[8:11], s[72:73]
	v_add_u32_e32 v12, 0x48100, v210
	s_nop 0
	v_pk_fma_f32 v[10:11], v[56:57], v[112:113], v[0:1]
	v_cvt_pk_bf16_f32 v0, v4, v5
	v_cvt_pk_bf16_f32 v1, v6, v7
	v_pk_fma_f32 v[8:9], v[58:59], v[118:119], v[2:3]
	v_cvt_pk_bf16_f32 v2, v10, v11
	s_nop 0
	v_cvt_pk_bf16_f32 v3, v8, v9
	global_store_dwordx4 v12, v[0:3], s[26:27] nt
	s_nop 1
	v_mul_f32_e32 v0, v5, v5
	v_mul_f32_e32 v1, v7, v7
	v_fmac_f32_e32 v0, v4, v4
	v_fmac_f32_e32 v1, v6, v6
	v_add_f32_e32 v0, v0, v1
	v_mul_f32_e32 v1, v11, v11
	v_mul_f32_e32 v2, v9, v9
	v_fmac_f32_e32 v1, v10, v10
	v_fmac_f32_e32 v2, v8, v8
	v_add_f32_e32 v1, v1, v2
	v_add_f32_e32 v0, v0, v1
	v_add_f32_e32 v3, v23, v0
	ds_bpermute_b32 v13, v16, v3
	v_pk_mul_f32 v[0:1], v[72:73], v[4:5]
	v_pk_mul_f32 v[4:5], v[84:85], v[10:11]
	v_cvt_pk_bf16_f32 v2, v0, v1
	v_pk_mul_f32 v[6:7], v[90:91], v[6:7]
	s_waitcnt lgkmcnt(0)
	v_add_f32_e32 v0, v3, v13
	ds_bpermute_b32 v1, v17, v0
	v_pk_mul_f32 v[8:9], v[82:83], v[8:9]
	v_cvt_pk_bf16_f32 v3, v6, v7
	v_cvt_pk_bf16_f32 v4, v4, v5
	s_nop 0
	v_cvt_pk_bf16_f32 v5, v8, v9
	global_store_dwordx4 v12, v[2:5], s[72:73]
	s_and_saveexec_b64 s[38:39], s[0:1]
	s_cbranch_execz .LBB0_325
	v_add_u32_e32 v2, 0x90, v136
	v_mov_b32_e32 v3, v137
	v_lshl_add_u64 v[2:3], v[2:3], 2, s[24:25]
	s_waitcnt lgkmcnt(0)
	v_add_f32_e32 v0, v0, v1
	global_atomic_add_f32 v[2:3], v0, off
;     __device__ __forceinline__ void operator()(const f32x4 (&acc)[2][2][4][2], const Unit& u, int wr, int wc, int fr, int fq) const {
;     ...
;         for (int rg = 0; rg < 8 / RGB; ++rg) {
;             u32x4 braw[INPLACE ? RGB : 1][2]; f32x4 bb[INPLACE ? 1 : RGB][2][2];
; #pragma unroll
;             for (int mm = 0; mm < RGB; ++mm) { const int q = rg * RGB + mm, ai = q >> 2, m = q & 3;
; #pragma unroll
;                 for (int bj = 0; bj < 2; ++bj) { const unsigned e = e0 + (unsigned)((ai * 128 + m * 16) * D + bj * 128);
;                     if constexpr (INPLACE) braw[mm][bj] = *(const u32x4*)(Hc + (size_t)(e * 2u));
;                     else { bb[mm][bj][0] = *(const f32x4*)(bsc + (size_t)(e * 4u)); bb[mm][bj][1] = *(const f32x4*)(bsc + (size_t)(e * 4u + 16u)); } } }
; #pragma unroll
;             for (int mm = 0; mm < RGB; ++mm) { const int q = rg * RGB + mm, ai = q >> 2, m = q & 3; float ssum = 0.f;
; #pragma unroll
;                 for (int bj = 0; bj < 2; ++bj) { const unsigned e = e0 + (unsigned)((ai * 128 + m * 16) * D + bj * 128);
;                     f32x4 r0, r1;
;                     if constexpr (INPLACE) { const u32x4 q4 = braw[mm][bj];
;                         r0 = (f32x4){__uint_as_float(q4[0] << 16), __uint_as_float(q4[0] & 0xffff0000u), __uint_as_float(q4[1] << 16), __uint_as_float(q4[1] & 0xffff0000u)};
;                         r1 = (f32x4){__uint_as_float(q4[2] << 16), __uint_as_float(q4[2] & 0xffff0000u), __uint_as_float(q4[3] << 16), __uint_as_float(q4[3] & 0xffff0000u)}; }
;                     else { r0 = bb[mm][bj][0]; r1 = bb[mm][bj][1]; }
;                     const f32x4 h0 = r0 + gv[bj][0] * (acc[ai][bj][m][0] + bv[bj][0]), h1 = r1 + gv[bj][1] * (acc[ai][bj][m][1] + bv[bj][1]);
;                     { u32x4 w; w.x = cvt_pk_bf16(h0[0], h0[1]); w.y = cvt_pk_bf16(h0[2], h0[3]); w.z = cvt_pk_bf16(h1[0], h1[1]); w.w = cvt_pk_bf16(h1[2], h1[3]); ST16(1, Hc + (size_t)(e * 2u), w); }
;                     if (FUSE) { ssum += ((h0[0] * h0[0] + h0[1] * h0[1]) + (h0[2] * h0[2] + h0[3] * h0[3])) + ((h1[0] * h1[0] + h1[1] * h1[1]) + (h1[2] * h1[2] + h1[3] * h1[3]));
;                         const f32x4 z0 = h0 * wv[bj][0], z1 = h1 * wv[bj][1];
;                         u32x4 w; w.x = cvt_pk_bf16(z0[0], z0[1]); w.y = cvt_pk_bf16(z0[2], z0[3]); w.z = cvt_pk_bf16(z1[0], z1[1]); w.w = cvt_pk_bf16(z1[2], z1[3]);
.LBB0_325:
	s_or_b64 exec, exec, s[38:39]
	v_add_u32_e32 v0, 0xa0000, v231
	global_load_dwordx4 v[18:21], v0, s[16:17]
	global_load_dwordx4 v[56:59], v0, s[16:17] offset:16
	v_add_u32_e32 v0, 0xa0200, v231
	global_load_dwordx4 v[60:63], v0, s[16:17]
	global_load_dwordx4 v[64:67], v0, s[16:17] offset:16
	v_add_u32_e32 v0, 0xb0000, v231
	v_add_u32_e32 v4, 0xb0200, v231
	global_load_dwordx4 v[8:11], v0, s[16:17] offset:16
	global_load_dwordx4 v[12:15], v0, s[16:17]
	s_waitcnt lgkmcnt(0)
	global_load_dwordx4 v[0:3], v4, s[16:17] offset:16
	s_nop 0
	global_load_dwordx4 v[4:7], v4, s[16:17]
	v_add_u32_e32 v68, 0x50000, v210
	v_add_u32_e32 v69, 0x50100, v210
	s_waitcnt vmcnt(7)
	v_pk_fma_f32 v[22:23], v[42:43], v[100:101], v[20:21]
	v_pk_fma_f32 v[40:41], v[40:41], v[98:99], v[18:19]
	s_waitcnt vmcnt(6)
	v_pk_fma_f32 v[42:43], v[44:45], v[102:103], v[58:59]
	v_pk_fma_f32 v[44:45], v[46:47], v[96:97], v[56:57]
	s_waitcnt vmcnt(5)
	v_pk_fma_f32 v[46:47], v[48:49], v[116:117], v[62:63]
	v_pk_fma_f32 v[48:49], v[50:51], v[114:115], v[60:61]
	s_waitcnt vmcnt(4)
	v_pk_fma_f32 v[50:51], v[52:53], v[118:119], v[66:67]
	v_pk_fma_f32 v[52:53], v[54:55], v[112:113], v[64:65]
	v_cvt_pk_bf16_f32 v18, v40, v41
	v_cvt_pk_bf16_f32 v19, v22, v23
	v_cvt_pk_bf16_f32 v20, v44, v45
	v_cvt_pk_bf16_f32 v21, v42, v43
	v_mul_f32_e32 v62, v41, v41
	v_mul_f32_e32 v63, v23, v23
	v_mul_f32_e32 v64, v45, v45
	v_mul_f32_e32 v65, v43, v43
	v_pk_mul_f32 v[54:55], v[74:75], v[22:23]
	v_pk_mul_f32 v[56:57], v[76:77], v[40:41]
	v_pk_mul_f32 v[58:59], v[78:79], v[42:43]
	v_pk_mul_f32 v[60:61], v[80:81], v[44:45]
	v_mul_f32_e32 v23, v49, v49
	v_mul_f32_e32 v41, v47, v47
	v_mul_f32_e32 v43, v53, v53
	v_mul_f32_e32 v45, v51, v51
	global_store_dwordx4 v68, v[18:21], s[26:27] nt
	v_fmac_f32_e32 v62, v40, v40
	v_fmac_f32_e32 v63, v22, v22
	v_fmac_f32_e32 v64, v44, v44
	v_fmac_f32_e32 v65, v42, v42
	v_cvt_pk_bf16_f32 v18, v56, v57
	v_fmac_f32_e32 v23, v48, v48
	v_fmac_f32_e32 v41, v46, v46
	v_fmac_f32_e32 v43, v52, v52
	v_fmac_f32_e32 v45, v50, v50
	v_cvt_pk_bf16_f32 v19, v54, v55
	v_cvt_pk_bf16_f32 v20, v60, v61
	v_cvt_pk_bf16_f32 v21, v58, v59
	v_add_f32_e32 v22, v62, v63
	v_add_f32_e32 v40, v64, v65
	global_store_dwordx4 v68, v[18:21], s[72:73]
	v_add_f32_e32 v23, v23, v41
	v_add_f32_e32 v41, v43, v45
	v_cvt_pk_bf16_f32 v18, v48, v49
	v_cvt_pk_bf16_f32 v19, v46, v47
	v_cvt_pk_bf16_f32 v20, v52, v53
	v_cvt_pk_bf16_f32 v21, v50, v51
	v_add_f32_e32 v22, v22, v40
	global_store_dwordx4 v69, v[18:21], s[26:27] nt
	v_pk_mul_f32 v[42:43], v[84:85], v[52:53]
	s_nop 0
	v_add_f32_e32 v18, v23, v41
	v_add_f32_e32 v21, v22, v18
	ds_bpermute_b32 v44, v16, v21
	v_pk_mul_f32 v[18:19], v[72:73], v[48:49]
	v_pk_mul_f32 v[22:23], v[90:91], v[46:47]
	v_cvt_pk_bf16_f32 v20, v18, v19
	v_pk_mul_f32 v[40:41], v[82:83], v[50:51]
	s_waitcnt lgkmcnt(0)
	v_add_f32_e32 v18, v21, v44
	ds_bpermute_b32 v19, v17, v18
	v_cvt_pk_bf16_f32 v21, v22, v23
	v_cvt_pk_bf16_f32 v22, v42, v43
	v_cvt_pk_bf16_f32 v23, v40, v41
	global_store_dwordx4 v69, v[20:23], s[72:73]
	s_and_saveexec_b64 s[38:39], s[0:1]
	s_cbranch_execz .LBB0_327
	v_add_u32_e32 v20, 0xa0, v136
	v_mov_b32_e32 v21, v137
	v_lshl_add_u64 v[20:21], v[20:21], 2, s[24:25]
	s_waitcnt lgkmcnt(0)
	v_add_f32_e32 v18, v18, v19
	global_atomic_add_f32 v[20:21], v18, off
.LBB0_327:
	s_or_b64 exec, exec, s[38:39]
	s_waitcnt vmcnt(6)
	v_pk_fma_f32 v[14:15], v[38:39], v[100:101], v[14:15]
	v_pk_fma_f32 v[12:13], v[36:37], v[98:99], v[12:13]
	v_pk_fma_f32 v[20:21], v[32:33], v[96:97], v[8:9]
	v_cvt_pk_bf16_f32 v8, v12, v13
	v_cvt_pk_bf16_f32 v9, v14, v15
	v_add_u32_e32 v22, 0x58000, v210
	s_waitcnt lgkmcnt(0)
	v_pk_fma_f32 v[18:19], v[34:35], v[102:103], v[10:11]
	v_cvt_pk_bf16_f32 v10, v20, v21
	s_waitcnt vmcnt(4)
	v_pk_fma_f32 v[6:7], v[30:31], v[116:117], v[6:7]
	v_cvt_pk_bf16_f32 v11, v18, v19
	global_store_dwordx4 v22, v[8:11], s[26:27] nt
	v_pk_fma_f32 v[4:5], v[28:29], v[114:115], v[4:5]
	s_nop 0
	v_mul_f32_e32 v8, v13, v13
	v_mul_f32_e32 v9, v15, v15
	v_fmac_f32_e32 v8, v12, v12
	v_fmac_f32_e32 v9, v14, v14
	v_add_f32_e32 v8, v8, v9
	v_mul_f32_e32 v9, v21, v21
	v_mul_f32_e32 v10, v19, v19
	v_fmac_f32_e32 v9, v20, v20
	v_fmac_f32_e32 v10, v18, v18
	v_add_f32_e32 v9, v9, v10
	v_add_f32_e32 v23, v8, v9
	v_pk_mul_f32 v[10:11], v[74:75], v[14:15]
	v_pk_mul_f32 v[8:9], v[76:77], v[12:13]
	v_pk_mul_f32 v[12:13], v[78:79], v[18:19]
	v_pk_mul_f32 v[14:15], v[80:81], v[20:21]
	v_cvt_pk_bf16_f32 v8, v8, v9
	v_cvt_pk_bf16_f32 v9, v10, v11
	s_nop 0
	v_cvt_pk_bf16_f32 v10, v14, v15
	v_cvt_pk_bf16_f32 v11, v12, v13
	global_store_dwordx4 v22, v[8:11], s[72:73]
	v_add_u32_e32 v12, 0x58100, v210
	s_nop 0
	v_pk_fma_f32 v[10:11], v[24:25], v[112:113], v[0:1]
	v_cvt_pk_bf16_f32 v0, v4, v5
	v_cvt_pk_bf16_f32 v1, v6, v7
	v_pk_fma_f32 v[8:9], v[26:27], v[118:119], v[2:3]
	v_cvt_pk_bf16_f32 v2, v10, v11
	s_nop 0
	v_cvt_pk_bf16_f32 v3, v8, v9
	global_store_dwordx4 v12, v[0:3], s[26:27] nt
	s_nop 1
	v_mul_f32_e32 v0, v5, v5
	v_mul_f32_e32 v1, v7, v7
	v_fmac_f32_e32 v0, v4, v4
	v_fmac_f32_e32 v1, v6, v6
	v_add_f32_e32 v0, v0, v1
	v_mul_f32_e32 v1, v11, v11
	v_mul_f32_e32 v2, v9, v9
	v_fmac_f32_e32 v1, v10, v10
	v_fmac_f32_e32 v2, v8, v8
	v_add_f32_e32 v1, v1, v2
	v_add_f32_e32 v0, v0, v1
	v_add_f32_e32 v3, v23, v0
	ds_bpermute_b32 v13, v16, v3
	v_pk_mul_f32 v[0:1], v[72:73], v[4:5]
	v_pk_mul_f32 v[4:5], v[84:85], v[10:11]
	v_cvt_pk_bf16_f32 v2, v0, v1
	v_pk_mul_f32 v[6:7], v[90:91], v[6:7]
	s_waitcnt lgkmcnt(0)
	v_add_f32_e32 v0, v3, v13
	ds_bpermute_b32 v1, v17, v0
	v_pk_mul_f32 v[8:9], v[82:83], v[8:9]
	v_cvt_pk_bf16_f32 v3, v6, v7
	v_cvt_pk_bf16_f32 v4, v4, v5
	s_nop 0
	v_cvt_pk_bf16_f32 v5, v8, v9
	global_store_dwordx4 v12, v[2:5], s[72:73]
	s_and_saveexec_b64 s[38:39], s[0:1]
	s_cbranch_execz .LBB0_329
	v_add_u32_e32 v136, 0xb0, v136
	v_lshl_add_u64 v[2:3], v[136:137], 2, s[24:25]
	s_waitcnt lgkmcnt(0)
	v_add_f32_e32 v0, v0, v1
	global_atomic_add_f32 v[2:3], v0, off

;     __device__ __forceinline__ void operator()(const f32x4 (&acc)[2][2][4][2], const Unit& u, int wr, int wc, int fr, int fq) const {
;         const int row0 = u.pm * 256 + wr * 64 + fr, col0 = u.pn * 256 + wc * 32 + 8 * fq;
;         const int mb = u.pm < 64 ? (u.pm >> 4) : 4;
;         float* SSn = (float*)(ws + WS_SS) + ss_off;
;         const float* gate = (const float*)(ws + WS_MOD) + gate_off + (size_t)mb * 9216; const float* gn = (const float*)(ws + WS_NG) + gn_off; const float* scn = (const float*)(ws + WS_MOD) + scn_off + (size_t)mb * 9216;
;         f32x4 gv[2][2], bv[2][2], wv[2][2];
; #pragma unroll
;         for (int bj = 0; bj < 2; ++bj)
; #pragma unroll
;             for (int n = 0; n < 2; ++n) { const int cc = col0 + bj * 128 + 4 * n;
;                 gv[bj][n] = *(const f32x4*)(gate + cc) * gmul;
;                 bv[bj][n] = HASBIAS ? *(const f32x4*)(bias + cc) : (f32x4){0.f, 0.f, 0.f, 0.f};
;                 wv[bj][n] = FUSE ? *(const f32x4*)(gn + cc) * (*(const f32x4*)(scn + cc) + 1.0f) : (f32x4){0.f, 0.f, 0.f, 0.f}; }
;         const unsigned e0 = (unsigned)(row0 * D + col0);
;         const char* bsc = (const char*)base0; char* Hc = (char*)(ws + WS_H); char* HBc = (char*)(ws + WS_XN);
;         constexpr int RGB = 2;
; #pragma unroll
;         for (int rg = 0; rg < 8 / RGB; ++rg) {
;             u32x4 braw[INPLACE ? RGB : 1][2]; f32x4 bb[INPLACE ? 1 : RGB][2][2];
; #pragma unroll
;             for (int mm = 0; mm < RGB; ++mm) { const int q = rg * RGB + mm, ai = q >> 2, m = q & 3;
; #pragma unroll
;                 for (int bj = 0; bj < 2; ++bj) { const unsigned e = e0 + (unsigned)((ai * 128 + m * 16) * D + bj * 128);
;                     if constexpr (INPLACE) braw[mm][bj] = *(const u32x4*)(Hc + (size_t)(e * 2u));
;                     else { bb[mm][bj][0] = *(const f32x4*)(bsc + (size_t)(e * 4u)); bb[mm][bj][1] = *(const f32x4*)(bsc + (size_t)(e * 4u + 16u)); } } }
; #pragma unroll
;             for (int mm = 0; mm < RGB; ++mm) { const int q = rg * RGB + mm, ai = q >> 2, m = q & 3; float ssum = 0.f;
; #pragma unroll
;                 for (int bj = 0; bj < 2; ++bj) { const unsigned e = e0 + (unsigned)((ai * 128 + m * 16) * D + bj * 128);
;                     f32x4 r0, r1;
;                     if constexpr (INPLACE) { const u32x4 q4 = braw[mm][bj];
.LBB0_888:
	v_lshl_add_u32 v56, s24, 8, v179
	s_ashr_i32 s19, s24, 4
	v_lshl_or_b32 v0, s51, 8, v192
	s_mul_hi_i32 s26, s19, 0x9000
	s_waitcnt lgkmcnt(0)
	v_lshlrev_b32_e32 v1, 11, v56
	s_mul_i32 s19, s19, 0x9000
	v_lshl_add_u32 v196, v0, 1, v1
	s_add_u32 s24, s45, s19
	v_ashrrev_i32_e32 v1, 31, v0
	s_addc_u32 s25, s46, s26
	v_lshlrev_b64 v[2:3], 2, v[0:1]
	v_or_b32_e32 v57, 0x100, v196
	v_lshl_add_u64 v[16:17], s[24:25], 0, v[2:3]
	s_add_u32 s24, s47, s19
	global_load_dwordx4 v[198:201], v57, s[14:15]
	global_load_dwordx4 v[74:77], v196, s[14:15]
	s_addc_u32 s25, s48, s26
	global_load_dwordx4 v[12:15], v[16:17], off
	global_load_dwordx4 v[8:11], v[16:17], off offset:16
	v_lshl_add_u64 v[4:5], s[24:25], 0, v[2:3]
	v_lshl_add_u64 v[2:3], s[10:11], 0, v[2:3]
	global_load_dwordx4 v[80:83], v[4:5], off
	global_load_dwordx4 v[98:101], v[4:5], off offset:16
	global_load_dwordx4 v[102:105], v[4:5], off offset:512
	global_load_dwordx4 v[202:205], v[4:5], off offset:528
	global_load_dwordx4 v[206:209], v[2:3], off offset:16
	global_load_dwordx4 v[210:213], v[2:3], off
	v_or_b32_e32 v0, 0x80, v0
	v_ashrrev_i32_e32 v1, 31, v0
	v_lshl_add_u64 v[0:1], v[0:1], 2, s[10:11]
	global_load_dwordx4 v[214:217], v[0:1], off
	global_load_dwordx4 v[218:221], v[0:1], off offset:16
	global_load_dwordx4 v[4:7], v[16:17], off offset:512
	s_nop 0
	global_load_dwordx4 v[0:3], v[16:17], off offset:528
	v_add_u32_e32 v136, 0x8000, v196
	v_add_u32_e32 v190, 0x8100, v196
	global_load_dwordx4 v[20:23], v136, s[14:15]
	global_load_dwordx4 v[16:19], v190, s[14:15]
	s_waitcnt vmcnt(0)
	v_lshlrev_b32_e32 v222, 16, v198
	v_lshlrev_b32_e32 v224, 16, v74
	v_and_b32_e32 v225, 0xffff0000, v74
	v_lshlrev_b32_e32 v74, 16, v75
	v_and_b32_e32 v75, 0xffff0000, v75
	v_lshlrev_b32_e32 v226, 16, v76
	v_and_b32_e32 v227, 0xffff0000, v76
	v_lshlrev_b32_e32 v76, 16, v77
	v_and_b32_e32 v77, 0xffff0000, v77
	v_pk_fma_f32 v[228:229], v[182:183], v[14:15], v[74:75]
	v_pk_fma_f32 v[186:187], v[186:187], v[10:11], v[76:77]
	v_pk_add_f32 v[74:75], v[82:83], 1.0 op_sel_hi:[1,0]
	v_pk_add_f32 v[76:77], v[80:81], 1.0 op_sel_hi:[1,0]
	v_pk_fma_f32 v[224:225], v[184:185], v[12:13], v[224:225]
	v_pk_fma_f32 v[188:189], v[188:189], v[8:9], v[226:227]
	v_pk_add_f32 v[80:81], v[100:101], 1.0 op_sel_hi:[1,0]
	v_pk_add_f32 v[82:83], v[98:99], 1.0 op_sel_hi:[1,0]
	v_pk_add_f32 v[226:227], v[104:105], 1.0 op_sel_hi:[1,0]
	v_pk_add_f32 v[230:231], v[102:103], 1.0 op_sel_hi:[1,0]
	v_cvt_pk_bf16_f32 v182, v224, v225
	v_cvt_pk_bf16_f32 v183, v228, v229
	v_cvt_pk_bf16_f32 v184, v188, v189
	v_cvt_pk_bf16_f32 v185, v186, v187
	v_pk_mul_f32 v[102:103], v[212:213], v[74:75]
	v_pk_mul_f32 v[104:105], v[210:211], v[76:77]
	v_mul_f32_e32 v191, v225, v225
	v_mul_f32_e32 v197, v229, v229
	v_mul_f32_e32 v223, v189, v189
	v_mul_f32_e32 v232, v187, v187
	v_pk_mul_f32 v[98:99], v[208:209], v[80:81]
	v_pk_mul_f32 v[100:101], v[206:207], v[82:83]
	global_store_dwordx4 v196, v[182:185], s[14:15] nt
	v_fmac_f32_e32 v191, v224, v224
	v_fmac_f32_e32 v197, v228, v228
	v_pk_mul_f32 v[184:185], v[102:103], v[228:229]
	v_pk_mul_f32 v[182:183], v[104:105], v[224:225]
	v_fmac_f32_e32 v223, v188, v188
	v_fmac_f32_e32 v232, v186, v186
	v_pk_mul_f32 v[186:187], v[98:99], v[186:187]
	v_pk_mul_f32 v[188:189], v[100:101], v[188:189]
	v_cvt_pk_bf16_f32 v182, v182, v183
	v_cvt_pk_bf16_f32 v183, v184, v185
	v_add_f32_e32 v191, v191, v197
	v_cvt_pk_bf16_f32 v184, v188, v189
	v_cvt_pk_bf16_f32 v185, v186, v187
	v_add_f32_e32 v197, v223, v232
	global_store_dwordx4 v196, v[182:185], s[86:87]
	v_and_b32_e32 v223, 0xffff0000, v198
	v_lshlrev_b32_e32 v186, 16, v201
	v_lshlrev_b32_e32 v182, 16, v199
	v_and_b32_e32 v183, 0xffff0000, v199
	v_lshlrev_b32_e32 v184, 16, v200
	v_and_b32_e32 v185, 0xffff0000, v200
	v_and_b32_e32 v187, 0xffff0000, v201
	v_pk_fma_f32 v[174:175], v[174:175], v[6:7], v[182:183]
	v_pk_fma_f32 v[172:173], v[172:173], v[4:5], v[222:223]
	v_pk_fma_f32 v[184:185], v[168:169], v[0:1], v[184:185]
	v_cvt_pk_bf16_f32 v168, v172, v173
	v_cvt_pk_bf16_f32 v169, v174, v175
	v_pk_fma_f32 v[182:183], v[170:171], v[2:3], v[186:187]
	v_cvt_pk_bf16_f32 v170, v184, v185
	v_add_f32_e32 v191, v191, v197
	v_cvt_pk_bf16_f32 v171, v182, v183
	global_store_dwordx4 v57, v[168:171], s[14:15] nt
	v_pk_mul_f32 v[82:83], v[214:215], v[230:231]
	v_pk_add_f32 v[204:205], v[204:205], 1.0 op_sel_hi:[1,0]
	v_mul_f32_e32 v168, v173, v173
	v_mul_f32_e32 v169, v175, v175
	v_fmac_f32_e32 v168, v172, v172
	v_fmac_f32_e32 v169, v174, v174
	v_add_f32_e32 v168, v168, v169
	v_mul_f32_e32 v169, v185, v185
	v_mul_f32_e32 v170, v183, v183
	v_fmac_f32_e32 v169, v184, v184
	v_fmac_f32_e32 v170, v182, v182
	v_add_f32_e32 v169, v169, v170
	v_add_f32_e32 v168, v168, v169
	v_and_b32_e32 v170, 64, v177
	v_add_f32_e32 v169, v191, v168
	v_xor_b32_e32 v168, 16, v177
	v_add_u32_e32 v186, 64, v170
	v_cmp_lt_i32_e32 vcc, v168, v186
	v_pk_mul_f32 v[170:171], v[82:83], v[172:173]
	v_pk_add_f32 v[202:203], v[202:203], 1.0 op_sel_hi:[1,0]
	v_cndmask_b32_e32 v168, v177, v168, vcc
	v_lshlrev_b32_e32 v168, 2, v168
	ds_bpermute_b32 v187, v168, v169
	v_cvt_pk_bf16_f32 v172, v170, v171
	v_pk_mul_f32 v[80:81], v[216:217], v[226:227]
	v_pk_mul_f32 v[74:75], v[220:221], v[204:205]
	v_pk_mul_f32 v[76:77], v[218:219], v[202:203]
	s_waitcnt lgkmcnt(0)
	v_add_f32_e32 v170, v169, v187
	v_xor_b32_e32 v169, 32, v177
	v_cmp_lt_i32_e32 vcc, v169, v186
	v_pk_mul_f32 v[174:175], v[80:81], v[174:175]
	v_pk_mul_f32 v[182:183], v[74:75], v[182:183]
	v_cndmask_b32_e32 v169, v177, v169, vcc
	v_lshlrev_b32_e32 v169, 2, v169
	ds_bpermute_b32 v171, v169, v170
	v_pk_mul_f32 v[184:185], v[76:77], v[184:185]
	v_cvt_pk_bf16_f32 v173, v174, v175
	s_nop 0
	v_cvt_pk_bf16_f32 v174, v184, v185
	v_cvt_pk_bf16_f32 v175, v182, v183
	global_store_dwordx4 v57, v[172:175], s[86:87]
	s_and_saveexec_b64 s[24:25], s[0:1]
	s_cbranch_execz .LBB0_890
	v_mov_b32_e32 v57, v137
	v_lshl_add_u64 v[172:173], v[56:57], 2, s[12:13]
	s_waitcnt lgkmcnt(0)
	v_add_f32_e32 v57, v170, v171
	global_atomic_add_f32 v[172:173], v57, off
;     __device__ __forceinline__ void operator()(const f32x4 (&acc)[2][2][4][2], const Unit& u, int wr, int wc, int fr, int fq) const {
;     ...
;         for (int rg = 0; rg < 8 / RGB; ++rg) {
;             u32x4 braw[INPLACE ? RGB : 1][2]; f32x4 bb[INPLACE ? 1 : RGB][2][2];
; #pragma unroll
;             for (int mm = 0; mm < RGB; ++mm) { const int q = rg * RGB + mm, ai = q >> 2, m = q & 3;
; #pragma unroll
;                 for (int bj = 0; bj < 2; ++bj) { const unsigned e = e0 + (unsigned)((ai * 128 + m * 16) * D + bj * 128);
;                     if constexpr (INPLACE) braw[mm][bj] = *(const u32x4*)(Hc + (size_t)(e * 2u));
;                     else { bb[mm][bj][0] = *(const f32x4*)(bsc + (size_t)(e * 4u)); bb[mm][bj][1] = *(const f32x4*)(bsc + (size_t)(e * 4u + 16u)); } } }
; #pragma unroll
;             for (int mm = 0; mm < RGB; ++mm) { const int q = rg * RGB + mm, ai = q >> 2, m = q & 3; float ssum = 0.f;
; #pragma unroll
;                 for (int bj = 0; bj < 2; ++bj) { const unsigned e = e0 + (unsigned)((ai * 128 + m * 16) * D + bj * 128);
;                     f32x4 r0, r1;
;                     if constexpr (INPLACE) { const u32x4 q4 = braw[mm][bj];
;                         r0 = (f32x4){__uint_as_float(q4[0] << 16), __uint_as_float(q4[0] & 0xffff0000u), __uint_as_float(q4[1] << 16), __uint_as_float(q4[1] & 0xffff0000u)};
;                         r1 = (f32x4){__uint_as_float(q4[2] << 16), __uint_as_float(q4[2] & 0xffff0000u), __uint_as_float(q4[3] << 16), __uint_as_float(q4[3] & 0xffff0000u)}; }
;                     else { r0 = bb[mm][bj][0]; r1 = bb[mm][bj][1]; }
;                     const f32x4 h0 = r0 + gv[bj][0] * (acc[ai][bj][m][0] + bv[bj][0]), h1 = r1 + gv[bj][1] * (acc[ai][bj][m][1] + bv[bj][1]);
;                     { u32x4 w; w.x = cvt_pk_bf16(h0[0], h0[1]); w.y = cvt_pk_bf16(h0[2], h0[3]); w.z = cvt_pk_bf16(h1[0], h1[1]); w.w = cvt_pk_bf16(h1[2], h1[3]); ST16(1, Hc + (size_t)(e * 2u), w); }
;                     if (FUSE) { ssum += ((h0[0] * h0[0] + h0[1] * h0[1]) + (h0[2] * h0[2] + h0[3] * h0[3])) + ((h1[0] * h1[0] + h1[1] * h1[1]) + (h1[2] * h1[2] + h1[3] * h1[3]));
;                         const f32x4 z0 = h0 * wv[bj][0], z1 = h1 * wv[bj][1];
;                         u32x4 w; w.x = cvt_pk_bf16(z0[0], z0[1]); w.y = cvt_pk_bf16(z0[2], z0[3]); w.z = cvt_pk_bf16(z1[0], z1[1]); w.w = cvt_pk_bf16(z1[2], z1[3]);
.LBB0_890:
	s_or_b64 exec, exec, s[24:25]
	v_lshlrev_b32_e32 v174, 16, v20
	v_and_b32_e32 v175, 0xffff0000, v20
	v_lshlrev_b32_e32 v20, 16, v21
	v_and_b32_e32 v21, 0xffff0000, v21
	s_waitcnt lgkmcnt(0)
	v_lshl_add_u64 v[170:171], s[14:15], 0, v[136:137]
	v_lshlrev_b32_e32 v182, 16, v22
	v_and_b32_e32 v183, 0xffff0000, v22
	v_lshlrev_b32_e32 v22, 16, v23
	v_and_b32_e32 v23, 0xffff0000, v23
	v_pk_fma_f32 v[166:167], v[166:167], v[14:15], v[20:21]
	v_pk_fma_f32 v[164:165], v[164:165], v[12:13], v[174:175]
	v_pk_fma_f32 v[162:163], v[162:163], v[10:11], v[22:23]
	v_cvt_pk_bf16_f32 v20, v164, v165
	v_cvt_pk_bf16_f32 v21, v166, v167
	v_pk_fma_f32 v[160:161], v[160:161], v[8:9], v[182:183]
	v_mov_b32_e32 v191, v137
	v_cvt_pk_bf16_f32 v22, v160, v161
	v_cvt_pk_bf16_f32 v23, v162, v163
	global_store_dwordx4 v[170:171], v[20:23], off nt
	v_lshl_add_u64 v[172:173], s[14:15], 0, v[190:191]
	s_nop 0
	v_mul_f32_e32 v20, v165, v165
	v_mul_f32_e32 v21, v167, v167
	v_fmac_f32_e32 v20, v164, v164
	v_fmac_f32_e32 v21, v166, v166
	v_add_f32_e32 v20, v20, v21
	v_mul_f32_e32 v21, v161, v161
	v_mul_f32_e32 v22, v163, v163
	v_fmac_f32_e32 v21, v160, v160
	v_fmac_f32_e32 v22, v162, v162
	v_add_f32_e32 v21, v21, v22
	v_add_f32_e32 v57, v20, v21
	v_pk_mul_f32 v[22:23], v[102:103], v[166:167]
	v_pk_mul_f32 v[20:21], v[104:105], v[164:165]
	v_pk_mul_f32 v[160:161], v[100:101], v[160:161]
	v_cvt_pk_bf16_f32 v20, v20, v21
	v_cvt_pk_bf16_f32 v21, v22, v23
	v_pk_mul_f32 v[162:163], v[98:99], v[162:163]
	v_cvt_pk_bf16_f32 v22, v160, v161
	v_lshl_add_u64 v[160:161], s[86:87], 0, v[136:137]
	v_cvt_pk_bf16_f32 v23, v162, v163
	global_store_dwordx4 v[160:161], v[20:23], off
	s_nop 1
	v_lshlrev_b32_e32 v20, 16, v16
	v_and_b32_e32 v21, 0xffff0000, v16
	v_lshlrev_b32_e32 v16, 16, v17
	v_and_b32_e32 v17, 0xffff0000, v17
	v_lshlrev_b32_e32 v22, 16, v18
	v_and_b32_e32 v23, 0xffff0000, v18
	v_lshlrev_b32_e32 v18, 16, v19
	v_and_b32_e32 v19, 0xffff0000, v19
	v_pk_fma_f32 v[158:159], v[158:159], v[6:7], v[16:17]
	v_pk_fma_f32 v[20:21], v[156:157], v[4:5], v[20:21]
	v_pk_fma_f32 v[154:155], v[154:155], v[2:3], v[18:19]
	v_cvt_pk_bf16_f32 v16, v20, v21
	v_cvt_pk_bf16_f32 v17, v158, v159
	v_pk_fma_f32 v[22:23], v[152:153], v[0:1], v[22:23]
	v_pk_mul_f32 v[152:153], v[74:75], v[154:155]
	v_cvt_pk_bf16_f32 v18, v22, v23
	v_cvt_pk_bf16_f32 v19, v154, v155
	global_store_dwordx4 v[172:173], v[16:19], off nt
	s_nop 1
	v_mul_f32_e32 v16, v21, v21
	v_mul_f32_e32 v17, v159, v159
	v_fmac_f32_e32 v16, v20, v20
	v_fmac_f32_e32 v17, v158, v158
	v_add_f32_e32 v16, v16, v17
	v_mul_f32_e32 v17, v23, v23
	v_mul_f32_e32 v18, v155, v155
	v_fmac_f32_e32 v17, v22, v22
	v_fmac_f32_e32 v18, v154, v154
	v_add_f32_e32 v17, v17, v18
	v_add_f32_e32 v16, v16, v17
	v_add_f32_e32 v57, v57, v16
	ds_bpermute_b32 v136, v168, v57
	v_pk_mul_f32 v[16:17], v[80:81], v[158:159]
	v_pk_mul_f32 v[18:19], v[82:83], v[20:21]
	v_pk_mul_f32 v[20:21], v[76:77], v[22:23]
	v_cvt_pk_bf16_f32 v18, v18, v19
	v_cvt_pk_bf16_f32 v19, v16, v17
	s_waitcnt lgkmcnt(0)
	v_add_f32_e32 v16, v57, v136
	ds_bpermute_b32 v17, v169, v16
	v_lshl_add_u64 v[22:23], s[86:87], 0, v[190:191]
	v_cvt_pk_bf16_f32 v20, v20, v21
	v_cvt_pk_bf16_f32 v21, v152, v153
	global_store_dwordx4 v[22:23], v[18:21], off
	s_and_saveexec_b64 s[24:25], s[0:1]
	s_cbranch_execz .LBB0_892
	v_or_b32_e32 v136, 16, v56
	v_lshl_add_u64 v[18:19], v[136:137], 2, s[12:13]
	s_waitcnt lgkmcnt(0)
	v_add_f32_e32 v16, v16, v17
	global_atomic_add_f32 v[18:19], v16, off
.LBB0_892:
	s_or_b64 exec, exec, s[24:25]
	v_add_u32_e32 v57, 0x10000, v196
	v_add_u32_e32 v153, 0x10100, v196
	global_load_dwordx4 v[154:157], v57, s[14:15]
	global_load_dwordx4 v[158:161], v153, s[14:15]
	v_add_u32_e32 v136, 0x18000, v196
	v_add_u32_e32 v152, 0x18100, v196
	global_load_dwordx4 v[20:23], v136, s[14:15]
	s_waitcnt lgkmcnt(0)
	global_load_dwordx4 v[16:19], v152, s[14:15]
	s_waitcnt vmcnt(3)
	v_lshlrev_b32_e32 v162, 16, v154
	v_and_b32_e32 v163, 0xffff0000, v154
	v_lshlrev_b32_e32 v154, 16, v155
	v_and_b32_e32 v155, 0xffff0000, v155
	v_lshlrev_b32_e32 v164, 16, v156
	v_and_b32_e32 v165, 0xffff0000, v156
	v_lshlrev_b32_e32 v156, 16, v157
	v_and_b32_e32 v157, 0xffff0000, v157
	s_waitcnt vmcnt(2)
	v_lshlrev_b32_e32 v166, 16, v158
	v_and_b32_e32 v167, 0xffff0000, v158
	v_lshlrev_b32_e32 v158, 16, v159
	v_and_b32_e32 v159, 0xffff0000, v159
	v_lshlrev_b32_e32 v170, 16, v160
	v_and_b32_e32 v171, 0xffff0000, v160
	v_lshlrev_b32_e32 v160, 16, v161
	v_and_b32_e32 v161, 0xffff0000, v161
	v_pk_fma_f32 v[154:155], v[122:123], v[14:15], v[154:155]
	v_pk_fma_f32 v[162:163], v[124:125], v[12:13], v[162:163]
	v_pk_fma_f32 v[126:127], v[126:127], v[10:11], v[156:157]
	v_pk_fma_f32 v[142:143], v[142:143], v[8:9], v[164:165]
	v_pk_fma_f32 v[150:151], v[150:151], v[6:7], v[158:159]
	v_pk_fma_f32 v[148:149], v[148:149], v[4:5], v[166:167]
	v_pk_fma_f32 v[146:147], v[146:147], v[2:3], v[160:161]
	v_pk_fma_f32 v[144:145], v[144:145], v[0:1], v[170:171]
	v_cvt_pk_bf16_f32 v122, v162, v163
	v_cvt_pk_bf16_f32 v123, v154, v155
	v_cvt_pk_bf16_f32 v124, v142, v143
	v_cvt_pk_bf16_f32 v125, v126, v127
	v_mul_f32_e32 v166, v163, v163
	v_mul_f32_e32 v167, v155, v155
	v_mul_f32_e32 v170, v143, v143
	v_mul_f32_e32 v171, v127, v127
	v_pk_mul_f32 v[156:157], v[102:103], v[154:155]
	v_pk_mul_f32 v[158:159], v[104:105], v[162:163]
	v_pk_mul_f32 v[160:161], v[98:99], v[126:127]
	v_pk_mul_f32 v[164:165], v[100:101], v[142:143]
	v_mul_f32_e32 v127, v149, v149
	v_mul_f32_e32 v143, v151, v151
	v_mul_f32_e32 v155, v145, v145
	v_mul_f32_e32 v163, v147, v147
	v_fmac_f32_e32 v166, v162, v162
	v_fmac_f32_e32 v167, v154, v154
	v_fmac_f32_e32 v170, v142, v142
	v_fmac_f32_e32 v171, v126, v126
	v_fmac_f32_e32 v127, v148, v148
	v_fmac_f32_e32 v143, v150, v150
	v_fmac_f32_e32 v155, v144, v144
	v_fmac_f32_e32 v163, v146, v146
	global_store_dwordx4 v57, v[122:125], s[14:15] nt
	v_add_f32_e32 v126, v166, v167
	v_add_f32_e32 v142, v170, v171
	v_cvt_pk_bf16_f32 v122, v158, v159
	v_cvt_pk_bf16_f32 v123, v156, v157
	v_cvt_pk_bf16_f32 v124, v164, v165
	v_cvt_pk_bf16_f32 v125, v160, v161
	global_store_dwordx4 v57, v[122:125], s[86:87]
	v_add_f32_e32 v57, v127, v143
	v_add_f32_e32 v127, v155, v163
	v_add_f32_e32 v126, v126, v142
	v_add_f32_e32 v57, v57, v127
	v_cvt_pk_bf16_f32 v122, v148, v149
	v_cvt_pk_bf16_f32 v123, v150, v151
	v_cvt_pk_bf16_f32 v124, v144, v145
	v_cvt_pk_bf16_f32 v125, v146, v147
	v_add_f32_e32 v57, v126, v57
	global_store_dwordx4 v153, v[122:125], s[14:15] nt
	ds_bpermute_b32 v125, v168, v57
	v_pk_mul_f32 v[126:127], v[80:81], v[150:151]
	v_pk_mul_f32 v[122:123], v[82:83], v[148:149]
	v_pk_mul_f32 v[142:143], v[74:75], v[146:147]
	v_cvt_pk_bf16_f32 v124, v122, v123
	s_waitcnt lgkmcnt(0)
	v_add_f32_e32 v57, v57, v125
	ds_bpermute_b32 v122, v169, v57
	v_pk_mul_f32 v[144:145], v[76:77], v[144:145]
	v_cvt_pk_bf16_f32 v125, v126, v127
	s_nop 0
	v_cvt_pk_bf16_f32 v126, v144, v145
	v_cvt_pk_bf16_f32 v127, v142, v143
	global_store_dwordx4 v153, v[124:127], s[86:87]
	s_and_saveexec_b64 s[24:25], s[0:1]
	s_cbranch_execz .LBB0_894
;     __device__ __forceinline__ void operator()(const f32x4 (&acc)[2][2][4][2], const Unit& u, int wr, int wc, int fr, int fq) const {
;     ...
;         for (int rg = 0; rg < 8 / RGB; ++rg) {
;             u32x4 braw[INPLACE ? RGB : 1][2]; f32x4 bb[INPLACE ? 1 : RGB][2][2];
; #pragma unroll
;             for (int mm = 0; mm < RGB; ++mm) { const int q = rg * RGB + mm, ai = q >> 2, m = q & 3;
; #pragma unroll
;                 for (int bj = 0; bj < 2; ++bj) { const unsigned e = e0 + (unsigned)((ai * 128 + m * 16) * D + bj * 128);
;                     if constexpr (INPLACE) braw[mm][bj] = *(const u32x4*)(Hc + (size_t)(e * 2u));
;                     else { bb[mm][bj][0] = *(const f32x4*)(bsc + (size_t)(e * 4u)); bb[mm][bj][1] = *(const f32x4*)(bsc + (size_t)(e * 4u + 16u)); } } }
; #pragma unroll
;             for (int mm = 0; mm < RGB; ++mm) { const int q = rg * RGB + mm, ai = q >> 2, m = q & 3; float ssum = 0.f;
; #pragma unroll
;                 for (int bj = 0; bj < 2; ++bj) { const unsigned e = e0 + (unsigned)((ai * 128 + m * 16) * D + bj * 128);
;                     f32x4 r0, r1;
;                     if constexpr (INPLACE) { const u32x4 q4 = braw[mm][bj];
;                         r0 = (f32x4){__uint_as_float(q4[0] << 16), __uint_as_float(q4[0] & 0xffff0000u), __uint_as_float(q4[1] << 16), __uint_as_float(q4[1] & 0xffff0000u)};
;                         r1 = (f32x4){__uint_as_float(q4[2] << 16), __uint_as_float(q4[2] & 0xffff0000u), __uint_as_float(q4[3] << 16), __uint_as_float(q4[3] & 0xffff0000u)}; }
;                     else { r0 = bb[mm][bj][0]; r1 = bb[mm][bj][1]; }
;                     const f32x4 h0 = r0 + gv[bj][0] * (acc[ai][bj][m][0] + bv[bj][0]), h1 = r1 + gv[bj][1] * (acc[ai][bj][m][1] + bv[bj][1]);
;                     { u32x4 w; w.x = cvt_pk_bf16(h0[0], h0[1]); w.y = cvt_pk_bf16(h0[2], h0[3]); w.z = cvt_pk_bf16(h1[0], h1[1]); w.w = cvt_pk_bf16(h1[2], h1[3]); ST16(1, Hc + (size_t)(e * 2u), w); }
;                     if (FUSE) { ssum += ((h0[0] * h0[0] + h0[1] * h0[1]) + (h0[2] * h0[2] + h0[3] * h0[3])) + ((h1[0] * h1[0] + h1[1] * h1[1]) + (h1[2] * h1[2] + h1[3] * h1[3]));
;                         const f32x4 z0 = h0 * wv[bj][0], z1 = h1 * wv[bj][1];
;                         u32x4 w; w.x = cvt_pk_bf16(z0[0], z0[1]); w.y = cvt_pk_bf16(z0[2], z0[3]); w.z = cvt_pk_bf16(z1[0], z1[1]); w.w = cvt_pk_bf16(z1[2], z1[3]);
	v_or_b32_e32 v124, 32, v56
	v_mov_b32_e32 v125, v137
	v_lshl_add_u64 v[124:125], v[124:125], 2, s[12:13]
	s_waitcnt lgkmcnt(0)
	v_add_f32_e32 v57, v57, v122
	global_atomic_add_f32 v[124:125], v57, off
.LBB0_894:
	s_or_b64 exec, exec, s[24:25]
	s_waitcnt vmcnt(5)
	v_lshlrev_b32_e32 v126, 16, v20
	v_and_b32_e32 v127, 0xffff0000, v20
	v_lshlrev_b32_e32 v20, 16, v21
	v_and_b32_e32 v21, 0xffff0000, v21
	s_waitcnt lgkmcnt(0)
	v_lshl_add_u64 v[122:123], s[14:15], 0, v[136:137]
	v_lshlrev_b32_e32 v142, 16, v22
	v_and_b32_e32 v143, 0xffff0000, v22
	v_lshlrev_b32_e32 v22, 16, v23
	v_and_b32_e32 v23, 0xffff0000, v23
	v_pk_fma_f32 v[120:121], v[120:121], v[14:15], v[20:21]
	v_pk_fma_f32 v[118:119], v[118:119], v[12:13], v[126:127]
	v_pk_fma_f32 v[116:117], v[116:117], v[10:11], v[22:23]
	v_cvt_pk_bf16_f32 v20, v118, v119
	v_cvt_pk_bf16_f32 v21, v120, v121
	v_pk_fma_f32 v[114:115], v[114:115], v[8:9], v[142:143]
	v_mov_b32_e32 v153, v137
	v_cvt_pk_bf16_f32 v22, v114, v115
	v_cvt_pk_bf16_f32 v23, v116, v117
	global_store_dwordx4 v[122:123], v[20:23], off nt
	v_lshl_add_u64 v[124:125], s[14:15], 0, v[152:153]
	s_nop 0
	v_mul_f32_e32 v20, v119, v119
	v_mul_f32_e32 v21, v121, v121
	v_fmac_f32_e32 v20, v118, v118
	v_fmac_f32_e32 v21, v120, v120
	v_add_f32_e32 v20, v20, v21
	v_mul_f32_e32 v21, v115, v115
	v_mul_f32_e32 v22, v117, v117
	v_fmac_f32_e32 v21, v114, v114
	v_fmac_f32_e32 v22, v116, v116
	v_add_f32_e32 v21, v21, v22
	v_add_f32_e32 v57, v20, v21
	v_pk_mul_f32 v[22:23], v[102:103], v[120:121]
	v_pk_mul_f32 v[20:21], v[104:105], v[118:119]
	v_pk_mul_f32 v[114:115], v[100:101], v[114:115]
	v_cvt_pk_bf16_f32 v20, v20, v21
	v_cvt_pk_bf16_f32 v21, v22, v23
	v_pk_mul_f32 v[116:117], v[98:99], v[116:117]
	v_cvt_pk_bf16_f32 v22, v114, v115
	v_lshl_add_u64 v[114:115], s[86:87], 0, v[136:137]
	v_cvt_pk_bf16_f32 v23, v116, v117
	global_store_dwordx4 v[114:115], v[20:23], off
	s_waitcnt vmcnt(6)
	s_nop 0
	v_lshlrev_b32_e32 v20, 16, v16
	v_and_b32_e32 v21, 0xffff0000, v16
	v_lshlrev_b32_e32 v16, 16, v17
	v_and_b32_e32 v17, 0xffff0000, v17
	v_lshlrev_b32_e32 v22, 16, v18
	v_and_b32_e32 v23, 0xffff0000, v18
	v_lshlrev_b32_e32 v18, 16, v19
	v_and_b32_e32 v19, 0xffff0000, v19
	v_pk_fma_f32 v[112:113], v[112:113], v[6:7], v[16:17]
	v_pk_fma_f32 v[20:21], v[110:111], v[4:5], v[20:21]
	v_pk_fma_f32 v[108:109], v[108:109], v[2:3], v[18:19]
	v_cvt_pk_bf16_f32 v16, v20, v21
	v_cvt_pk_bf16_f32 v17, v112, v113
	v_pk_fma_f32 v[22:23], v[106:107], v[0:1], v[22:23]
	v_pk_mul_f32 v[106:107], v[74:75], v[108:109]
	v_cvt_pk_bf16_f32 v18, v22, v23
	v_cvt_pk_bf16_f32 v19, v108, v109
	global_store_dwordx4 v[124:125], v[16:19], off nt
	s_nop 1
	v_mul_f32_e32 v16, v21, v21
	v_mul_f32_e32 v17, v113, v113
	v_fmac_f32_e32 v16, v20, v20
	v_fmac_f32_e32 v17, v112, v112
	v_add_f32_e32 v16, v16, v17
	v_mul_f32_e32 v17, v23, v23
	v_mul_f32_e32 v18, v109, v109
	v_fmac_f32_e32 v17, v22, v22
	v_fmac_f32_e32 v18, v108, v108
	v_add_f32_e32 v17, v17, v18
	v_add_f32_e32 v16, v16, v17
	v_add_f32_e32 v57, v57, v16
	ds_bpermute_b32 v110, v168, v57
	v_pk_mul_f32 v[16:17], v[80:81], v[112:113]
	v_pk_mul_f32 v[18:19], v[82:83], v[20:21]
	v_pk_mul_f32 v[20:21], v[76:77], v[22:23]
	v_cvt_pk_bf16_f32 v18, v18, v19
	v_cvt_pk_bf16_f32 v19, v16, v17
	s_waitcnt lgkmcnt(0)
	v_add_f32_e32 v16, v57, v110
	ds_bpermute_b32 v17, v169, v16
	v_lshl_add_u64 v[22:23], s[86:87], 0, v[152:153]
	v_cvt_pk_bf16_f32 v20, v20, v21
	v_cvt_pk_bf16_f32 v21, v106, v107
	global_store_dwordx4 v[22:23], v[18:21], off
	s_and_saveexec_b64 s[24:25], s[0:1]
	s_cbranch_execz .LBB0_896
	v_or_b32_e32 v136, 48, v56
	v_lshl_add_u64 v[18:19], v[136:137], 2, s[12:13]
	s_waitcnt lgkmcnt(0)
	v_add_f32_e32 v16, v16, v17
	global_atomic_add_f32 v[18:19], v16, off
.LBB0_896:
	s_or_b64 exec, exec, s[24:25]
	v_add_u32_e32 v57, 0x40000, v196
	v_add_u32_e32 v107, 0x40100, v196
	global_load_dwordx4 v[108:111], v57, s[14:15]
	global_load_dwordx4 v[112:115], v107, s[14:15]
	v_add_u32_e32 v136, 0x48000, v196
	v_add_u32_e32 v106, 0x48100, v196
	global_load_dwordx4 v[20:23], v136, s[14:15]
	s_waitcnt lgkmcnt(0)
	global_load_dwordx4 v[16:19], v106, s[14:15]
	s_waitcnt vmcnt(3)
	v_lshlrev_b32_e32 v116, 16, v108
	v_and_b32_e32 v117, 0xffff0000, v108
	v_lshlrev_b32_e32 v108, 16, v109
	v_and_b32_e32 v109, 0xffff0000, v109
	v_lshlrev_b32_e32 v118, 16, v110
	v_and_b32_e32 v119, 0xffff0000, v110
	v_lshlrev_b32_e32 v110, 16, v111
	v_and_b32_e32 v111, 0xffff0000, v111
	s_waitcnt vmcnt(2)
	v_lshlrev_b32_e32 v120, 16, v112
	v_and_b32_e32 v121, 0xffff0000, v112
	v_lshlrev_b32_e32 v112, 16, v113
	v_and_b32_e32 v113, 0xffff0000, v113
	v_lshlrev_b32_e32 v122, 16, v114
	v_and_b32_e32 v123, 0xffff0000, v114
	v_lshlrev_b32_e32 v114, 16, v115
	v_and_b32_e32 v115, 0xffff0000, v115
	v_pk_fma_f32 v[78:79], v[78:79], v[14:15], v[108:109]
	v_pk_fma_f32 v[108:109], v[84:85], v[12:13], v[116:117]
	v_pk_fma_f32 v[110:111], v[86:87], v[10:11], v[110:111]
	v_pk_fma_f32 v[88:89], v[88:89], v[8:9], v[118:119]
	v_pk_fma_f32 v[96:97], v[96:97], v[6:7], v[112:113]
	v_pk_fma_f32 v[94:95], v[94:95], v[4:5], v[120:121]
	v_pk_fma_f32 v[92:93], v[92:93], v[2:3], v[114:115]
	v_pk_fma_f32 v[90:91], v[90:91], v[0:1], v[122:123]
	v_cvt_pk_bf16_f32 v84, v108, v109
	v_cvt_pk_bf16_f32 v85, v78, v79
	v_cvt_pk_bf16_f32 v86, v88, v89
	v_cvt_pk_bf16_f32 v87, v110, v111
	v_mul_f32_e32 v120, v109, v109
	v_mul_f32_e32 v121, v79, v79
	v_mul_f32_e32 v122, v89, v89
	v_mul_f32_e32 v123, v111, v111
	v_pk_mul_f32 v[112:113], v[102:103], v[78:79]
	v_pk_mul_f32 v[114:115], v[104:105], v[108:109]
	v_pk_mul_f32 v[116:117], v[98:99], v[110:111]
	v_pk_mul_f32 v[118:119], v[100:101], v[88:89]
	v_mul_f32_e32 v79, v95, v95
	v_mul_f32_e32 v89, v97, v97
	v_mul_f32_e32 v109, v91, v91
	v_mul_f32_e32 v111, v93, v93
	v_fmac_f32_e32 v120, v108, v108
	v_fmac_f32_e32 v121, v78, v78
	v_fmac_f32_e32 v122, v88, v88
	v_fmac_f32_e32 v123, v110, v110
	v_fmac_f32_e32 v79, v94, v94
	v_fmac_f32_e32 v89, v96, v96
	v_fmac_f32_e32 v109, v90, v90
	v_fmac_f32_e32 v111, v92, v92
	global_store_dwordx4 v57, v[84:87], s[14:15] nt
	v_add_f32_e32 v78, v120, v121
	v_add_f32_e32 v88, v122, v123
	v_cvt_pk_bf16_f32 v84, v114, v115
	v_cvt_pk_bf16_f32 v85, v112, v113
	v_cvt_pk_bf16_f32 v86, v118, v119
	v_cvt_pk_bf16_f32 v87, v116, v117
	global_store_dwordx4 v57, v[84:87], s[86:87]
	v_add_f32_e32 v57, v79, v89
	v_add_f32_e32 v79, v109, v111
	v_add_f32_e32 v78, v78, v88
	v_add_f32_e32 v57, v57, v79
	v_cvt_pk_bf16_f32 v84, v94, v95
	v_cvt_pk_bf16_f32 v85, v96, v97
	v_add_f32_e32 v57, v78, v57
	v_cvt_pk_bf16_f32 v86, v90, v91
	v_cvt_pk_bf16_f32 v87, v92, v93
	global_store_dwordx4 v107, v[84:87], s[14:15] nt
	ds_bpermute_b32 v85, v168, v57
	v_pk_mul_f32 v[78:79], v[82:83], v[94:95]
	v_pk_mul_f32 v[86:87], v[80:81], v[96:97]
	v_cvt_pk_bf16_f32 v84, v78, v79
	v_pk_mul_f32 v[88:89], v[74:75], v[92:93]
	s_waitcnt lgkmcnt(0)
; __device__ __forceinline__ unsigned cvt_pk_bf16(float lo, float hi) { unsigned r; asm volatile("v_cvt_pk_bf16_f32 %0, %1, %2" : "=v"(r) : "v"(lo), "v"(hi)); return r; }
; #define ST16(grp, p, v) do { if ((NTG >> (grp)) & 1) NT16(p, v); else PL16(p, v); } while (0)
;     __device__ __forceinline__ void operator()(const f32x4 (&acc)[2][2][4][2], const Unit& u, int wr, int wc, int fr, int fq) const {
;     ...
;             for (int mm = 0; mm < RGB; ++mm) { const int q = rg * RGB + mm, ai = q >> 2, m = q & 3; float ssum = 0.f;
; #pragma unroll
;                 for (int bj = 0; bj < 2; ++bj) { const unsigned e = e0 + (unsigned)((ai * 128 + m * 16) * D + bj * 128);
;                     f32x4 r0, r1;
;                     if constexpr (INPLACE) { const u32x4 q4 = braw[mm][bj];
;                         r0 = (f32x4){__uint_as_float(q4[0] << 16), __uint_as_float(q4[0] & 0xffff0000u), __uint_as_float(q4[1] << 16), __uint_as_float(q4[1] & 0xffff0000u)};
;                         r1 = (f32x4){__uint_as_float(q4[2] << 16), __uint_as_float(q4[2] & 0xffff0000u), __uint_as_float(q4[3] << 16), __uint_as_float(q4[3] & 0xffff0000u)}; }
;                     else { r0 = bb[mm][bj][0]; r1 = bb[mm][bj][1]; }
;                     const f32x4 h0 = r0 + gv[bj][0] * (acc[ai][bj][m][0] + bv[bj][0]), h1 = r1 + gv[bj][1] * (acc[ai][bj][m][1] + bv[bj][1]);
;                     { u32x4 w; w.x = cvt_pk_bf16(h0[0], h0[1]); w.y = cvt_pk_bf16(h0[2], h0[3]); w.z = cvt_pk_bf16(h1[0], h1[1]); w.w = cvt_pk_bf16(h1[2], h1[3]); ST16(1, Hc + (size_t)(e * 2u), w); }
;                     if (FUSE) { ssum += ((h0[0] * h0[0] + h0[1] * h0[1]) + (h0[2] * h0[2] + h0[3] * h0[3])) + ((h1[0] * h1[0] + h1[1] * h1[1]) + (h1[2] * h1[2] + h1[3] * h1[3]));
;                         const f32x4 z0 = h0 * wv[bj][0], z1 = h1 * wv[bj][1];
;                         u32x4 w; w.x = cvt_pk_bf16(z0[0], z0[1]); w.y = cvt_pk_bf16(z0[2], z0[3]); w.z = cvt_pk_bf16(z1[0], z1[1]); w.w = cvt_pk_bf16(z1[2], z1[3]);
;                         ST16(2, HBc + (size_t)(e * 2u), w); } }
;                 if (FUSE) { ssum += __shfl_xor(ssum, 16); ssum += __shfl_xor(ssum, 32); if (fq == 0) unsafeAtomicAdd(SSn + (unsigned)(row0 + ai * 128 + m * 16), ssum); } }
;             asm volatile("" ::: "memory"); }
	v_add_f32_e32 v57, v57, v85
	ds_bpermute_b32 v78, v169, v57
	v_pk_mul_f32 v[90:91], v[76:77], v[90:91]
	v_cvt_pk_bf16_f32 v85, v86, v87
	s_nop 0
	v_cvt_pk_bf16_f32 v86, v90, v91
	v_cvt_pk_bf16_f32 v87, v88, v89
	global_store_dwordx4 v107, v[84:87], s[86:87]
	s_and_saveexec_b64 s[24:25], s[0:1]
	s_cbranch_execz .LBB0_898
	v_add_u32_e32 v84, 0x80, v56
	v_mov_b32_e32 v85, v137
	v_lshl_add_u64 v[84:85], v[84:85], 2, s[12:13]
	s_waitcnt lgkmcnt(0)
	v_add_f32_e32 v57, v57, v78
	global_atomic_add_f32 v[84:85], v57, off
.LBB0_898:
	s_or_b64 exec, exec, s[24:25]
	s_waitcnt vmcnt(5)
	v_lshlrev_b32_e32 v86, 16, v20
	v_and_b32_e32 v87, 0xffff0000, v20
	v_lshlrev_b32_e32 v20, 16, v21
	v_and_b32_e32 v21, 0xffff0000, v21
	s_waitcnt lgkmcnt(0)
	v_lshl_add_u64 v[78:79], s[14:15], 0, v[136:137]
	v_lshlrev_b32_e32 v88, 16, v22
	v_and_b32_e32 v89, 0xffff0000, v22
	v_lshlrev_b32_e32 v22, 16, v23
	v_and_b32_e32 v23, 0xffff0000, v23
	v_pk_fma_f32 v[72:73], v[72:73], v[14:15], v[20:21]
	v_pk_fma_f32 v[70:71], v[70:71], v[12:13], v[86:87]
	v_pk_fma_f32 v[68:69], v[68:69], v[10:11], v[22:23]
	v_cvt_pk_bf16_f32 v20, v70, v71
	v_cvt_pk_bf16_f32 v21, v72, v73
	v_pk_fma_f32 v[66:67], v[66:67], v[8:9], v[88:89]
	v_mov_b32_e32 v107, v137
	v_cvt_pk_bf16_f32 v22, v66, v67
	v_cvt_pk_bf16_f32 v23, v68, v69
	global_store_dwordx4 v[78:79], v[20:23], off nt
	v_lshl_add_u64 v[84:85], s[14:15], 0, v[106:107]
	s_nop 0
	v_mul_f32_e32 v20, v71, v71
	v_mul_f32_e32 v21, v73, v73
	v_fmac_f32_e32 v20, v70, v70
	v_fmac_f32_e32 v21, v72, v72
	v_add_f32_e32 v20, v20, v21
	v_mul_f32_e32 v21, v67, v67
	v_mul_f32_e32 v22, v69, v69
	v_fmac_f32_e32 v21, v66, v66
	v_fmac_f32_e32 v22, v68, v68
	v_add_f32_e32 v21, v21, v22
	v_add_f32_e32 v57, v20, v21
	v_pk_mul_f32 v[22:23], v[102:103], v[72:73]
	v_pk_mul_f32 v[20:21], v[104:105], v[70:71]
	v_pk_mul_f32 v[66:67], v[100:101], v[66:67]
	v_cvt_pk_bf16_f32 v20, v20, v21
	v_cvt_pk_bf16_f32 v21, v22, v23
	v_pk_mul_f32 v[68:69], v[98:99], v[68:69]
	v_cvt_pk_bf16_f32 v22, v66, v67
	v_lshl_add_u64 v[66:67], s[86:87], 0, v[136:137]
	v_cvt_pk_bf16_f32 v23, v68, v69
	global_store_dwordx4 v[66:67], v[20:23], off
	s_waitcnt vmcnt(6)
	s_nop 0
	v_lshlrev_b32_e32 v20, 16, v16
	v_and_b32_e32 v21, 0xffff0000, v16
	v_lshlrev_b32_e32 v16, 16, v17
	v_and_b32_e32 v17, 0xffff0000, v17
	v_lshlrev_b32_e32 v22, 16, v18
	v_and_b32_e32 v23, 0xffff0000, v18
	v_lshlrev_b32_e32 v18, 16, v19
	v_and_b32_e32 v19, 0xffff0000, v19
	v_pk_fma_f32 v[64:65], v[64:65], v[6:7], v[16:17]
	v_pk_fma_f32 v[20:21], v[62:63], v[4:5], v[20:21]
	v_pk_fma_f32 v[60:61], v[60:61], v[2:3], v[18:19]
	v_cvt_pk_bf16_f32 v16, v20, v21
	v_cvt_pk_bf16_f32 v17, v64, v65
	v_pk_fma_f32 v[22:23], v[58:59], v[0:1], v[22:23]
	v_pk_mul_f32 v[58:59], v[74:75], v[60:61]
	v_cvt_pk_bf16_f32 v18, v22, v23
	v_cvt_pk_bf16_f32 v19, v60, v61
	global_store_dwordx4 v[84:85], v[16:19], off nt
	s_nop 1
	v_mul_f32_e32 v16, v21, v21
	v_mul_f32_e32 v17, v65, v65
	v_fmac_f32_e32 v16, v20, v20
	v_fmac_f32_e32 v17, v64, v64
	v_add_f32_e32 v16, v16, v17
	v_mul_f32_e32 v17, v23, v23
	v_mul_f32_e32 v18, v61, v61
	v_fmac_f32_e32 v17, v22, v22
	v_fmac_f32_e32 v18, v60, v60
	v_add_f32_e32 v17, v17, v18
	v_add_f32_e32 v16, v16, v17
	v_add_f32_e32 v57, v57, v16
	ds_bpermute_b32 v62, v168, v57
	v_pk_mul_f32 v[16:17], v[80:81], v[64:65]
	v_pk_mul_f32 v[18:19], v[82:83], v[20:21]
	v_pk_mul_f32 v[20:21], v[76:77], v[22:23]
	v_cvt_pk_bf16_f32 v18, v18, v19
	v_cvt_pk_bf16_f32 v19, v16, v17
	s_waitcnt lgkmcnt(0)
	v_add_f32_e32 v16, v57, v62
	ds_bpermute_b32 v17, v169, v16
	v_lshl_add_u64 v[22:23], s[86:87], 0, v[106:107]
	v_cvt_pk_bf16_f32 v20, v20, v21
	v_cvt_pk_bf16_f32 v21, v58, v59
	global_store_dwordx4 v[22:23], v[18:21], off
	s_and_saveexec_b64 s[24:25], s[0:1]
	s_cbranch_execz .LBB0_900
	v_add_u32_e32 v136, 0x90, v56
	v_lshl_add_u64 v[18:19], v[136:137], 2, s[12:13]
	s_waitcnt lgkmcnt(0)
	v_add_f32_e32 v16, v16, v17
	global_atomic_add_f32 v[18:19], v16, off
;     __device__ __forceinline__ void operator()(const f32x4 (&acc)[2][2][4][2], const Unit& u, int wr, int wc, int fr, int fq) const {
;     ...
;         for (int rg = 0; rg < 8 / RGB; ++rg) {
;             u32x4 braw[INPLACE ? RGB : 1][2]; f32x4 bb[INPLACE ? 1 : RGB][2][2];
; #pragma unroll
;             for (int mm = 0; mm < RGB; ++mm) { const int q = rg * RGB + mm, ai = q >> 2, m = q & 3;
; #pragma unroll
;                 for (int bj = 0; bj < 2; ++bj) { const unsigned e = e0 + (unsigned)((ai * 128 + m * 16) * D + bj * 128);
;                     if constexpr (INPLACE) braw[mm][bj] = *(const u32x4*)(Hc + (size_t)(e * 2u));
;                     else { bb[mm][bj][0] = *(const f32x4*)(bsc + (size_t)(e * 4u)); bb[mm][bj][1] = *(const f32x4*)(bsc + (size_t)(e * 4u + 16u)); } } }
; #pragma unroll
;             for (int mm = 0; mm < RGB; ++mm) { const int q = rg * RGB + mm, ai = q >> 2, m = q & 3; float ssum = 0.f;
; #pragma unroll
;                 for (int bj = 0; bj < 2; ++bj) { const unsigned e = e0 + (unsigned)((ai * 128 + m * 16) * D + bj * 128);
;                     f32x4 r0, r1;
;                     if constexpr (INPLACE) { const u32x4 q4 = braw[mm][bj];
;                         r0 = (f32x4){__uint_as_float(q4[0] << 16), __uint_as_float(q4[0] & 0xffff0000u), __uint_as_float(q4[1] << 16), __uint_as_float(q4[1] & 0xffff0000u)};
;                         r1 = (f32x4){__uint_as_float(q4[2] << 16), __uint_as_float(q4[2] & 0xffff0000u), __uint_as_float(q4[3] << 16), __uint_as_float(q4[3] & 0xffff0000u)}; }
;                     else { r0 = bb[mm][bj][0]; r1 = bb[mm][bj][1]; }
;                     const f32x4 h0 = r0 + gv[bj][0] * (acc[ai][bj][m][0] + bv[bj][0]), h1 = r1 + gv[bj][1] * (acc[ai][bj][m][1] + bv[bj][1]);
;                     { u32x4 w; w.x = cvt_pk_bf16(h0[0], h0[1]); w.y = cvt_pk_bf16(h0[2], h0[3]); w.z = cvt_pk_bf16(h1[0], h1[1]); w.w = cvt_pk_bf16(h1[2], h1[3]); ST16(1, Hc + (size_t)(e * 2u), w); }
;                     if (FUSE) { ssum += ((h0[0] * h0[0] + h0[1] * h0[1]) + (h0[2] * h0[2] + h0[3] * h0[3])) + ((h1[0] * h1[0] + h1[1] * h1[1]) + (h1[2] * h1[2] + h1[3] * h1[3]));
;                         const f32x4 z0 = h0 * wv[bj][0], z1 = h1 * wv[bj][1];
;                         u32x4 w; w.x = cvt_pk_bf16(z0[0], z0[1]); w.y = cvt_pk_bf16(z0[2], z0[3]); w.z = cvt_pk_bf16(z1[0], z1[1]); w.w = cvt_pk_bf16(z1[2], z1[3]);
.LBB0_900:
	s_or_b64 exec, exec, s[24:25]
	v_add_u32_e32 v57, 0x50000, v196
	v_add_u32_e32 v59, 0x50100, v196
	global_load_dwordx4 v[60:63], v57, s[14:15]
	global_load_dwordx4 v[64:67], v59, s[14:15]
	v_add_u32_e32 v136, 0x58000, v196
	v_add_u32_e32 v58, 0x58100, v196
	global_load_dwordx4 v[20:23], v136, s[14:15]
	s_waitcnt lgkmcnt(0)
	global_load_dwordx4 v[16:19], v58, s[14:15]
	s_waitcnt vmcnt(3)
	v_lshlrev_b32_e32 v68, 16, v60
	v_and_b32_e32 v69, 0xffff0000, v60
	v_lshlrev_b32_e32 v60, 16, v61
	v_and_b32_e32 v61, 0xffff0000, v61
	v_lshlrev_b32_e32 v70, 16, v62
	v_and_b32_e32 v71, 0xffff0000, v62
	v_lshlrev_b32_e32 v62, 16, v63
	v_and_b32_e32 v63, 0xffff0000, v63
	s_waitcnt vmcnt(2)
	v_lshlrev_b32_e32 v72, 16, v64
	v_and_b32_e32 v73, 0xffff0000, v64
	v_lshlrev_b32_e32 v64, 16, v65
	v_and_b32_e32 v65, 0xffff0000, v65
	v_lshlrev_b32_e32 v78, 16, v66
	v_and_b32_e32 v79, 0xffff0000, v66
	v_lshlrev_b32_e32 v66, 16, v67
	v_and_b32_e32 v67, 0xffff0000, v67
	v_pk_fma_f32 v[60:61], v[42:43], v[14:15], v[60:61]
	v_pk_fma_f32 v[68:69], v[40:41], v[12:13], v[68:69]
	v_pk_fma_f32 v[44:45], v[44:45], v[10:11], v[62:63]
	v_pk_fma_f32 v[46:47], v[46:47], v[8:9], v[70:71]
	v_pk_fma_f32 v[54:55], v[54:55], v[6:7], v[64:65]
	v_pk_fma_f32 v[52:53], v[52:53], v[4:5], v[72:73]
	v_pk_fma_f32 v[50:51], v[50:51], v[2:3], v[66:67]
	v_pk_fma_f32 v[48:49], v[48:49], v[0:1], v[78:79]
	v_cvt_pk_bf16_f32 v40, v68, v69
	v_cvt_pk_bf16_f32 v41, v60, v61
	v_cvt_pk_bf16_f32 v42, v46, v47
	v_cvt_pk_bf16_f32 v43, v44, v45
	v_mul_f32_e32 v72, v69, v69
	v_mul_f32_e32 v73, v61, v61
	v_mul_f32_e32 v78, v47, v47
	v_mul_f32_e32 v79, v45, v45
	v_pk_mul_f32 v[62:63], v[102:103], v[60:61]
	v_pk_mul_f32 v[64:65], v[104:105], v[68:69]
	v_pk_mul_f32 v[66:67], v[98:99], v[44:45]
	v_pk_mul_f32 v[70:71], v[100:101], v[46:47]
	v_mul_f32_e32 v45, v53, v53
	v_mul_f32_e32 v47, v55, v55
	v_mul_f32_e32 v61, v49, v49
	v_mul_f32_e32 v69, v51, v51
	global_store_dwordx4 v57, v[40:43], s[14:15] nt
	v_fmac_f32_e32 v72, v68, v68
	v_fmac_f32_e32 v73, v60, v60
	v_fmac_f32_e32 v78, v46, v46
	v_fmac_f32_e32 v79, v44, v44
	v_cvt_pk_bf16_f32 v40, v64, v65
	v_fmac_f32_e32 v45, v52, v52
	v_fmac_f32_e32 v47, v54, v54
	v_fmac_f32_e32 v61, v48, v48
	v_fmac_f32_e32 v69, v50, v50
	v_cvt_pk_bf16_f32 v41, v62, v63
	v_cvt_pk_bf16_f32 v42, v70, v71
	v_cvt_pk_bf16_f32 v43, v66, v67
	v_add_f32_e32 v44, v72, v73
	v_add_f32_e32 v46, v78, v79
	global_store_dwordx4 v57, v[40:43], s[86:87]
	v_add_f32_e32 v45, v45, v47
	v_add_f32_e32 v47, v61, v69
	v_cvt_pk_bf16_f32 v40, v52, v53
	v_cvt_pk_bf16_f32 v41, v54, v55
	v_cvt_pk_bf16_f32 v42, v48, v49
	v_cvt_pk_bf16_f32 v43, v50, v51
	v_add_f32_e32 v44, v44, v46
	global_store_dwordx4 v59, v[40:43], s[14:15] nt
	v_pk_mul_f32 v[48:49], v[76:77], v[48:49]
	s_nop 0
	v_add_f32_e32 v40, v45, v47
	v_add_f32_e32 v43, v44, v40
	v_pk_mul_f32 v[44:45], v[80:81], v[54:55]
	ds_bpermute_b32 v54, v168, v43
	v_pk_mul_f32 v[40:41], v[82:83], v[52:53]
	v_pk_mul_f32 v[46:47], v[74:75], v[50:51]
	v_cvt_pk_bf16_f32 v42, v40, v41
	s_waitcnt lgkmcnt(0)
	v_add_f32_e32 v40, v43, v54
	ds_bpermute_b32 v41, v169, v40
	v_cvt_pk_bf16_f32 v43, v44, v45
	v_cvt_pk_bf16_f32 v44, v48, v49
	v_cvt_pk_bf16_f32 v45, v46, v47
	global_store_dwordx4 v59, v[42:45], s[86:87]
	s_and_saveexec_b64 s[24:25], s[0:1]
	s_cbranch_execz .LBB0_902
	v_add_u32_e32 v42, 0xa0, v56
	v_mov_b32_e32 v43, v137
	v_lshl_add_u64 v[42:43], v[42:43], 2, s[12:13]
	s_waitcnt lgkmcnt(0)
	v_add_f32_e32 v40, v40, v41
	global_atomic_add_f32 v[42:43], v40, off
.LBB0_902:
	s_or_b64 exec, exec, s[24:25]
	s_waitcnt vmcnt(5)
	v_lshlrev_b32_e32 v44, 16, v20
	v_and_b32_e32 v45, 0xffff0000, v20
	v_lshlrev_b32_e32 v20, 16, v21
	v_and_b32_e32 v21, 0xffff0000, v21
	v_lshlrev_b32_e32 v46, 16, v22
	v_and_b32_e32 v47, 0xffff0000, v22
	v_lshlrev_b32_e32 v22, 16, v23
	v_and_b32_e32 v23, 0xffff0000, v23
	s_waitcnt lgkmcnt(0)
	v_lshl_add_u64 v[40:41], s[14:15], 0, v[136:137]
	v_pk_fma_f32 v[14:15], v[38:39], v[14:15], v[20:21]
	v_pk_fma_f32 v[12:13], v[36:37], v[12:13], v[44:45]
	v_pk_fma_f32 v[20:21], v[34:35], v[10:11], v[22:23]
	v_pk_fma_f32 v[22:23], v[32:33], v[8:9], v[46:47]
	v_cvt_pk_bf16_f32 v8, v12, v13
	v_cvt_pk_bf16_f32 v9, v14, v15
	v_mov_b32_e32 v59, v137
	v_cvt_pk_bf16_f32 v10, v22, v23
	v_cvt_pk_bf16_f32 v11, v20, v21
	global_store_dwordx4 v[40:41], v[8:11], off nt
	v_lshl_add_u64 v[42:43], s[14:15], 0, v[58:59]
	s_nop 0
	v_mul_f32_e32 v8, v13, v13
	v_mul_f32_e32 v9, v15, v15
	v_fmac_f32_e32 v8, v12, v12
	v_fmac_f32_e32 v9, v14, v14
	v_add_f32_e32 v8, v8, v9
	v_mul_f32_e32 v9, v23, v23
	v_mul_f32_e32 v10, v21, v21
	v_fmac_f32_e32 v9, v22, v22
	v_fmac_f32_e32 v10, v20, v20
	v_add_f32_e32 v9, v9, v10
	v_add_f32_e32 v32, v8, v9
	v_pk_mul_f32 v[10:11], v[102:103], v[14:15]
	v_pk_mul_f32 v[8:9], v[104:105], v[12:13]
	v_pk_mul_f32 v[12:13], v[98:99], v[20:21]
	v_pk_mul_f32 v[14:15], v[100:101], v[22:23]
	v_cvt_pk_bf16_f32 v8, v8, v9
	v_cvt_pk_bf16_f32 v9, v10, v11
	s_nop 0
	v_cvt_pk_bf16_f32 v10, v14, v15
	v_cvt_pk_bf16_f32 v11, v12, v13
	v_lshl_add_u64 v[12:13], s[86:87], 0, v[136:137]
	global_store_dwordx4 v[12:13], v[8:11], off
	s_waitcnt vmcnt(6)
	v_lshlrev_b32_e32 v12, 16, v18
	v_and_b32_e32 v13, 0xffff0000, v18
	v_lshlrev_b32_e32 v8, 16, v16
	v_and_b32_e32 v9, 0xffff0000, v16
	v_lshlrev_b32_e32 v10, 16, v17
	v_and_b32_e32 v11, 0xffff0000, v17
	v_lshlrev_b32_e32 v14, 16, v19
	v_and_b32_e32 v15, 0xffff0000, v19
	v_pk_fma_f32 v[6:7], v[30:31], v[6:7], v[10:11]
	v_pk_fma_f32 v[4:5], v[28:29], v[4:5], v[8:9]
	v_pk_fma_f32 v[10:11], v[24:25], v[0:1], v[12:13]
	v_cvt_pk_bf16_f32 v0, v4, v5
	v_cvt_pk_bf16_f32 v1, v6, v7
	v_pk_fma_f32 v[8:9], v[26:27], v[2:3], v[14:15]
	v_cvt_pk_bf16_f32 v2, v10, v11
	s_nop 0
	v_cvt_pk_bf16_f32 v3, v8, v9
	global_store_dwordx4 v[42:43], v[0:3], off nt
	s_nop 1
	v_mul_f32_e32 v0, v5, v5
	v_mul_f32_e32 v1, v7, v7
	v_fmac_f32_e32 v0, v4, v4
	v_fmac_f32_e32 v1, v6, v6
	v_add_f32_e32 v0, v0, v1
	v_mul_f32_e32 v1, v11, v11
	v_mul_f32_e32 v2, v9, v9
	v_fmac_f32_e32 v1, v10, v10
	v_fmac_f32_e32 v2, v8, v8
	v_add_f32_e32 v1, v1, v2
	v_add_f32_e32 v0, v0, v1
	v_add_f32_e32 v12, v32, v0
	ds_bpermute_b32 v13, v168, v12
	v_pk_mul_f32 v[0:1], v[80:81], v[6:7]
	v_pk_mul_f32 v[2:3], v[82:83], v[4:5]
	v_pk_mul_f32 v[6:7], v[74:75], v[8:9]
	v_cvt_pk_bf16_f32 v2, v2, v3
	v_cvt_pk_bf16_f32 v3, v0, v1
	s_waitcnt lgkmcnt(0)
	v_add_f32_e32 v0, v12, v13
	ds_bpermute_b32 v1, v169, v0
	v_pk_mul_f32 v[4:5], v[76:77], v[10:11]
	s_nop 0
	v_cvt_pk_bf16_f32 v4, v4, v5
	v_cvt_pk_bf16_f32 v5, v6, v7
	v_lshl_add_u64 v[6:7], s[86:87], 0, v[58:59]
	global_store_dwordx4 v[6:7], v[2:5], off
	s_and_saveexec_b64 s[24:25], s[0:1]
	s_cbranch_execz .LBB0_904
	v_add_u32_e32 v136, 0xb0, v56
	v_lshl_add_u64 v[2:3], v[136:137], 2, s[12:13]
	s_waitcnt lgkmcnt(0)
	v_add_f32_e32 v0, v0, v1
	global_atomic_add_f32 v[2:3], v0, off

;     __device__ __forceinline__ void operator()(const f32x4 (&acc)[2][2][4][2], const Unit& u, int wr, int wc, int fr, int fq) const {
;         const int row0 = u.pm * 256 + wr * 64 + fr, col0 = u.pn * 256 + wc * 32 + 8 * fq;
;         const int mb = u.pm < 64 ? (u.pm >> 4) : 4;
;         float* SSn = (float*)(ws + WS_SS) + ss_off;
;         const float* gate = (const float*)(ws + WS_MOD) + gate_off + (size_t)mb * 9216; const float* gn = (const float*)(ws + WS_NG) + gn_off; const float* scn = (const float*)(ws + WS_MOD) + scn_off + (size_t)mb * 9216;
;         f32x4 gv[2][2], bv[2][2], wv[2][2];
; #pragma unroll
;         for (int bj = 0; bj < 2; ++bj)
; #pragma unroll
;             for (int n = 0; n < 2; ++n) { const int cc = col0 + bj * 128 + 4 * n;
;                 gv[bj][n] = *(const f32x4*)(gate + cc) * gmul;
;                 bv[bj][n] = HASBIAS ? *(const f32x4*)(bias + cc) : (f32x4){0.f, 0.f, 0.f, 0.f};
;                 wv[bj][n] = FUSE ? *(const f32x4*)(gn + cc) * (*(const f32x4*)(scn + cc) + 1.0f) : (f32x4){0.f, 0.f, 0.f, 0.f}; }
;         const unsigned e0 = (unsigned)(row0 * D + col0);
;         const char* bsc = (const char*)base0; char* Hc = (char*)(ws + WS_H); char* HBc = (char*)(ws + WS_XN);
;         constexpr int RGB = 2;
; #pragma unroll
;         for (int rg = 0; rg < 8 / RGB; ++rg) {
;             u32x4 braw[INPLACE ? RGB : 1][2]; f32x4 bb[INPLACE ? 1 : RGB][2][2];
; #pragma unroll
;             for (int mm = 0; mm < RGB; ++mm) { const int q = rg * RGB + mm, ai = q >> 2, m = q & 3;
; #pragma unroll
;                 for (int bj = 0; bj < 2; ++bj) { const unsigned e = e0 + (unsigned)((ai * 128 + m * 16) * D + bj * 128);
;                     if constexpr (INPLACE) braw[mm][bj] = *(const u32x4*)(Hc + (size_t)(e * 2u));
;                     else { bb[mm][bj][0] = *(const f32x4*)(bsc + (size_t)(e * 4u)); bb[mm][bj][1] = *(const f32x4*)(bsc + (size_t)(e * 4u + 16u)); } } }
; #pragma unroll
;             for (int mm = 0; mm < RGB; ++mm) { const int q = rg * RGB + mm, ai = q >> 2, m = q & 3; float ssum = 0.f;
; #pragma unroll
;                 for (int bj = 0; bj < 2; ++bj) { const unsigned e = e0 + (unsigned)((ai * 128 + m * 16) * D + bj * 128);
;                     f32x4 r0, r1;
;                     if constexpr (INPLACE) { const u32x4 q4 = braw[mm][bj];
.LBB0_1053:
	s_ashr_i32 s24, s52, 4
	v_lshl_or_b32 v0, s53, 8, v192
	s_mul_i32 s27, s24, 0x9000
	s_mul_hi_i32 s26, s24, 0x9000
	s_add_u32 s24, s45, s27
	s_waitcnt lgkmcnt(0)
	v_ashrrev_i32_e32 v1, 31, v0
	v_lshl_add_u32 v24, s52, 8, v179
	s_addc_u32 s25, s46, s26
	v_lshlrev_b64 v[2:3], 2, v[0:1]
	v_lshlrev_b32_e32 v1, 11, v24
	v_lshl_add_u64 v[4:5], s[24:25], 0, v[2:3]
	v_lshl_add_u32 v196, v0, 1, v1
	global_load_dwordx4 v[60:63], v[4:5], off
	global_load_dwordx4 v[64:67], v[4:5], off offset:16
	global_load_dwordx4 v[70:73], v[4:5], off offset:512
	global_load_dwordx4 v[98:101], v[4:5], off offset:528
	global_load_dwordx4 v[102:105], v196, s[16:17]
	s_add_u32 s24, s47, s27
	s_addc_u32 s25, s48, s26
	v_lshl_add_u64 v[4:5], s[24:25], 0, v[2:3]
	global_load_dwordx4 v[198:201], v[4:5], off
	global_load_dwordx4 v[202:205], v[4:5], off offset:16
	global_load_dwordx4 v[206:209], v[4:5], off offset:512
	global_load_dwordx4 v[210:213], v[4:5], off offset:528
	v_lshl_add_u64 v[2:3], s[12:13], 0, v[2:3]
	global_load_dwordx4 v[214:217], v[2:3], off offset:16
	global_load_dwordx4 v[218:221], v[2:3], off
	v_or_b32_e32 v0, 0x80, v0
	v_ashrrev_i32_e32 v1, 31, v0
	v_lshl_add_u64 v[0:1], v[0:1], 2, s[12:13]
	v_or_b32_e32 v25, 0x100, v196
	global_load_dwordx4 v[222:225], v[0:1], off
	global_load_dwordx4 v[226:229], v[0:1], off offset:16
	global_load_dwordx4 v[230:233], v25, s[16:17]
	v_add_u32_e32 v136, 0x8000, v196
	v_add_u32_e32 v190, 0x8100, v196
	global_load_dwordx4 v[4:7], v136, s[16:17]
	global_load_dwordx4 v[0:3], v190, s[16:17]
	s_waitcnt vmcnt(0)
	v_pk_mul_f32 v[94:95], v[62:63], 0.5 op_sel_hi:[1,0]
	v_pk_mul_f32 v[86:87], v[60:61], 0.5 op_sel_hi:[1,0]
	v_pk_mul_f32 v[84:85], v[66:67], 0.5 op_sel_hi:[1,0]
	v_pk_mul_f32 v[82:83], v[64:65], 0.5 op_sel_hi:[1,0]
	v_pk_mul_f32 v[68:69], v[72:73], 0.5 op_sel_hi:[1,0]
	v_pk_mul_f32 v[66:67], v[70:71], 0.5 op_sel_hi:[1,0]
	v_lshlrev_b32_e32 v62, 16, v102
	v_and_b32_e32 v63, 0xffff0000, v102
	v_lshlrev_b32_e32 v64, 16, v103
	v_and_b32_e32 v65, 0xffff0000, v103
	v_lshlrev_b32_e32 v70, 16, v104
	v_and_b32_e32 v71, 0xffff0000, v104
	v_lshlrev_b32_e32 v72, 16, v105
	v_and_b32_e32 v73, 0xffff0000, v105
	v_pk_fma_f32 v[234:235], v[184:185], v[94:95], v[64:65]
	v_pk_fma_f32 v[188:189], v[188:189], v[86:87], v[62:63]
	v_pk_fma_f32 v[186:187], v[186:187], v[84:85], v[72:73]
	v_pk_fma_f32 v[236:237], v[182:183], v[82:83], v[70:71]
	v_pk_add_f32 v[62:63], v[200:201], 1.0 op_sel_hi:[1,0]
	v_pk_add_f32 v[200:201], v[206:207], 1.0 op_sel_hi:[1,0]
	v_mul_f32_e32 v191, v189, v189
	v_mul_f32_e32 v197, v235, v235
	v_mul_f32_e32 v206, v237, v237
	v_mul_f32_e32 v207, v187, v187
	v_pk_add_f32 v[64:65], v[198:199], 1.0 op_sel_hi:[1,0]
	v_cvt_pk_bf16_f32 v182, v188, v189
	v_cvt_pk_bf16_f32 v183, v234, v235
	v_fmac_f32_e32 v191, v188, v188
	v_fmac_f32_e32 v197, v234, v234
	v_fmac_f32_e32 v206, v236, v236
	v_fmac_f32_e32 v207, v186, v186
	v_pk_add_f32 v[70:71], v[204:205], 1.0 op_sel_hi:[1,0]
	v_pk_add_f32 v[72:73], v[202:203], 1.0 op_sel_hi:[1,0]
	v_cvt_pk_bf16_f32 v184, v236, v237
	v_cvt_pk_bf16_f32 v185, v186, v187
	v_pk_mul_f32 v[102:103], v[220:221], v[62:63]
	v_pk_mul_f32 v[104:105], v[218:219], v[64:65]
	global_store_dwordx4 v196, v[182:185], s[16:17] nt
	v_pk_mul_f32 v[60:61], v[100:101], 0.5 op_sel_hi:[1,0]
	v_pk_mul_f32 v[26:27], v[98:99], 0.5 op_sel_hi:[1,0]
	v_add_f32_e32 v182, v191, v197
	v_add_f32_e32 v183, v206, v207
	v_pk_mul_f32 v[98:99], v[216:217], v[70:71]
	v_pk_mul_f32 v[100:101], v[214:215], v[72:73]
	v_pk_mul_f32 v[184:185], v[102:103], v[234:235]
	v_add_f32_e32 v191, v182, v183
	v_pk_mul_f32 v[182:183], v[104:105], v[188:189]
	v_pk_mul_f32 v[186:187], v[98:99], v[186:187]
	v_pk_mul_f32 v[188:189], v[100:101], v[236:237]
	v_cvt_pk_bf16_f32 v182, v182, v183
	v_cvt_pk_bf16_f32 v183, v184, v185
	v_pk_mul_f32 v[72:73], v[222:223], v[200:201]
	v_cvt_pk_bf16_f32 v184, v188, v189
	v_cvt_pk_bf16_f32 v185, v186, v187
	global_store_dwordx4 v196, v[182:185], s[86:87]
	v_lshlrev_b32_e32 v186, 16, v232
	v_and_b32_e32 v187, 0xffff0000, v232
	v_lshlrev_b32_e32 v182, 16, v230
	v_and_b32_e32 v183, 0xffff0000, v230
	v_lshlrev_b32_e32 v184, 16, v231
	v_and_b32_e32 v185, 0xffff0000, v231
	v_lshlrev_b32_e32 v188, 16, v233
	v_and_b32_e32 v189, 0xffff0000, v233
	v_pk_fma_f32 v[174:175], v[174:175], v[68:69], v[184:185]
	v_pk_fma_f32 v[172:173], v[172:173], v[66:67], v[182:183]
	v_pk_fma_f32 v[184:185], v[168:169], v[26:27], v[186:187]
	v_cvt_pk_bf16_f32 v168, v172, v173
	v_cvt_pk_bf16_f32 v169, v174, v175
	v_pk_fma_f32 v[182:183], v[170:171], v[60:61], v[188:189]
	v_cvt_pk_bf16_f32 v170, v184, v185
	v_pk_add_f32 v[198:199], v[208:209], 1.0 op_sel_hi:[1,0]
	v_cvt_pk_bf16_f32 v171, v182, v183
	global_store_dwordx4 v25, v[168:171], s[16:17] nt
	v_pk_add_f32 v[202:203], v[212:213], 1.0 op_sel_hi:[1,0]
	v_pk_add_f32 v[204:205], v[210:211], 1.0 op_sel_hi:[1,0]
	v_mul_f32_e32 v168, v173, v173
	v_mul_f32_e32 v169, v175, v175
	v_fmac_f32_e32 v168, v172, v172
	v_fmac_f32_e32 v169, v174, v174
	v_add_f32_e32 v168, v168, v169
	v_mul_f32_e32 v169, v185, v185
	v_mul_f32_e32 v170, v183, v183
	v_fmac_f32_e32 v169, v184, v184
	v_fmac_f32_e32 v170, v182, v182
	v_add_f32_e32 v169, v169, v170
	v_add_f32_e32 v168, v168, v169
	v_and_b32_e32 v170, 64, v177
	v_add_f32_e32 v169, v191, v168
	v_xor_b32_e32 v168, 16, v177
	v_add_u32_e32 v186, 64, v170
	v_cmp_lt_i32_e32 vcc, v168, v186
	v_pk_mul_f32 v[170:171], v[72:73], v[172:173]
	v_pk_mul_f32 v[70:71], v[224:225], v[198:199]
	v_cndmask_b32_e32 v168, v177, v168, vcc
	v_lshlrev_b32_e32 v168, 2, v168
	ds_bpermute_b32 v187, v168, v169
	v_cvt_pk_bf16_f32 v172, v170, v171
	v_pk_mul_f32 v[62:63], v[228:229], v[202:203]
	v_pk_mul_f32 v[64:65], v[226:227], v[204:205]
	v_pk_mul_f32 v[174:175], v[70:71], v[174:175]
	s_waitcnt lgkmcnt(0)
	v_add_f32_e32 v170, v169, v187
	v_xor_b32_e32 v169, 32, v177
	v_cmp_lt_i32_e32 vcc, v169, v186
	v_pk_mul_f32 v[182:183], v[62:63], v[182:183]
	v_pk_mul_f32 v[184:185], v[64:65], v[184:185]
	v_cndmask_b32_e32 v169, v177, v169, vcc
	v_lshlrev_b32_e32 v169, 2, v169
	ds_bpermute_b32 v171, v169, v170
	v_cvt_pk_bf16_f32 v173, v174, v175
	v_cvt_pk_bf16_f32 v174, v184, v185
	v_cvt_pk_bf16_f32 v175, v182, v183
	global_store_dwordx4 v25, v[172:175], s[86:87]
	s_and_saveexec_b64 s[24:25], s[0:1]
	s_cbranch_execz .LBB0_1055
	v_mov_b32_e32 v25, v137
	v_lshl_add_u64 v[172:173], v[24:25], 2, s[14:15]
	s_waitcnt lgkmcnt(0)
	v_add_f32_e32 v25, v170, v171
	global_atomic_add_f32 v[172:173], v25, off
;     __device__ __forceinline__ void operator()(const f32x4 (&acc)[2][2][4][2], const Unit& u, int wr, int wc, int fr, int fq) const {
;     ...
;         for (int rg = 0; rg < 8 / RGB; ++rg) {
;             u32x4 braw[INPLACE ? RGB : 1][2]; f32x4 bb[INPLACE ? 1 : RGB][2][2];
; #pragma unroll
;             for (int mm = 0; mm < RGB; ++mm) { const int q = rg * RGB + mm, ai = q >> 2, m = q & 3;
; #pragma unroll
;                 for (int bj = 0; bj < 2; ++bj) { const unsigned e = e0 + (unsigned)((ai * 128 + m * 16) * D + bj * 128);
;                     if constexpr (INPLACE) braw[mm][bj] = *(const u32x4*)(Hc + (size_t)(e * 2u));
;                     else { bb[mm][bj][0] = *(const f32x4*)(bsc + (size_t)(e * 4u)); bb[mm][bj][1] = *(const f32x4*)(bsc + (size_t)(e * 4u + 16u)); } } }
; #pragma unroll
;             for (int mm = 0; mm < RGB; ++mm) { const int q = rg * RGB + mm, ai = q >> 2, m = q & 3; float ssum = 0.f;
; #pragma unroll
;                 for (int bj = 0; bj < 2; ++bj) { const unsigned e = e0 + (unsigned)((ai * 128 + m * 16) * D + bj * 128);
;                     f32x4 r0, r1;
;                     if constexpr (INPLACE) { const u32x4 q4 = braw[mm][bj];
;                         r0 = (f32x4){__uint_as_float(q4[0] << 16), __uint_as_float(q4[0] & 0xffff0000u), __uint_as_float(q4[1] << 16), __uint_as_float(q4[1] & 0xffff0000u)};
;                         r1 = (f32x4){__uint_as_float(q4[2] << 16), __uint_as_float(q4[2] & 0xffff0000u), __uint_as_float(q4[3] << 16), __uint_as_float(q4[3] & 0xffff0000u)}; }
;                     else { r0 = bb[mm][bj][0]; r1 = bb[mm][bj][1]; }
;                     const f32x4 h0 = r0 + gv[bj][0] * (acc[ai][bj][m][0] + bv[bj][0]), h1 = r1 + gv[bj][1] * (acc[ai][bj][m][1] + bv[bj][1]);
;                     { u32x4 w; w.x = cvt_pk_bf16(h0[0], h0[1]); w.y = cvt_pk_bf16(h0[2], h0[3]); w.z = cvt_pk_bf16(h1[0], h1[1]); w.w = cvt_pk_bf16(h1[2], h1[3]); ST16(1, Hc + (size_t)(e * 2u), w); }
;                     if (FUSE) { ssum += ((h0[0] * h0[0] + h0[1] * h0[1]) + (h0[2] * h0[2] + h0[3] * h0[3])) + ((h1[0] * h1[0] + h1[1] * h1[1]) + (h1[2] * h1[2] + h1[3] * h1[3]));
;                         const f32x4 z0 = h0 * wv[bj][0], z1 = h1 * wv[bj][1];
;                         u32x4 w; w.x = cvt_pk_bf16(z0[0], z0[1]); w.y = cvt_pk_bf16(z0[2], z0[3]); w.z = cvt_pk_bf16(z1[0], z1[1]); w.w = cvt_pk_bf16(z1[2], z1[3]);
.LBB0_1055:
	s_or_b64 exec, exec, s[24:25]
	v_lshlrev_b32_e32 v174, 16, v4
	v_and_b32_e32 v175, 0xffff0000, v4
	v_lshlrev_b32_e32 v4, 16, v5
	v_and_b32_e32 v5, 0xffff0000, v5
	s_waitcnt lgkmcnt(0)
	v_lshl_add_u64 v[170:171], s[16:17], 0, v[136:137]
	v_lshlrev_b32_e32 v182, 16, v6
	v_and_b32_e32 v183, 0xffff0000, v6
	v_lshlrev_b32_e32 v6, 16, v7
	v_and_b32_e32 v7, 0xffff0000, v7
	v_pk_fma_f32 v[166:167], v[166:167], v[94:95], v[4:5]
	v_pk_fma_f32 v[164:165], v[164:165], v[86:87], v[174:175]
	v_pk_fma_f32 v[162:163], v[162:163], v[84:85], v[6:7]
	v_cvt_pk_bf16_f32 v4, v164, v165
	v_cvt_pk_bf16_f32 v5, v166, v167
	v_pk_fma_f32 v[160:161], v[160:161], v[82:83], v[182:183]
	v_mov_b32_e32 v191, v137
	v_cvt_pk_bf16_f32 v6, v160, v161
	v_cvt_pk_bf16_f32 v7, v162, v163
	global_store_dwordx4 v[170:171], v[4:7], off nt
	v_lshl_add_u64 v[172:173], s[16:17], 0, v[190:191]
	s_nop 0
	v_mul_f32_e32 v4, v165, v165
	v_mul_f32_e32 v5, v167, v167
	v_fmac_f32_e32 v4, v164, v164
	v_fmac_f32_e32 v5, v166, v166
	v_add_f32_e32 v4, v4, v5
	v_mul_f32_e32 v5, v161, v161
	v_mul_f32_e32 v6, v163, v163
	v_fmac_f32_e32 v5, v160, v160
	v_fmac_f32_e32 v6, v162, v162
	v_add_f32_e32 v5, v5, v6
	v_add_f32_e32 v25, v4, v5
	v_pk_mul_f32 v[6:7], v[102:103], v[166:167]
	v_pk_mul_f32 v[4:5], v[104:105], v[164:165]
	v_pk_mul_f32 v[160:161], v[100:101], v[160:161]
	v_cvt_pk_bf16_f32 v4, v4, v5
	v_cvt_pk_bf16_f32 v5, v6, v7
	v_pk_mul_f32 v[162:163], v[98:99], v[162:163]
	v_cvt_pk_bf16_f32 v6, v160, v161
	v_lshl_add_u64 v[160:161], s[86:87], 0, v[136:137]
	v_cvt_pk_bf16_f32 v7, v162, v163
	global_store_dwordx4 v[160:161], v[4:7], off
	s_nop 1
	v_lshlrev_b32_e32 v4, 16, v0
	v_and_b32_e32 v5, 0xffff0000, v0
	v_lshlrev_b32_e32 v0, 16, v1
	v_and_b32_e32 v1, 0xffff0000, v1
	v_lshlrev_b32_e32 v6, 16, v2
	v_and_b32_e32 v7, 0xffff0000, v2
	v_lshlrev_b32_e32 v2, 16, v3
	v_and_b32_e32 v3, 0xffff0000, v3
	v_pk_fma_f32 v[158:159], v[158:159], v[68:69], v[0:1]
	v_pk_fma_f32 v[4:5], v[156:157], v[66:67], v[4:5]
	v_pk_fma_f32 v[154:155], v[154:155], v[60:61], v[2:3]
	v_cvt_pk_bf16_f32 v0, v4, v5
	v_cvt_pk_bf16_f32 v1, v158, v159
	v_pk_fma_f32 v[6:7], v[152:153], v[26:27], v[6:7]
	v_pk_mul_f32 v[152:153], v[62:63], v[154:155]
	v_cvt_pk_bf16_f32 v2, v6, v7
	v_cvt_pk_bf16_f32 v3, v154, v155
	global_store_dwordx4 v[172:173], v[0:3], off nt
	s_nop 1
	v_mul_f32_e32 v0, v5, v5
	v_mul_f32_e32 v1, v159, v159
	v_fmac_f32_e32 v0, v4, v4
	v_fmac_f32_e32 v1, v158, v158
	v_add_f32_e32 v0, v0, v1
	v_mul_f32_e32 v1, v7, v7
	v_mul_f32_e32 v2, v155, v155
	v_fmac_f32_e32 v1, v6, v6
	v_fmac_f32_e32 v2, v154, v154
	v_add_f32_e32 v1, v1, v2
	v_add_f32_e32 v0, v0, v1
	v_add_f32_e32 v25, v25, v0
	ds_bpermute_b32 v136, v168, v25
	v_pk_mul_f32 v[0:1], v[70:71], v[158:159]
	v_pk_mul_f32 v[2:3], v[72:73], v[4:5]
	v_pk_mul_f32 v[4:5], v[64:65], v[6:7]
	v_cvt_pk_bf16_f32 v2, v2, v3
	v_cvt_pk_bf16_f32 v3, v0, v1
	s_waitcnt lgkmcnt(0)
	v_add_f32_e32 v0, v25, v136
	ds_bpermute_b32 v1, v169, v0
	v_lshl_add_u64 v[6:7], s[86:87], 0, v[190:191]
	v_cvt_pk_bf16_f32 v4, v4, v5
	v_cvt_pk_bf16_f32 v5, v152, v153
	global_store_dwordx4 v[6:7], v[2:5], off
	s_and_saveexec_b64 s[24:25], s[0:1]
	s_cbranch_execz .LBB0_1057
	v_or_b32_e32 v136, 16, v24
	v_lshl_add_u64 v[2:3], v[136:137], 2, s[14:15]
	s_waitcnt lgkmcnt(0)
	v_add_f32_e32 v0, v0, v1
	global_atomic_add_f32 v[2:3], v0, off
.LBB0_1057:
	s_or_b64 exec, exec, s[24:25]
	v_add_u32_e32 v25, 0x10000, v196
	v_add_u32_e32 v153, 0x10100, v196
	global_load_dwordx4 v[154:157], v25, s[16:17]
	global_load_dwordx4 v[158:161], v153, s[16:17]
	v_add_u32_e32 v136, 0x18000, v196
	v_add_u32_e32 v152, 0x18100, v196
	global_load_dwordx4 v[4:7], v136, s[16:17]
	s_waitcnt lgkmcnt(0)
	global_load_dwordx4 v[0:3], v152, s[16:17]
	s_waitcnt vmcnt(3)
	v_lshlrev_b32_e32 v162, 16, v154
	v_and_b32_e32 v163, 0xffff0000, v154
	v_lshlrev_b32_e32 v154, 16, v155
	v_and_b32_e32 v155, 0xffff0000, v155
	v_lshlrev_b32_e32 v164, 16, v156
	v_and_b32_e32 v165, 0xffff0000, v156
	v_lshlrev_b32_e32 v156, 16, v157
	v_and_b32_e32 v157, 0xffff0000, v157
	s_waitcnt vmcnt(2)
	v_lshlrev_b32_e32 v166, 16, v158
	v_and_b32_e32 v167, 0xffff0000, v158
	v_lshlrev_b32_e32 v158, 16, v159
	v_and_b32_e32 v159, 0xffff0000, v159
	v_lshlrev_b32_e32 v170, 16, v160
	v_and_b32_e32 v171, 0xffff0000, v160
	v_lshlrev_b32_e32 v160, 16, v161
	v_and_b32_e32 v161, 0xffff0000, v161
	v_pk_fma_f32 v[154:155], v[122:123], v[94:95], v[154:155]
	v_pk_fma_f32 v[162:163], v[124:125], v[86:87], v[162:163]
	v_pk_fma_f32 v[126:127], v[126:127], v[84:85], v[156:157]
	v_pk_fma_f32 v[142:143], v[142:143], v[82:83], v[164:165]
	v_pk_fma_f32 v[150:151], v[150:151], v[68:69], v[158:159]
	v_pk_fma_f32 v[148:149], v[148:149], v[66:67], v[166:167]
	v_pk_fma_f32 v[146:147], v[146:147], v[60:61], v[160:161]
	v_pk_fma_f32 v[144:145], v[144:145], v[26:27], v[170:171]
	v_cvt_pk_bf16_f32 v122, v162, v163
	v_cvt_pk_bf16_f32 v123, v154, v155
	v_cvt_pk_bf16_f32 v124, v142, v143
	v_cvt_pk_bf16_f32 v125, v126, v127
	v_mul_f32_e32 v166, v163, v163
	v_mul_f32_e32 v167, v155, v155
	v_mul_f32_e32 v170, v143, v143
	v_mul_f32_e32 v171, v127, v127
	v_pk_mul_f32 v[156:157], v[102:103], v[154:155]
	v_pk_mul_f32 v[158:159], v[104:105], v[162:163]
	v_pk_mul_f32 v[160:161], v[98:99], v[126:127]
	v_pk_mul_f32 v[164:165], v[100:101], v[142:143]
	v_mul_f32_e32 v127, v149, v149
	v_mul_f32_e32 v143, v151, v151
	v_mul_f32_e32 v155, v145, v145
	v_mul_f32_e32 v163, v147, v147
	v_fmac_f32_e32 v166, v162, v162
	v_fmac_f32_e32 v167, v154, v154
	v_fmac_f32_e32 v170, v142, v142
	v_fmac_f32_e32 v171, v126, v126
	v_fmac_f32_e32 v127, v148, v148
	v_fmac_f32_e32 v143, v150, v150
	v_fmac_f32_e32 v155, v144, v144
	v_fmac_f32_e32 v163, v146, v146
	global_store_dwordx4 v25, v[122:125], s[16:17] nt
	v_add_f32_e32 v126, v166, v167
	v_add_f32_e32 v142, v170, v171
	v_cvt_pk_bf16_f32 v122, v158, v159
	v_cvt_pk_bf16_f32 v123, v156, v157
	v_cvt_pk_bf16_f32 v124, v164, v165
	v_cvt_pk_bf16_f32 v125, v160, v161
	global_store_dwordx4 v25, v[122:125], s[86:87]
	v_add_f32_e32 v25, v127, v143
	v_add_f32_e32 v127, v155, v163
	v_add_f32_e32 v126, v126, v142
	v_add_f32_e32 v25, v25, v127
	v_cvt_pk_bf16_f32 v122, v148, v149
	v_cvt_pk_bf16_f32 v123, v150, v151
	v_cvt_pk_bf16_f32 v124, v144, v145
	v_cvt_pk_bf16_f32 v125, v146, v147
	v_add_f32_e32 v25, v126, v25
	global_store_dwordx4 v153, v[122:125], s[16:17] nt
	ds_bpermute_b32 v125, v168, v25
	v_pk_mul_f32 v[126:127], v[70:71], v[150:151]
	v_pk_mul_f32 v[122:123], v[72:73], v[148:149]
	v_pk_mul_f32 v[142:143], v[62:63], v[146:147]
	v_cvt_pk_bf16_f32 v124, v122, v123
	s_waitcnt lgkmcnt(0)
	v_add_f32_e32 v25, v25, v125
	ds_bpermute_b32 v122, v169, v25
	v_pk_mul_f32 v[144:145], v[64:65], v[144:145]
	v_cvt_pk_bf16_f32 v125, v126, v127
	s_nop 0
	v_cvt_pk_bf16_f32 v126, v144, v145
	v_cvt_pk_bf16_f32 v127, v142, v143
	global_store_dwordx4 v153, v[124:127], s[86:87]
	s_and_saveexec_b64 s[24:25], s[0:1]
	s_cbranch_execz .LBB0_1059
;     __device__ __forceinline__ void operator()(const f32x4 (&acc)[2][2][4][2], const Unit& u, int wr, int wc, int fr, int fq) const {
;     ...
;         for (int rg = 0; rg < 8 / RGB; ++rg) {
;             u32x4 braw[INPLACE ? RGB : 1][2]; f32x4 bb[INPLACE ? 1 : RGB][2][2];
; #pragma unroll
;             for (int mm = 0; mm < RGB; ++mm) { const int q = rg * RGB + mm, ai = q >> 2, m = q & 3;
; #pragma unroll
;                 for (int bj = 0; bj < 2; ++bj) { const unsigned e = e0 + (unsigned)((ai * 128 + m * 16) * D + bj * 128);
;                     if constexpr (INPLACE) braw[mm][bj] = *(const u32x4*)(Hc + (size_t)(e * 2u));
;                     else { bb[mm][bj][0] = *(const f32x4*)(bsc + (size_t)(e * 4u)); bb[mm][bj][1] = *(const f32x4*)(bsc + (size_t)(e * 4u + 16u)); } } }
; #pragma unroll
;             for (int mm = 0; mm < RGB; ++mm) { const int q = rg * RGB + mm, ai = q >> 2, m = q & 3; float ssum = 0.f;
; #pragma unroll
;                 for (int bj = 0; bj < 2; ++bj) { const unsigned e = e0 + (unsigned)((ai * 128 + m * 16) * D + bj * 128);
;                     f32x4 r0, r1;
;                     if constexpr (INPLACE) { const u32x4 q4 = braw[mm][bj];
;                         r0 = (f32x4){__uint_as_float(q4[0] << 16), __uint_as_float(q4[0] & 0xffff0000u), __uint_as_float(q4[1] << 16), __uint_as_float(q4[1] & 0xffff0000u)};
;                         r1 = (f32x4){__uint_as_float(q4[2] << 16), __uint_as_float(q4[2] & 0xffff0000u), __uint_as_float(q4[3] << 16), __uint_as_float(q4[3] & 0xffff0000u)}; }
;                     else { r0 = bb[mm][bj][0]; r1 = bb[mm][bj][1]; }
;                     const f32x4 h0 = r0 + gv[bj][0] * (acc[ai][bj][m][0] + bv[bj][0]), h1 = r1 + gv[bj][1] * (acc[ai][bj][m][1] + bv[bj][1]);
;                     { u32x4 w; w.x = cvt_pk_bf16(h0[0], h0[1]); w.y = cvt_pk_bf16(h0[2], h0[3]); w.z = cvt_pk_bf16(h1[0], h1[1]); w.w = cvt_pk_bf16(h1[2], h1[3]); ST16(1, Hc + (size_t)(e * 2u), w); }
;                     if (FUSE) { ssum += ((h0[0] * h0[0] + h0[1] * h0[1]) + (h0[2] * h0[2] + h0[3] * h0[3])) + ((h1[0] * h1[0] + h1[1] * h1[1]) + (h1[2] * h1[2] + h1[3] * h1[3]));
;                         const f32x4 z0 = h0 * wv[bj][0], z1 = h1 * wv[bj][1];
;                         u32x4 w; w.x = cvt_pk_bf16(z0[0], z0[1]); w.y = cvt_pk_bf16(z0[2], z0[3]); w.z = cvt_pk_bf16(z1[0], z1[1]); w.w = cvt_pk_bf16(z1[2], z1[3]);
	v_or_b32_e32 v124, 32, v24
	v_mov_b32_e32 v125, v137
	v_lshl_add_u64 v[124:125], v[124:125], 2, s[14:15]
	s_waitcnt lgkmcnt(0)
	v_add_f32_e32 v25, v25, v122
	global_atomic_add_f32 v[124:125], v25, off
.LBB0_1059:
	s_or_b64 exec, exec, s[24:25]
	s_waitcnt vmcnt(5)
	v_lshlrev_b32_e32 v126, 16, v4
	v_and_b32_e32 v127, 0xffff0000, v4
	v_lshlrev_b32_e32 v4, 16, v5
	v_and_b32_e32 v5, 0xffff0000, v5
	s_waitcnt lgkmcnt(0)
	v_lshl_add_u64 v[122:123], s[16:17], 0, v[136:137]
	v_lshlrev_b32_e32 v142, 16, v6
	v_and_b32_e32 v143, 0xffff0000, v6
	v_lshlrev_b32_e32 v6, 16, v7
	v_and_b32_e32 v7, 0xffff0000, v7
	v_pk_fma_f32 v[120:121], v[120:121], v[94:95], v[4:5]
	v_pk_fma_f32 v[118:119], v[118:119], v[86:87], v[126:127]
	v_pk_fma_f32 v[116:117], v[116:117], v[84:85], v[6:7]
	v_cvt_pk_bf16_f32 v4, v118, v119
	v_cvt_pk_bf16_f32 v5, v120, v121
	v_pk_fma_f32 v[114:115], v[114:115], v[82:83], v[142:143]
	v_mov_b32_e32 v153, v137
	v_cvt_pk_bf16_f32 v6, v114, v115
	v_cvt_pk_bf16_f32 v7, v116, v117
	global_store_dwordx4 v[122:123], v[4:7], off nt
	v_lshl_add_u64 v[124:125], s[16:17], 0, v[152:153]
	s_nop 0
	v_mul_f32_e32 v4, v119, v119
	v_mul_f32_e32 v5, v121, v121
	v_fmac_f32_e32 v4, v118, v118
	v_fmac_f32_e32 v5, v120, v120
	v_add_f32_e32 v4, v4, v5
	v_mul_f32_e32 v5, v115, v115
	v_mul_f32_e32 v6, v117, v117
	v_fmac_f32_e32 v5, v114, v114
	v_fmac_f32_e32 v6, v116, v116
	v_add_f32_e32 v5, v5, v6
	v_add_f32_e32 v25, v4, v5
	v_pk_mul_f32 v[6:7], v[102:103], v[120:121]
	v_pk_mul_f32 v[4:5], v[104:105], v[118:119]
	v_pk_mul_f32 v[114:115], v[100:101], v[114:115]
	v_cvt_pk_bf16_f32 v4, v4, v5
	v_cvt_pk_bf16_f32 v5, v6, v7
	v_pk_mul_f32 v[116:117], v[98:99], v[116:117]
	v_cvt_pk_bf16_f32 v6, v114, v115
	v_lshl_add_u64 v[114:115], s[86:87], 0, v[136:137]
	v_cvt_pk_bf16_f32 v7, v116, v117
	global_store_dwordx4 v[114:115], v[4:7], off
	s_waitcnt vmcnt(6)
	s_nop 0
	v_lshlrev_b32_e32 v4, 16, v0
	v_and_b32_e32 v5, 0xffff0000, v0
	v_lshlrev_b32_e32 v0, 16, v1
	v_and_b32_e32 v1, 0xffff0000, v1
	v_lshlrev_b32_e32 v6, 16, v2
	v_and_b32_e32 v7, 0xffff0000, v2
	v_lshlrev_b32_e32 v2, 16, v3
	v_and_b32_e32 v3, 0xffff0000, v3
	v_pk_fma_f32 v[112:113], v[112:113], v[68:69], v[0:1]
	v_pk_fma_f32 v[4:5], v[110:111], v[66:67], v[4:5]
	v_pk_fma_f32 v[108:109], v[108:109], v[60:61], v[2:3]
	v_cvt_pk_bf16_f32 v0, v4, v5
	v_cvt_pk_bf16_f32 v1, v112, v113
	v_pk_fma_f32 v[6:7], v[106:107], v[26:27], v[6:7]
	v_pk_mul_f32 v[106:107], v[62:63], v[108:109]
	v_cvt_pk_bf16_f32 v2, v6, v7
	v_cvt_pk_bf16_f32 v3, v108, v109
	global_store_dwordx4 v[124:125], v[0:3], off nt
	s_nop 1
	v_mul_f32_e32 v0, v5, v5
	v_mul_f32_e32 v1, v113, v113
	v_fmac_f32_e32 v0, v4, v4
	v_fmac_f32_e32 v1, v112, v112
	v_add_f32_e32 v0, v0, v1
	v_mul_f32_e32 v1, v7, v7
	v_mul_f32_e32 v2, v109, v109
	v_fmac_f32_e32 v1, v6, v6
	v_fmac_f32_e32 v2, v108, v108
	v_add_f32_e32 v1, v1, v2
	v_add_f32_e32 v0, v0, v1
	v_add_f32_e32 v25, v25, v0
	ds_bpermute_b32 v110, v168, v25
	v_pk_mul_f32 v[0:1], v[70:71], v[112:113]
	v_pk_mul_f32 v[2:3], v[72:73], v[4:5]
	v_pk_mul_f32 v[4:5], v[64:65], v[6:7]
	v_cvt_pk_bf16_f32 v2, v2, v3
	v_cvt_pk_bf16_f32 v3, v0, v1
	s_waitcnt lgkmcnt(0)
	v_add_f32_e32 v0, v25, v110
	ds_bpermute_b32 v1, v169, v0
	v_lshl_add_u64 v[6:7], s[86:87], 0, v[152:153]
	v_cvt_pk_bf16_f32 v4, v4, v5
	v_cvt_pk_bf16_f32 v5, v106, v107
	global_store_dwordx4 v[6:7], v[2:5], off
	s_and_saveexec_b64 s[24:25], s[0:1]
	s_cbranch_execz .LBB0_1061
	v_or_b32_e32 v136, 48, v24
	v_lshl_add_u64 v[2:3], v[136:137], 2, s[14:15]
	s_waitcnt lgkmcnt(0)
	v_add_f32_e32 v0, v0, v1
	global_atomic_add_f32 v[2:3], v0, off
.LBB0_1061:
	s_or_b64 exec, exec, s[24:25]
	v_add_u32_e32 v25, 0x40000, v196
	v_add_u32_e32 v107, 0x40100, v196
	global_load_dwordx4 v[108:111], v25, s[16:17]
	global_load_dwordx4 v[112:115], v107, s[16:17]
	v_add_u32_e32 v136, 0x48000, v196
	v_add_u32_e32 v106, 0x48100, v196
	global_load_dwordx4 v[4:7], v136, s[16:17]
	s_waitcnt lgkmcnt(0)
	global_load_dwordx4 v[0:3], v106, s[16:17]
	s_waitcnt vmcnt(3)
	v_lshlrev_b32_e32 v116, 16, v108
	v_and_b32_e32 v117, 0xffff0000, v108
	v_lshlrev_b32_e32 v108, 16, v109
	v_and_b32_e32 v109, 0xffff0000, v109
	v_lshlrev_b32_e32 v118, 16, v110
	v_and_b32_e32 v119, 0xffff0000, v110
	v_lshlrev_b32_e32 v110, 16, v111
	v_and_b32_e32 v111, 0xffff0000, v111
	s_waitcnt vmcnt(2)
	v_lshlrev_b32_e32 v120, 16, v112
	v_and_b32_e32 v121, 0xffff0000, v112
	v_lshlrev_b32_e32 v112, 16, v113
	v_and_b32_e32 v113, 0xffff0000, v113
	v_lshlrev_b32_e32 v122, 16, v114
	v_and_b32_e32 v123, 0xffff0000, v114
	v_lshlrev_b32_e32 v114, 16, v115
	v_and_b32_e32 v115, 0xffff0000, v115
	v_pk_fma_f32 v[108:109], v[74:75], v[94:95], v[108:109]
	v_pk_fma_f32 v[116:117], v[76:77], v[86:87], v[116:117]
	v_pk_fma_f32 v[78:79], v[78:79], v[84:85], v[110:111]
	v_pk_fma_f32 v[80:81], v[80:81], v[82:83], v[118:119]
	v_pk_fma_f32 v[96:97], v[96:97], v[68:69], v[112:113]
	v_pk_fma_f32 v[92:93], v[92:93], v[66:67], v[120:121]
	v_pk_fma_f32 v[90:91], v[90:91], v[60:61], v[114:115]
	v_pk_fma_f32 v[88:89], v[88:89], v[26:27], v[122:123]
	v_cvt_pk_bf16_f32 v74, v116, v117
	v_cvt_pk_bf16_f32 v75, v108, v109
	v_cvt_pk_bf16_f32 v76, v80, v81
	v_cvt_pk_bf16_f32 v77, v78, v79
	v_mul_f32_e32 v120, v117, v117
	v_mul_f32_e32 v121, v109, v109
	v_mul_f32_e32 v122, v81, v81
	v_mul_f32_e32 v123, v79, v79
	v_pk_mul_f32 v[110:111], v[102:103], v[108:109]
	v_pk_mul_f32 v[112:113], v[104:105], v[116:117]
	v_pk_mul_f32 v[114:115], v[98:99], v[78:79]
	v_pk_mul_f32 v[118:119], v[100:101], v[80:81]
	v_mul_f32_e32 v79, v93, v93
	v_mul_f32_e32 v81, v97, v97
	v_mul_f32_e32 v109, v89, v89
	v_mul_f32_e32 v117, v91, v91
	v_fmac_f32_e32 v120, v116, v116
	v_fmac_f32_e32 v121, v108, v108
	v_fmac_f32_e32 v122, v80, v80
	v_fmac_f32_e32 v123, v78, v78
	v_fmac_f32_e32 v79, v92, v92
	v_fmac_f32_e32 v81, v96, v96
	v_fmac_f32_e32 v109, v88, v88
	v_fmac_f32_e32 v117, v90, v90
	global_store_dwordx4 v25, v[74:77], s[16:17] nt
	v_add_f32_e32 v78, v120, v121
	v_add_f32_e32 v80, v122, v123
	v_cvt_pk_bf16_f32 v74, v112, v113
	v_cvt_pk_bf16_f32 v75, v110, v111
	v_cvt_pk_bf16_f32 v76, v118, v119
	v_cvt_pk_bf16_f32 v77, v114, v115
	global_store_dwordx4 v25, v[74:77], s[86:87]
	v_add_f32_e32 v25, v79, v81
	v_add_f32_e32 v79, v109, v117
	v_add_f32_e32 v78, v78, v80
	v_add_f32_e32 v25, v25, v79
	v_cvt_pk_bf16_f32 v74, v92, v93
	v_cvt_pk_bf16_f32 v75, v96, v97
	v_cvt_pk_bf16_f32 v76, v88, v89
	v_cvt_pk_bf16_f32 v77, v90, v91
	v_add_f32_e32 v25, v78, v25
	global_store_dwordx4 v107, v[74:77], s[16:17] nt
	ds_bpermute_b32 v77, v168, v25
	v_pk_mul_f32 v[78:79], v[70:71], v[96:97]
	v_pk_mul_f32 v[74:75], v[72:73], v[92:93]
	v_pk_mul_f32 v[80:81], v[62:63], v[90:91]
	v_cvt_pk_bf16_f32 v76, v74, v75
	s_waitcnt lgkmcnt(0)
	v_add_f32_e32 v25, v25, v77
	ds_bpermute_b32 v74, v169, v25
	v_pk_mul_f32 v[88:89], v[64:65], v[88:89]
	v_cvt_pk_bf16_f32 v77, v78, v79
	s_nop 0
	v_cvt_pk_bf16_f32 v78, v88, v89
	v_cvt_pk_bf16_f32 v79, v80, v81
	global_store_dwordx4 v107, v[76:79], s[86:87]
	s_and_saveexec_b64 s[24:25], s[0:1]
	s_cbranch_execz .LBB0_1063
; __device__ __forceinline__ unsigned cvt_pk_bf16(float lo, float hi) { unsigned r; asm volatile("v_cvt_pk_bf16_f32 %0, %1, %2" : "=v"(r) : "v"(lo), "v"(hi)); return r; }
; #define ST16(grp, p, v) do { if ((NTG >> (grp)) & 1) NT16(p, v); else PL16(p, v); } while (0)
;     __device__ __forceinline__ void operator()(const f32x4 (&acc)[2][2][4][2], const Unit& u, int wr, int wc, int fr, int fq) const {
;     ...
;             for (int mm = 0; mm < RGB; ++mm) { const int q = rg * RGB + mm, ai = q >> 2, m = q & 3; float ssum = 0.f;
; #pragma unroll
;                 for (int bj = 0; bj < 2; ++bj) { const unsigned e = e0 + (unsigned)((ai * 128 + m * 16) * D + bj * 128);
;                     f32x4 r0, r1;
;                     if constexpr (INPLACE) { const u32x4 q4 = braw[mm][bj];
;                         r0 = (f32x4){__uint_as_float(q4[0] << 16), __uint_as_float(q4[0] & 0xffff0000u), __uint_as_float(q4[1] << 16), __uint_as_float(q4[1] & 0xffff0000u)};
;                         r1 = (f32x4){__uint_as_float(q4[2] << 16), __uint_as_float(q4[2] & 0xffff0000u), __uint_as_float(q4[3] << 16), __uint_as_float(q4[3] & 0xffff0000u)}; }
;                     else { r0 = bb[mm][bj][0]; r1 = bb[mm][bj][1]; }
;                     const f32x4 h0 = r0 + gv[bj][0] * (acc[ai][bj][m][0] + bv[bj][0]), h1 = r1 + gv[bj][1] * (acc[ai][bj][m][1] + bv[bj][1]);
;                     { u32x4 w; w.x = cvt_pk_bf16(h0[0], h0[1]); w.y = cvt_pk_bf16(h0[2], h0[3]); w.z = cvt_pk_bf16(h1[0], h1[1]); w.w = cvt_pk_bf16(h1[2], h1[3]); ST16(1, Hc + (size_t)(e * 2u), w); }
;                     if (FUSE) { ssum += ((h0[0] * h0[0] + h0[1] * h0[1]) + (h0[2] * h0[2] + h0[3] * h0[3])) + ((h1[0] * h1[0] + h1[1] * h1[1]) + (h1[2] * h1[2] + h1[3] * h1[3]));
;                         const f32x4 z0 = h0 * wv[bj][0], z1 = h1 * wv[bj][1];
;                         u32x4 w; w.x = cvt_pk_bf16(z0[0], z0[1]); w.y = cvt_pk_bf16(z0[2], z0[3]); w.z = cvt_pk_bf16(z1[0], z1[1]); w.w = cvt_pk_bf16(z1[2], z1[3]);
;                         ST16(2, HBc + (size_t)(e * 2u), w); } }
;                 if (FUSE) { ssum += __shfl_xor(ssum, 16); ssum += __shfl_xor(ssum, 32); if (fq == 0) unsafeAtomicAdd(SSn + (unsigned)(row0 + ai * 128 + m * 16), ssum); } }
;             asm volatile("" ::: "memory"); }
	v_add_u32_e32 v76, 0x80, v24
	v_mov_b32_e32 v77, v137
	v_lshl_add_u64 v[76:77], v[76:77], 2, s[14:15]
	s_waitcnt lgkmcnt(0)
	v_add_f32_e32 v25, v25, v74
	global_atomic_add_f32 v[76:77], v25, off
.LBB0_1063:
	s_or_b64 exec, exec, s[24:25]
	s_waitcnt vmcnt(5)
	v_lshlrev_b32_e32 v78, 16, v4
	v_and_b32_e32 v79, 0xffff0000, v4
	v_lshlrev_b32_e32 v4, 16, v5
	v_and_b32_e32 v5, 0xffff0000, v5
	s_waitcnt lgkmcnt(0)
	v_lshl_add_u64 v[74:75], s[16:17], 0, v[136:137]
	v_lshlrev_b32_e32 v80, 16, v6
	v_and_b32_e32 v81, 0xffff0000, v6
	v_lshlrev_b32_e32 v6, 16, v7
	v_and_b32_e32 v7, 0xffff0000, v7
	v_pk_fma_f32 v[58:59], v[58:59], v[94:95], v[4:5]
	v_pk_fma_f32 v[56:57], v[56:57], v[86:87], v[78:79]
	v_pk_fma_f32 v[54:55], v[54:55], v[84:85], v[6:7]
	v_cvt_pk_bf16_f32 v4, v56, v57
	v_cvt_pk_bf16_f32 v5, v58, v59
	v_pk_fma_f32 v[52:53], v[52:53], v[82:83], v[80:81]
	v_mov_b32_e32 v107, v137
	v_cvt_pk_bf16_f32 v6, v52, v53
	v_cvt_pk_bf16_f32 v7, v54, v55
	global_store_dwordx4 v[74:75], v[4:7], off nt
	v_lshl_add_u64 v[76:77], s[16:17], 0, v[106:107]
	s_nop 0
	v_mul_f32_e32 v4, v57, v57
	v_mul_f32_e32 v5, v59, v59
	v_fmac_f32_e32 v4, v56, v56
	v_fmac_f32_e32 v5, v58, v58
	v_add_f32_e32 v4, v4, v5
	v_mul_f32_e32 v5, v53, v53
	v_mul_f32_e32 v6, v55, v55
	v_fmac_f32_e32 v5, v52, v52
	v_fmac_f32_e32 v6, v54, v54
	v_add_f32_e32 v5, v5, v6
	v_add_f32_e32 v25, v4, v5
	v_pk_mul_f32 v[6:7], v[102:103], v[58:59]
	v_pk_mul_f32 v[4:5], v[104:105], v[56:57]
	v_pk_mul_f32 v[52:53], v[100:101], v[52:53]
	v_cvt_pk_bf16_f32 v4, v4, v5
	v_cvt_pk_bf16_f32 v5, v6, v7
	v_pk_mul_f32 v[54:55], v[98:99], v[54:55]
	v_cvt_pk_bf16_f32 v6, v52, v53
	v_lshl_add_u64 v[52:53], s[86:87], 0, v[136:137]
	v_cvt_pk_bf16_f32 v7, v54, v55
	global_store_dwordx4 v[52:53], v[4:7], off
	s_waitcnt vmcnt(6)
	s_nop 0
	v_lshlrev_b32_e32 v4, 16, v0
	v_and_b32_e32 v5, 0xffff0000, v0
	v_lshlrev_b32_e32 v0, 16, v1
	v_and_b32_e32 v1, 0xffff0000, v1
	v_lshlrev_b32_e32 v6, 16, v2
	v_and_b32_e32 v7, 0xffff0000, v2
	v_lshlrev_b32_e32 v2, 16, v3
	v_and_b32_e32 v3, 0xffff0000, v3
	v_pk_fma_f32 v[50:51], v[50:51], v[68:69], v[0:1]
	v_pk_fma_f32 v[4:5], v[48:49], v[66:67], v[4:5]
	v_pk_fma_f32 v[46:47], v[46:47], v[60:61], v[2:3]
	v_cvt_pk_bf16_f32 v0, v4, v5
	v_cvt_pk_bf16_f32 v1, v50, v51
	v_pk_fma_f32 v[6:7], v[44:45], v[26:27], v[6:7]
	v_pk_mul_f32 v[44:45], v[62:63], v[46:47]
	v_cvt_pk_bf16_f32 v2, v6, v7
	v_cvt_pk_bf16_f32 v3, v46, v47
	global_store_dwordx4 v[76:77], v[0:3], off nt
	s_nop 1
	v_mul_f32_e32 v0, v5, v5
	v_mul_f32_e32 v1, v51, v51
	v_fmac_f32_e32 v0, v4, v4
	v_fmac_f32_e32 v1, v50, v50
	v_add_f32_e32 v0, v0, v1
	v_mul_f32_e32 v1, v7, v7
	v_mul_f32_e32 v2, v47, v47
	v_fmac_f32_e32 v1, v6, v6
	v_fmac_f32_e32 v2, v46, v46
	v_add_f32_e32 v1, v1, v2
	v_add_f32_e32 v0, v0, v1
	v_add_f32_e32 v25, v25, v0
	ds_bpermute_b32 v48, v168, v25
	v_pk_mul_f32 v[0:1], v[70:71], v[50:51]
	v_pk_mul_f32 v[2:3], v[72:73], v[4:5]
	v_pk_mul_f32 v[4:5], v[64:65], v[6:7]
	v_cvt_pk_bf16_f32 v2, v2, v3
	v_cvt_pk_bf16_f32 v3, v0, v1
	s_waitcnt lgkmcnt(0)
	v_add_f32_e32 v0, v25, v48
	ds_bpermute_b32 v1, v169, v0
	v_lshl_add_u64 v[6:7], s[86:87], 0, v[106:107]
	v_cvt_pk_bf16_f32 v4, v4, v5
	v_cvt_pk_bf16_f32 v5, v44, v45
	global_store_dwordx4 v[6:7], v[2:5], off
	s_and_saveexec_b64 s[24:25], s[0:1]
	s_cbranch_execz .LBB0_1065
	v_add_u32_e32 v136, 0x90, v24
	v_lshl_add_u64 v[2:3], v[136:137], 2, s[14:15]
	s_waitcnt lgkmcnt(0)
	v_add_f32_e32 v0, v0, v1
	global_atomic_add_f32 v[2:3], v0, off
;     __device__ __forceinline__ void operator()(const f32x4 (&acc)[2][2][4][2], const Unit& u, int wr, int wc, int fr, int fq) const {
;     ...
;         for (int rg = 0; rg < 8 / RGB; ++rg) {
;             u32x4 braw[INPLACE ? RGB : 1][2]; f32x4 bb[INPLACE ? 1 : RGB][2][2];
; #pragma unroll
;             for (int mm = 0; mm < RGB; ++mm) { const int q = rg * RGB + mm, ai = q >> 2, m = q & 3;
; #pragma unroll
;                 for (int bj = 0; bj < 2; ++bj) { const unsigned e = e0 + (unsigned)((ai * 128 + m * 16) * D + bj * 128);
;                     if constexpr (INPLACE) braw[mm][bj] = *(const u32x4*)(Hc + (size_t)(e * 2u));
;                     else { bb[mm][bj][0] = *(const f32x4*)(bsc + (size_t)(e * 4u)); bb[mm][bj][1] = *(const f32x4*)(bsc + (size_t)(e * 4u + 16u)); } } }
; #pragma unroll
;             for (int mm = 0; mm < RGB; ++mm) { const int q = rg * RGB + mm, ai = q >> 2, m = q & 3; float ssum = 0.f;
; #pragma unroll
;                 for (int bj = 0; bj < 2; ++bj) { const unsigned e = e0 + (unsigned)((ai * 128 + m * 16) * D + bj * 128);
;                     f32x4 r0, r1;
;                     if constexpr (INPLACE) { const u32x4 q4 = braw[mm][bj];
;                         r0 = (f32x4){__uint_as_float(q4[0] << 16), __uint_as_float(q4[0] & 0xffff0000u), __uint_as_float(q4[1] << 16), __uint_as_float(q4[1] & 0xffff0000u)};
;                         r1 = (f32x4){__uint_as_float(q4[2] << 16), __uint_as_float(q4[2] & 0xffff0000u), __uint_as_float(q4[3] << 16), __uint_as_float(q4[3] & 0xffff0000u)}; }
;                     else { r0 = bb[mm][bj][0]; r1 = bb[mm][bj][1]; }
;                     const f32x4 h0 = r0 + gv[bj][0] * (acc[ai][bj][m][0] + bv[bj][0]), h1 = r1 + gv[bj][1] * (acc[ai][bj][m][1] + bv[bj][1]);
;                     { u32x4 w; w.x = cvt_pk_bf16(h0[0], h0[1]); w.y = cvt_pk_bf16(h0[2], h0[3]); w.z = cvt_pk_bf16(h1[0], h1[1]); w.w = cvt_pk_bf16(h1[2], h1[3]); ST16(1, Hc + (size_t)(e * 2u), w); }
;                     if (FUSE) { ssum += ((h0[0] * h0[0] + h0[1] * h0[1]) + (h0[2] * h0[2] + h0[3] * h0[3])) + ((h1[0] * h1[0] + h1[1] * h1[1]) + (h1[2] * h1[2] + h1[3] * h1[3]));
;                         const f32x4 z0 = h0 * wv[bj][0], z1 = h1 * wv[bj][1];
;                         u32x4 w; w.x = cvt_pk_bf16(z0[0], z0[1]); w.y = cvt_pk_bf16(z0[2], z0[3]); w.z = cvt_pk_bf16(z1[0], z1[1]); w.w = cvt_pk_bf16(z1[2], z1[3]);
.LBB0_1065:
	s_or_b64 exec, exec, s[24:25]
	v_add_u32_e32 v25, 0x50000, v196
	v_add_u32_e32 v45, 0x50100, v196
	global_load_dwordx4 v[46:49], v25, s[16:17]
	global_load_dwordx4 v[50:53], v45, s[16:17]
	v_add_u32_e32 v136, 0x58000, v196
	v_add_u32_e32 v44, 0x58100, v196
	global_load_dwordx4 v[4:7], v136, s[16:17]
	s_waitcnt lgkmcnt(0)
	global_load_dwordx4 v[0:3], v44, s[16:17]
	s_waitcnt vmcnt(3)
	v_lshlrev_b32_e32 v54, 16, v46
	v_and_b32_e32 v55, 0xffff0000, v46
	v_lshlrev_b32_e32 v46, 16, v47
	v_and_b32_e32 v47, 0xffff0000, v47
	v_lshlrev_b32_e32 v56, 16, v48
	v_and_b32_e32 v57, 0xffff0000, v48
	v_lshlrev_b32_e32 v48, 16, v49
	v_and_b32_e32 v49, 0xffff0000, v49
	s_waitcnt vmcnt(2)
	v_lshlrev_b32_e32 v58, 16, v50
	v_and_b32_e32 v59, 0xffff0000, v50
	v_lshlrev_b32_e32 v50, 16, v51
	v_and_b32_e32 v51, 0xffff0000, v51
	v_lshlrev_b32_e32 v74, 16, v52
	v_and_b32_e32 v75, 0xffff0000, v52
	v_lshlrev_b32_e32 v52, 16, v53
	v_and_b32_e32 v53, 0xffff0000, v53
	v_pk_fma_f32 v[46:47], v[28:29], v[94:95], v[46:47]
	v_pk_fma_f32 v[54:55], v[30:31], v[86:87], v[54:55]
	v_pk_fma_f32 v[34:35], v[34:35], v[84:85], v[48:49]
	v_pk_fma_f32 v[32:33], v[32:33], v[82:83], v[56:57]
	v_pk_fma_f32 v[42:43], v[42:43], v[68:69], v[50:51]
	v_pk_fma_f32 v[40:41], v[40:41], v[66:67], v[58:59]
	v_pk_fma_f32 v[38:39], v[38:39], v[60:61], v[52:53]
	v_pk_fma_f32 v[36:37], v[36:37], v[26:27], v[74:75]
	v_cvt_pk_bf16_f32 v28, v54, v55
	v_cvt_pk_bf16_f32 v29, v46, v47
	v_cvt_pk_bf16_f32 v30, v32, v33
	v_cvt_pk_bf16_f32 v31, v34, v35
	v_mul_f32_e32 v58, v55, v55
	v_mul_f32_e32 v59, v47, v47
	v_mul_f32_e32 v74, v33, v33
	v_mul_f32_e32 v75, v35, v35
	v_pk_mul_f32 v[48:49], v[102:103], v[46:47]
	v_pk_mul_f32 v[50:51], v[104:105], v[54:55]
	v_pk_mul_f32 v[52:53], v[98:99], v[34:35]
	v_pk_mul_f32 v[56:57], v[100:101], v[32:33]
	v_mul_f32_e32 v33, v41, v41
	v_mul_f32_e32 v35, v43, v43
	v_mul_f32_e32 v47, v37, v37
	v_mul_f32_e32 v55, v39, v39
	v_fmac_f32_e32 v58, v54, v54
	v_fmac_f32_e32 v59, v46, v46
	v_fmac_f32_e32 v74, v32, v32
	v_fmac_f32_e32 v75, v34, v34
	v_fmac_f32_e32 v33, v40, v40
	v_fmac_f32_e32 v35, v42, v42
	v_fmac_f32_e32 v47, v36, v36
	v_fmac_f32_e32 v55, v38, v38
	global_store_dwordx4 v25, v[28:31], s[16:17] nt
	v_add_f32_e32 v32, v58, v59
	v_add_f32_e32 v34, v74, v75
	v_cvt_pk_bf16_f32 v28, v50, v51
	v_cvt_pk_bf16_f32 v29, v48, v49
	v_cvt_pk_bf16_f32 v30, v56, v57
	v_cvt_pk_bf16_f32 v31, v52, v53
	global_store_dwordx4 v25, v[28:31], s[86:87]
	v_add_f32_e32 v25, v33, v35
	v_add_f32_e32 v33, v47, v55
	v_add_f32_e32 v32, v32, v34
	v_add_f32_e32 v25, v25, v33
	v_cvt_pk_bf16_f32 v28, v40, v41
	v_cvt_pk_bf16_f32 v29, v42, v43
	v_cvt_pk_bf16_f32 v30, v36, v37
	v_cvt_pk_bf16_f32 v31, v38, v39
	v_add_f32_e32 v25, v32, v25
	global_store_dwordx4 v45, v[28:31], s[16:17] nt
	ds_bpermute_b32 v31, v168, v25
	v_pk_mul_f32 v[32:33], v[70:71], v[42:43]
	v_pk_mul_f32 v[28:29], v[72:73], v[40:41]
	v_pk_mul_f32 v[34:35], v[62:63], v[38:39]
	v_cvt_pk_bf16_f32 v30, v28, v29
	s_waitcnt lgkmcnt(0)
	v_add_f32_e32 v25, v25, v31
	ds_bpermute_b32 v28, v169, v25
	v_pk_mul_f32 v[36:37], v[64:65], v[36:37]
	v_cvt_pk_bf16_f32 v31, v32, v33
	s_nop 0
	v_cvt_pk_bf16_f32 v32, v36, v37
	v_cvt_pk_bf16_f32 v33, v34, v35
	global_store_dwordx4 v45, v[30:33], s[86:87]
	s_and_saveexec_b64 s[24:25], s[0:1]
	s_cbranch_execz .LBB0_1067
	v_add_u32_e32 v30, 0xa0, v24
	v_mov_b32_e32 v31, v137
	v_lshl_add_u64 v[30:31], v[30:31], 2, s[14:15]
	s_waitcnt lgkmcnt(0)
	v_add_f32_e32 v25, v25, v28
	global_atomic_add_f32 v[30:31], v25, off
.LBB0_1067:
	s_or_b64 exec, exec, s[24:25]
	s_waitcnt vmcnt(5)
	v_lshlrev_b32_e32 v32, 16, v4
	v_and_b32_e32 v33, 0xffff0000, v4
	v_lshlrev_b32_e32 v4, 16, v5
	v_and_b32_e32 v5, 0xffff0000, v5
	s_waitcnt lgkmcnt(0)
	v_lshl_add_u64 v[28:29], s[16:17], 0, v[136:137]
	v_lshlrev_b32_e32 v34, 16, v6
	v_and_b32_e32 v35, 0xffff0000, v6
	v_lshlrev_b32_e32 v6, 16, v7
	v_and_b32_e32 v7, 0xffff0000, v7
	v_pk_fma_f32 v[22:23], v[22:23], v[94:95], v[4:5]
	v_pk_fma_f32 v[20:21], v[20:21], v[86:87], v[32:33]
	v_pk_fma_f32 v[18:19], v[18:19], v[84:85], v[6:7]
	v_cvt_pk_bf16_f32 v4, v20, v21
	v_cvt_pk_bf16_f32 v5, v22, v23
	v_pk_fma_f32 v[16:17], v[16:17], v[82:83], v[34:35]
	v_mov_b32_e32 v45, v137
	v_cvt_pk_bf16_f32 v6, v16, v17
	v_cvt_pk_bf16_f32 v7, v18, v19
	global_store_dwordx4 v[28:29], v[4:7], off nt
	v_lshl_add_u64 v[30:31], s[16:17], 0, v[44:45]
	s_nop 0
	v_mul_f32_e32 v4, v21, v21
	v_mul_f32_e32 v5, v23, v23
	v_fmac_f32_e32 v4, v20, v20
	v_fmac_f32_e32 v5, v22, v22
	v_add_f32_e32 v4, v4, v5
	v_mul_f32_e32 v5, v17, v17
	v_mul_f32_e32 v6, v19, v19
	v_fmac_f32_e32 v5, v16, v16
	v_fmac_f32_e32 v6, v18, v18
	v_add_f32_e32 v5, v5, v6
	v_add_f32_e32 v25, v4, v5
	v_pk_mul_f32 v[6:7], v[102:103], v[22:23]
	v_pk_mul_f32 v[4:5], v[104:105], v[20:21]
	v_pk_mul_f32 v[16:17], v[100:101], v[16:17]
	v_cvt_pk_bf16_f32 v4, v4, v5
	v_cvt_pk_bf16_f32 v5, v6, v7
	v_pk_mul_f32 v[18:19], v[98:99], v[18:19]
	v_cvt_pk_bf16_f32 v6, v16, v17
	v_lshl_add_u64 v[16:17], s[86:87], 0, v[136:137]
	v_cvt_pk_bf16_f32 v7, v18, v19
	global_store_dwordx4 v[16:17], v[4:7], off
	s_waitcnt vmcnt(6)
	s_nop 0
	v_lshlrev_b32_e32 v4, 16, v0
	v_and_b32_e32 v5, 0xffff0000, v0
	v_lshlrev_b32_e32 v0, 16, v1
	v_and_b32_e32 v1, 0xffff0000, v1
	v_lshlrev_b32_e32 v6, 16, v2
	v_and_b32_e32 v7, 0xffff0000, v2
	v_lshlrev_b32_e32 v2, 16, v3
	v_and_b32_e32 v3, 0xffff0000, v3
	v_pk_fma_f32 v[14:15], v[14:15], v[68:69], v[0:1]
	v_pk_fma_f32 v[4:5], v[12:13], v[66:67], v[4:5]
	v_pk_fma_f32 v[10:11], v[10:11], v[60:61], v[2:3]
	v_cvt_pk_bf16_f32 v0, v4, v5
	v_cvt_pk_bf16_f32 v1, v14, v15
	v_pk_fma_f32 v[6:7], v[8:9], v[26:27], v[6:7]
	v_pk_mul_f32 v[8:9], v[62:63], v[10:11]
	v_cvt_pk_bf16_f32 v2, v6, v7
	v_cvt_pk_bf16_f32 v3, v10, v11
	global_store_dwordx4 v[30:31], v[0:3], off nt
	s_nop 1
	v_mul_f32_e32 v0, v5, v5
	v_mul_f32_e32 v1, v15, v15
	v_fmac_f32_e32 v0, v4, v4
	v_fmac_f32_e32 v1, v14, v14
	v_add_f32_e32 v0, v0, v1
	v_mul_f32_e32 v1, v7, v7
	v_mul_f32_e32 v2, v11, v11
	v_fmac_f32_e32 v1, v6, v6
	v_fmac_f32_e32 v2, v10, v10
	v_add_f32_e32 v1, v1, v2
	v_add_f32_e32 v0, v0, v1
	v_add_f32_e32 v12, v25, v0
	ds_bpermute_b32 v13, v168, v12
	v_pk_mul_f32 v[0:1], v[70:71], v[14:15]
	v_pk_mul_f32 v[2:3], v[72:73], v[4:5]
	v_pk_mul_f32 v[4:5], v[64:65], v[6:7]
	v_cvt_pk_bf16_f32 v2, v2, v3
	v_cvt_pk_bf16_f32 v3, v0, v1
	s_waitcnt lgkmcnt(0)
	v_add_f32_e32 v0, v12, v13
	ds_bpermute_b32 v1, v169, v0
	v_lshl_add_u64 v[6:7], s[86:87], 0, v[44:45]
	v_cvt_pk_bf16_f32 v4, v4, v5
	v_cvt_pk_bf16_f32 v5, v8, v9
	global_store_dwordx4 v[6:7], v[2:5], off
	s_and_saveexec_b64 s[24:25], s[0:1]
	s_cbranch_execz .LBB0_1069
	v_add_u32_e32 v136, 0xb0, v24
	v_lshl_add_u64 v[2:3], v[136:137], 2, s[14:15]
	s_waitcnt lgkmcnt(0)
	v_add_f32_e32 v0, v0, v1
	global_atomic_add_f32 v[2:3], v0, off

;     __device__ __forceinline__ void operator()(const f32x4 (&acc)[2][2][4][2], const Unit& u, int wr, int wc, int fr, int fq) const {
;         const int row0 = u.pm * 256 + wr * 64 + fr, col0 = u.pn * 256 + wc * 32 + 8 * fq;
;         const int mb = u.pm < 64 ? (u.pm >> 4) : 4;
;         float* SSn = (float*)(ws + WS_SS) + ss_off;
;         const float* gate = (const float*)(ws + WS_MOD) + gate_off + (size_t)mb * 9216; const float* gn = (const float*)(ws + WS_NG) + gn_off; const float* scn = (const float*)(ws + WS_MOD) + scn_off + (size_t)mb * 9216;
;         f32x4 gv[2][2], bv[2][2], wv[2][2];
; #pragma unroll
;         for (int bj = 0; bj < 2; ++bj)
; #pragma unroll
;             for (int n = 0; n < 2; ++n) { const int cc = col0 + bj * 128 + 4 * n;
;                 gv[bj][n] = *(const f32x4*)(gate + cc) * gmul;
;                 bv[bj][n] = HASBIAS ? *(const f32x4*)(bias + cc) : (f32x4){0.f, 0.f, 0.f, 0.f};
;                 wv[bj][n] = FUSE ? *(const f32x4*)(gn + cc) * (*(const f32x4*)(scn + cc) + 1.0f) : (f32x4){0.f, 0.f, 0.f, 0.f}; }
;         const unsigned e0 = (unsigned)(row0 * D + col0);
;         const char* bsc = (const char*)base0; char* Hc = (char*)(ws + WS_H); char* HBc = (char*)(ws + WS_XN);
;         constexpr int RGB = 2;
; #pragma unroll
;         for (int rg = 0; rg < 8 / RGB; ++rg) {
;             u32x4 braw[INPLACE ? RGB : 1][2]; f32x4 bb[INPLACE ? 1 : RGB][2][2];
; #pragma unroll
;             for (int mm = 0; mm < RGB; ++mm) { const int q = rg * RGB + mm, ai = q >> 2, m = q & 3;
; #pragma unroll
;                 for (int bj = 0; bj < 2; ++bj) { const unsigned e = e0 + (unsigned)((ai * 128 + m * 16) * D + bj * 128);
;                     if constexpr (INPLACE) braw[mm][bj] = *(const u32x4*)(Hc + (size_t)(e * 2u));
;                     else { bb[mm][bj][0] = *(const f32x4*)(bsc + (size_t)(e * 4u)); bb[mm][bj][1] = *(const f32x4*)(bsc + (size_t)(e * 4u + 16u)); } } }
; #pragma unroll
;             for (int mm = 0; mm < RGB; ++mm) { const int q = rg * RGB + mm, ai = q >> 2, m = q & 3; float ssum = 0.f;
; #pragma unroll
;                 for (int bj = 0; bj < 2; ++bj) { const unsigned e = e0 + (unsigned)((ai * 128 + m * 16) * D + bj * 128);
;                     f32x4 r0, r1;
;                     if constexpr (INPLACE) { const u32x4 q4 = braw[mm][bj];
.LBB0_1474:
	s_ashr_i32 s21, s26, 4
	v_lshl_or_b32 v80, s55, 8, v198
	s_mul_hi_i32 s28, s21, 0x9000
	s_mul_i32 s21, s21, 0x9000
	v_ashrrev_i32_e32 v81, 31, v80
	v_lshl_add_u32 v184, s26, 8, v196
	s_add_u32 s26, s49, s21
	v_lshlrev_b64 v[82:83], 2, v[80:81]
	v_lshlrev_b32_e32 v81, 11, v184
	s_addc_u32 s27, s50, s28
	v_lshl_add_u64 v[84:85], s[70:71], 0, v[82:83]
	v_lshl_add_u32 v202, v80, 1, v81
	v_lshl_add_u64 v[160:161], s[26:27], 0, v[82:83]
	s_add_u32 s26, s51, s21
	global_load_dwordx4 v[92:95], v[84:85], off offset:16
	global_load_dwordx4 v[100:103], v[84:85], off
	global_load_dwordx4 v[186:189], v202, s[16:17]
	global_load_dwordx4 v[116:119], v[160:161], off
	s_addc_u32 s27, s52, s28
	global_load_dwordx4 v[108:111], v[160:161], off offset:16
	v_lshl_add_u64 v[86:87], s[26:27], 0, v[82:83]
	v_lshl_add_u64 v[82:83], s[12:13], 0, v[82:83]
	global_load_dwordx4 v[190:193], v[86:87], off
	global_load_dwordx4 v[204:207], v[86:87], off offset:16
	global_load_dwordx4 v[208:211], v[86:87], off offset:512
	global_load_dwordx4 v[212:215], v[86:87], off offset:528
	global_load_dwordx4 v[216:219], v[82:83], off offset:16
	global_load_dwordx4 v[220:223], v[82:83], off
	v_or_b32_e32 v80, 0x80, v80
	v_ashrrev_i32_e32 v81, 31, v80
	v_lshl_add_u64 v[80:81], v[80:81], 2, s[12:13]
	global_load_dwordx4 v[224:227], v[80:81], off
	global_load_dwordx4 v[228:231], v[80:81], off offset:16
	v_or_b32_e32 v185, 0x100, v202
	global_load_dwordx4 v[232:235], v185, s[16:17]
	global_load_dwordx4 v[96:99], v[84:85], off offset:512
	global_load_dwordx4 v[88:91], v[160:161], off offset:512
	s_nop 0
	global_load_dwordx4 v[84:87], v[84:85], off offset:528
	s_nop 0
	global_load_dwordx4 v[80:83], v[160:161], off offset:528
	v_add_u32_e32 v178, 0x8000, v202
	v_add_u32_e32 v194, 0x8100, v202
	global_load_dwordx4 v[164:167], v178, s[16:17]
	global_load_dwordx4 v[160:163], v194, s[16:17]
	s_waitcnt vmcnt(0)
	v_pk_add_f32 v[154:155], v[154:155], v[94:95]
	v_pk_add_f32 v[152:153], v[152:153], v[92:93]
	v_lshlrev_b32_e32 v238, 16, v188
	v_and_b32_e32 v239, 0xffff0000, v188
	v_lshlrev_b32_e32 v188, 16, v189
	v_and_b32_e32 v189, 0xffff0000, v189
	v_pk_add_f32 v[158:159], v[158:159], v[102:103]
	v_pk_add_f32 v[156:157], v[156:157], v[100:101]
	v_lshlrev_b32_e32 v236, 16, v186
	v_and_b32_e32 v237, 0xffff0000, v186
	v_lshlrev_b32_e32 v186, 16, v187
	v_and_b32_e32 v187, 0xffff0000, v187
	v_pk_fma_f32 v[242:243], v[110:111], v[154:155], v[188:189]
	v_pk_fma_f32 v[238:239], v[108:109], v[152:153], v[238:239]
	v_pk_add_f32 v[152:153], v[192:193], 1.0 op_sel_hi:[1,0]
	v_pk_add_f32 v[154:155], v[190:191], 1.0 op_sel_hi:[1,0]
	v_pk_fma_f32 v[240:241], v[118:119], v[158:159], v[186:187]
	v_pk_fma_f32 v[236:237], v[116:117], v[156:157], v[236:237]
	v_pk_add_f32 v[156:157], v[206:207], 1.0 op_sel_hi:[1,0]
	v_pk_add_f32 v[158:159], v[204:205], 1.0 op_sel_hi:[1,0]
	v_cvt_pk_bf16_f32 v204, v236, v237
	v_cvt_pk_bf16_f32 v205, v240, v241
	v_cvt_pk_bf16_f32 v206, v238, v239
	v_cvt_pk_bf16_f32 v207, v242, v243
	v_pk_mul_f32 v[190:191], v[222:223], v[152:153]
	v_pk_mul_f32 v[192:193], v[220:221], v[154:155]
	v_pk_add_f32 v[210:211], v[210:211], 1.0 op_sel_hi:[1,0]
	v_pk_add_f32 v[208:209], v[208:209], 1.0 op_sel_hi:[1,0]
	v_pk_mul_f32 v[186:187], v[218:219], v[156:157]
	v_pk_mul_f32 v[188:189], v[216:217], v[158:159]
	global_store_dwordx4 v202, v[204:207], s[16:17] nt
	v_pk_mul_f32 v[156:157], v[226:227], v[210:211]
	v_pk_mul_f32 v[158:159], v[224:225], v[208:209]
	v_pk_mul_f32 v[206:207], v[190:191], v[240:241]
	v_pk_mul_f32 v[204:205], v[192:193], v[236:237]
	v_pk_mul_f32 v[208:209], v[186:187], v[242:243]
	v_pk_mul_f32 v[210:211], v[188:189], v[238:239]
	v_cvt_pk_bf16_f32 v204, v204, v205
	v_cvt_pk_bf16_f32 v205, v206, v207
	v_pk_add_f32 v[150:151], v[150:151], v[98:99]
	v_cvt_pk_bf16_f32 v206, v210, v211
	v_cvt_pk_bf16_f32 v207, v208, v209
	global_store_dwordx4 v202, v[204:207], s[86:87]
	v_lshlrev_b32_e32 v208, 16, v234
	v_and_b32_e32 v209, 0xffff0000, v234
	v_lshlrev_b32_e32 v204, 16, v232
	v_and_b32_e32 v205, 0xffff0000, v232
	v_lshlrev_b32_e32 v206, 16, v233
	v_and_b32_e32 v207, 0xffff0000, v233
	v_pk_add_f32 v[148:149], v[148:149], v[96:97]
	v_pk_add_f32 v[144:145], v[144:145], v[84:85]
	v_lshlrev_b32_e32 v210, 16, v235
	v_and_b32_e32 v211, 0xffff0000, v235
	v_pk_fma_f32 v[150:151], v[90:91], v[150:151], v[206:207]
	v_pk_fma_f32 v[148:149], v[88:89], v[148:149], v[204:205]
	v_pk_add_f32 v[146:147], v[146:147], v[86:87]
	v_pk_fma_f32 v[206:207], v[80:81], v[144:145], v[208:209]
	v_cvt_pk_bf16_f32 v144, v148, v149
	v_cvt_pk_bf16_f32 v145, v150, v151
	v_pk_fma_f32 v[204:205], v[82:83], v[146:147], v[210:211]
	v_cvt_pk_bf16_f32 v146, v206, v207
	v_mul_f32_e32 v195, v237, v237
	v_cvt_pk_bf16_f32 v147, v204, v205
	global_store_dwordx4 v185, v[144:147], s[16:17] nt
	v_mul_f32_e32 v203, v241, v241
	v_mul_f32_e32 v244, v239, v239
	v_mul_f32_e32 v144, v149, v149
	v_mul_f32_e32 v145, v151, v151
	v_fmac_f32_e32 v144, v148, v148
	v_fmac_f32_e32 v145, v150, v150
	v_mul_f32_e32 v245, v243, v243
	v_add_f32_e32 v144, v144, v145
	v_mul_f32_e32 v145, v207, v207
	v_mul_f32_e32 v146, v205, v205
	v_fmac_f32_e32 v195, v236, v236
	v_fmac_f32_e32 v203, v240, v240
	v_fmac_f32_e32 v244, v238, v238
	v_fmac_f32_e32 v245, v242, v242
	v_fmac_f32_e32 v145, v206, v206
	v_fmac_f32_e32 v146, v204, v204
	v_add_f32_e32 v195, v195, v203
	v_add_f32_e32 v203, v244, v245
	v_add_f32_e32 v145, v145, v146
	v_add_f32_e32 v195, v195, v203
	v_add_f32_e32 v144, v144, v145
	v_and_b32_e32 v146, 64, v177
	v_add_f32_e32 v145, v195, v144
	v_xor_b32_e32 v144, 16, v177
	v_add_u32_e32 v195, 64, v146
	v_cmp_lt_i32_e32 vcc, v144, v195
	v_pk_mul_f32 v[146:147], v[158:159], v[148:149]
	v_pk_add_f32 v[214:215], v[214:215], 1.0 op_sel_hi:[1,0]
	v_cndmask_b32_e32 v144, v177, v144, vcc
	v_lshlrev_b32_e32 v144, 2, v144
	ds_bpermute_b32 v203, v144, v145
	v_cvt_pk_bf16_f32 v148, v146, v147
	v_pk_add_f32 v[212:213], v[212:213], 1.0 op_sel_hi:[1,0]
	v_pk_mul_f32 v[152:153], v[230:231], v[214:215]
	v_pk_mul_f32 v[154:155], v[228:229], v[212:213]
	s_waitcnt lgkmcnt(0)
	v_add_f32_e32 v146, v145, v203
	v_xor_b32_e32 v145, 32, v177
	v_cmp_lt_i32_e32 vcc, v145, v195
	v_pk_mul_f32 v[150:151], v[156:157], v[150:151]
	v_pk_mul_f32 v[204:205], v[152:153], v[204:205]
	v_cndmask_b32_e32 v145, v177, v145, vcc
	v_lshlrev_b32_e32 v145, 2, v145
	ds_bpermute_b32 v147, v145, v146
	v_pk_mul_f32 v[206:207], v[154:155], v[206:207]
	v_cvt_pk_bf16_f32 v149, v150, v151
	s_nop 0
	v_cvt_pk_bf16_f32 v150, v206, v207
	v_cvt_pk_bf16_f32 v151, v204, v205
	global_store_dwordx4 v185, v[148:151], s[86:87]
	s_and_saveexec_b64 s[26:27], s[0:1]
	s_cbranch_execz .LBB0_1476
	v_mov_b32_e32 v185, v179
	v_lshl_add_u64 v[148:149], v[184:185], 2, s[14:15]
	s_waitcnt lgkmcnt(0)
	v_add_f32_e32 v146, v146, v147
	global_atomic_add_f32 v[148:149], v146, off
;     __device__ __forceinline__ void operator()(const f32x4 (&acc)[2][2][4][2], const Unit& u, int wr, int wc, int fr, int fq) const {
;     ...
;         for (int rg = 0; rg < 8 / RGB; ++rg) {
;             u32x4 braw[INPLACE ? RGB : 1][2]; f32x4 bb[INPLACE ? 1 : RGB][2][2];
; #pragma unroll
;             for (int mm = 0; mm < RGB; ++mm) { const int q = rg * RGB + mm, ai = q >> 2, m = q & 3;
; #pragma unroll
;                 for (int bj = 0; bj < 2; ++bj) { const unsigned e = e0 + (unsigned)((ai * 128 + m * 16) * D + bj * 128);
;                     if constexpr (INPLACE) braw[mm][bj] = *(const u32x4*)(Hc + (size_t)(e * 2u));
;                     else { bb[mm][bj][0] = *(const f32x4*)(bsc + (size_t)(e * 4u)); bb[mm][bj][1] = *(const f32x4*)(bsc + (size_t)(e * 4u + 16u)); } } }
; #pragma unroll
;             for (int mm = 0; mm < RGB; ++mm) { const int q = rg * RGB + mm, ai = q >> 2, m = q & 3; float ssum = 0.f;
; #pragma unroll
;                 for (int bj = 0; bj < 2; ++bj) { const unsigned e = e0 + (unsigned)((ai * 128 + m * 16) * D + bj * 128);
;                     f32x4 r0, r1;
;                     if constexpr (INPLACE) { const u32x4 q4 = braw[mm][bj];
;                         r0 = (f32x4){__uint_as_float(q4[0] << 16), __uint_as_float(q4[0] & 0xffff0000u), __uint_as_float(q4[1] << 16), __uint_as_float(q4[1] & 0xffff0000u)};
;                         r1 = (f32x4){__uint_as_float(q4[2] << 16), __uint_as_float(q4[2] & 0xffff0000u), __uint_as_float(q4[3] << 16), __uint_as_float(q4[3] & 0xffff0000u)}; }
;                     else { r0 = bb[mm][bj][0]; r1 = bb[mm][bj][1]; }
;                     const f32x4 h0 = r0 + gv[bj][0] * (acc[ai][bj][m][0] + bv[bj][0]), h1 = r1 + gv[bj][1] * (acc[ai][bj][m][1] + bv[bj][1]);
;                     { u32x4 w; w.x = cvt_pk_bf16(h0[0], h0[1]); w.y = cvt_pk_bf16(h0[2], h0[3]); w.z = cvt_pk_bf16(h1[0], h1[1]); w.w = cvt_pk_bf16(h1[2], h1[3]); ST16(1, Hc + (size_t)(e * 2u), w); }
;                     if (FUSE) { ssum += ((h0[0] * h0[0] + h0[1] * h0[1]) + (h0[2] * h0[2] + h0[3] * h0[3])) + ((h1[0] * h1[0] + h1[1] * h1[1]) + (h1[2] * h1[2] + h1[3] * h1[3]));
;                         const f32x4 z0 = h0 * wv[bj][0], z1 = h1 * wv[bj][1];
;                         u32x4 w; w.x = cvt_pk_bf16(z0[0], z0[1]); w.y = cvt_pk_bf16(z0[2], z0[3]); w.z = cvt_pk_bf16(z1[0], z1[1]); w.w = cvt_pk_bf16(z1[2], z1[3]);
.LBB0_1476:
	s_or_b64 exec, exec, s[26:27]
	v_lshlrev_b32_e32 v150, 16, v164
	v_and_b32_e32 v151, 0xffff0000, v164
	v_lshlrev_b32_e32 v164, 16, v165
	v_and_b32_e32 v165, 0xffff0000, v165
	v_lshlrev_b32_e32 v204, 16, v166
	v_and_b32_e32 v205, 0xffff0000, v166
	v_pk_add_f32 v[142:143], v[142:143], v[102:103]
	v_pk_add_f32 v[140:141], v[140:141], v[100:101]
	v_pk_add_f32 v[136:137], v[136:137], v[92:93]
	s_waitcnt lgkmcnt(0)
	v_lshl_add_u64 v[146:147], s[16:17], 0, v[178:179]
	v_lshlrev_b32_e32 v166, 16, v167
	v_and_b32_e32 v167, 0xffff0000, v167
	v_pk_fma_f32 v[142:143], v[118:119], v[142:143], v[164:165]
	v_pk_fma_f32 v[140:141], v[116:117], v[140:141], v[150:151]
	v_pk_add_f32 v[138:139], v[138:139], v[94:95]
	v_pk_fma_f32 v[164:165], v[108:109], v[136:137], v[204:205]
	v_cvt_pk_bf16_f32 v136, v140, v141
	v_cvt_pk_bf16_f32 v137, v142, v143
	v_pk_fma_f32 v[150:151], v[110:111], v[138:139], v[166:167]
	v_cvt_pk_bf16_f32 v138, v164, v165
	v_mov_b32_e32 v195, v179
	v_cvt_pk_bf16_f32 v139, v150, v151
	global_store_dwordx4 v[146:147], v[136:139], off nt
	v_pk_add_f32 v[134:135], v[134:135], v[98:99]
	v_pk_add_f32 v[132:133], v[132:133], v[96:97]
	v_mul_f32_e32 v136, v141, v141
	v_mul_f32_e32 v137, v143, v143
	v_fmac_f32_e32 v136, v140, v140
	v_fmac_f32_e32 v137, v142, v142
	v_add_f32_e32 v136, v136, v137
	v_mul_f32_e32 v137, v165, v165
	v_mul_f32_e32 v138, v151, v151
	v_fmac_f32_e32 v137, v164, v164
	v_fmac_f32_e32 v138, v150, v150
	v_add_f32_e32 v137, v137, v138
	v_add_f32_e32 v146, v136, v137
	v_pk_mul_f32 v[138:139], v[190:191], v[142:143]
	v_pk_mul_f32 v[136:137], v[192:193], v[140:141]
	v_pk_mul_f32 v[140:141], v[186:187], v[150:151]
	v_pk_mul_f32 v[142:143], v[188:189], v[164:165]
	v_cvt_pk_bf16_f32 v136, v136, v137
	v_cvt_pk_bf16_f32 v137, v138, v139
	v_pk_add_f32 v[128:129], v[128:129], v[84:85]
	v_cvt_pk_bf16_f32 v138, v142, v143
	v_cvt_pk_bf16_f32 v139, v140, v141
	v_lshl_add_u64 v[140:141], s[86:87], 0, v[178:179]
	global_store_dwordx4 v[140:141], v[136:139], off
	v_lshlrev_b32_e32 v140, 16, v162
	v_and_b32_e32 v141, 0xffff0000, v162
	v_lshlrev_b32_e32 v136, 16, v160
	v_and_b32_e32 v137, 0xffff0000, v160
	v_lshlrev_b32_e32 v138, 16, v161
	v_and_b32_e32 v139, 0xffff0000, v161
	v_lshl_add_u64 v[148:149], s[16:17], 0, v[194:195]
	v_lshlrev_b32_e32 v142, 16, v163
	v_and_b32_e32 v143, 0xffff0000, v163
	v_pk_fma_f32 v[134:135], v[90:91], v[134:135], v[138:139]
	v_pk_fma_f32 v[132:133], v[88:89], v[132:133], v[136:137]
	v_pk_add_f32 v[130:131], v[130:131], v[86:87]
	v_pk_fma_f32 v[138:139], v[80:81], v[128:129], v[140:141]
	v_cvt_pk_bf16_f32 v128, v132, v133
	v_cvt_pk_bf16_f32 v129, v134, v135
	v_pk_fma_f32 v[136:137], v[82:83], v[130:131], v[142:143]
	v_cvt_pk_bf16_f32 v130, v138, v139
	s_nop 0
	v_cvt_pk_bf16_f32 v131, v136, v137
	global_store_dwordx4 v[148:149], v[128:131], off nt
	s_nop 1
	v_mul_f32_e32 v128, v133, v133
	v_mul_f32_e32 v129, v135, v135
	v_fmac_f32_e32 v128, v132, v132
	v_fmac_f32_e32 v129, v134, v134
	v_add_f32_e32 v128, v128, v129
	v_mul_f32_e32 v129, v139, v139
	v_mul_f32_e32 v130, v137, v137
	v_fmac_f32_e32 v129, v138, v138
	v_fmac_f32_e32 v130, v136, v136
	v_add_f32_e32 v129, v129, v130
	v_add_f32_e32 v128, v128, v129
	v_add_f32_e32 v140, v146, v128
	ds_bpermute_b32 v141, v144, v140
	v_pk_mul_f32 v[128:129], v[156:157], v[134:135]
	v_pk_mul_f32 v[130:131], v[158:159], v[132:133]
	v_pk_mul_f32 v[134:135], v[152:153], v[136:137]
	v_cvt_pk_bf16_f32 v130, v130, v131
	v_cvt_pk_bf16_f32 v131, v128, v129
	s_waitcnt lgkmcnt(0)
	v_add_f32_e32 v128, v140, v141
	ds_bpermute_b32 v129, v145, v128
	v_pk_mul_f32 v[132:133], v[154:155], v[138:139]
	s_nop 0
	v_cvt_pk_bf16_f32 v132, v132, v133
	v_cvt_pk_bf16_f32 v133, v134, v135
	v_lshl_add_u64 v[134:135], s[86:87], 0, v[194:195]
	global_store_dwordx4 v[134:135], v[130:133], off
	s_and_saveexec_b64 s[26:27], s[0:1]
	s_cbranch_execz .LBB0_1478
	v_or_b32_e32 v178, 16, v184
	v_lshl_add_u64 v[130:131], v[178:179], 2, s[14:15]
	s_waitcnt lgkmcnt(0)
	v_add_f32_e32 v128, v128, v129
	global_atomic_add_f32 v[130:131], v128, off
.LBB0_1478:
	s_or_b64 exec, exec, s[26:27]
	s_waitcnt lgkmcnt(0)
	v_add_u32_e32 v129, 0x10000, v202
	v_add_u32_e32 v164, 0x10100, v202
	global_load_dwordx4 v[130:133], v129, s[16:17]
	global_load_dwordx4 v[134:137], v164, s[16:17]
	v_add_u32_e32 v178, 0x18000, v202
	v_add_u32_e32 v128, 0x18100, v202
	v_pk_add_f32 v[138:139], v[122:123], v[94:95]
	v_pk_add_f32 v[140:141], v[120:121], v[92:93]
	v_pk_add_f32 v[142:143], v[114:115], v[98:99]
	v_pk_add_f32 v[146:147], v[112:113], v[96:97]
	global_load_dwordx4 v[120:123], v178, s[16:17]
	global_load_dwordx4 v[112:115], v128, s[16:17]
	v_pk_add_f32 v[126:127], v[126:127], v[102:103]
	v_pk_add_f32 v[124:125], v[124:125], v[100:101]
	v_pk_add_f32 v[106:107], v[106:107], v[86:87]
	v_pk_add_f32 v[104:105], v[104:105], v[84:85]
	s_waitcnt vmcnt(3)
	v_lshlrev_b32_e32 v148, 16, v130
	v_and_b32_e32 v149, 0xffff0000, v130
	v_lshlrev_b32_e32 v130, 16, v131
	v_and_b32_e32 v131, 0xffff0000, v131
	v_lshlrev_b32_e32 v150, 16, v132
	v_and_b32_e32 v151, 0xffff0000, v132
	v_lshlrev_b32_e32 v132, 16, v133
	v_and_b32_e32 v133, 0xffff0000, v133
	s_waitcnt vmcnt(2)
;     __device__ __forceinline__ void operator()(const f32x4 (&acc)[2][2][4][2], const Unit& u, int wr, int wc, int fr, int fq) const {
;     ...
;         for (int rg = 0; rg < 8 / RGB; ++rg) {
;             u32x4 braw[INPLACE ? RGB : 1][2]; f32x4 bb[INPLACE ? 1 : RGB][2][2];
; #pragma unroll
;             for (int mm = 0; mm < RGB; ++mm) { const int q = rg * RGB + mm, ai = q >> 2, m = q & 3;
; #pragma unroll
;                 for (int bj = 0; bj < 2; ++bj) { const unsigned e = e0 + (unsigned)((ai * 128 + m * 16) * D + bj * 128);
;                     if constexpr (INPLACE) braw[mm][bj] = *(const u32x4*)(Hc + (size_t)(e * 2u));
;                     else { bb[mm][bj][0] = *(const f32x4*)(bsc + (size_t)(e * 4u)); bb[mm][bj][1] = *(const f32x4*)(bsc + (size_t)(e * 4u + 16u)); } } }
; #pragma unroll
;             for (int mm = 0; mm < RGB; ++mm) { const int q = rg * RGB + mm, ai = q >> 2, m = q & 3; float ssum = 0.f;
; #pragma unroll
;                 for (int bj = 0; bj < 2; ++bj) { const unsigned e = e0 + (unsigned)((ai * 128 + m * 16) * D + bj * 128);
;                     f32x4 r0, r1;
;                     if constexpr (INPLACE) { const u32x4 q4 = braw[mm][bj];
;                         r0 = (f32x4){__uint_as_float(q4[0] << 16), __uint_as_float(q4[0] & 0xffff0000u), __uint_as_float(q4[1] << 16), __uint_as_float(q4[1] & 0xffff0000u)};
;                         r1 = (f32x4){__uint_as_float(q4[2] << 16), __uint_as_float(q4[2] & 0xffff0000u), __uint_as_float(q4[3] << 16), __uint_as_float(q4[3] & 0xffff0000u)}; }
;                     else { r0 = bb[mm][bj][0]; r1 = bb[mm][bj][1]; }
;                     const f32x4 h0 = r0 + gv[bj][0] * (acc[ai][bj][m][0] + bv[bj][0]), h1 = r1 + gv[bj][1] * (acc[ai][bj][m][1] + bv[bj][1]);
;                     { u32x4 w; w.x = cvt_pk_bf16(h0[0], h0[1]); w.y = cvt_pk_bf16(h0[2], h0[3]); w.z = cvt_pk_bf16(h1[0], h1[1]); w.w = cvt_pk_bf16(h1[2], h1[3]); ST16(1, Hc + (size_t)(e * 2u), w); }
;                     if (FUSE) { ssum += ((h0[0] * h0[0] + h0[1] * h0[1]) + (h0[2] * h0[2] + h0[3] * h0[3])) + ((h1[0] * h1[0] + h1[1] * h1[1]) + (h1[2] * h1[2] + h1[3] * h1[3]));
;                         const f32x4 z0 = h0 * wv[bj][0], z1 = h1 * wv[bj][1];
;                         u32x4 w; w.x = cvt_pk_bf16(z0[0], z0[1]); w.y = cvt_pk_bf16(z0[2], z0[3]); w.z = cvt_pk_bf16(z1[0], z1[1]); w.w = cvt_pk_bf16(z1[2], z1[3]);
	v_lshlrev_b32_e32 v160, 16, v134
	v_and_b32_e32 v161, 0xffff0000, v134
	v_lshlrev_b32_e32 v134, 16, v135
	v_and_b32_e32 v135, 0xffff0000, v135
	v_lshlrev_b32_e32 v162, 16, v136
	v_and_b32_e32 v163, 0xffff0000, v136
	v_lshlrev_b32_e32 v136, 16, v137
	v_and_b32_e32 v137, 0xffff0000, v137
	v_pk_fma_f32 v[126:127], v[118:119], v[126:127], v[130:131]
	v_pk_fma_f32 v[124:125], v[116:117], v[124:125], v[148:149]
	v_pk_fma_f32 v[130:131], v[110:111], v[138:139], v[132:133]
	v_pk_fma_f32 v[132:133], v[108:109], v[140:141], v[150:151]
	v_pk_fma_f32 v[134:135], v[90:91], v[142:143], v[134:135]
	v_pk_fma_f32 v[138:139], v[88:89], v[146:147], v[160:161]
	v_pk_fma_f32 v[136:137], v[82:83], v[106:107], v[136:137]
	v_pk_fma_f32 v[140:141], v[80:81], v[104:105], v[162:163]
	v_cvt_pk_bf16_f32 v104, v124, v125
	v_cvt_pk_bf16_f32 v105, v126, v127
	v_cvt_pk_bf16_f32 v106, v132, v133
	v_cvt_pk_bf16_f32 v107, v130, v131
	v_mul_f32_e32 v160, v125, v125
	v_mul_f32_e32 v161, v127, v127
	v_mul_f32_e32 v162, v133, v133
	v_mul_f32_e32 v163, v131, v131
	v_pk_mul_f32 v[142:143], v[190:191], v[126:127]
	v_pk_mul_f32 v[146:147], v[192:193], v[124:125]
	v_pk_mul_f32 v[148:149], v[186:187], v[130:131]
	v_pk_mul_f32 v[150:151], v[188:189], v[132:133]
	v_mul_f32_e32 v125, v139, v139
	v_mul_f32_e32 v127, v135, v135
	v_mul_f32_e32 v131, v141, v141
	v_mul_f32_e32 v133, v137, v137
	global_store_dwordx4 v129, v[104:107], s[16:17] nt
	v_fmac_f32_e32 v160, v124, v124
	v_fmac_f32_e32 v161, v126, v126
	v_fmac_f32_e32 v162, v132, v132
	v_fmac_f32_e32 v163, v130, v130
	v_cvt_pk_bf16_f32 v104, v146, v147
	v_fmac_f32_e32 v125, v138, v138
	v_fmac_f32_e32 v127, v134, v134
	v_fmac_f32_e32 v131, v140, v140
	v_fmac_f32_e32 v133, v136, v136
	v_cvt_pk_bf16_f32 v105, v142, v143
	v_cvt_pk_bf16_f32 v106, v150, v151
	v_cvt_pk_bf16_f32 v107, v148, v149
	v_add_f32_e32 v124, v160, v161
	v_add_f32_e32 v126, v162, v163
	global_store_dwordx4 v129, v[104:107], s[86:87]
	v_add_f32_e32 v125, v125, v127
	v_add_f32_e32 v127, v131, v133
	v_cvt_pk_bf16_f32 v104, v138, v139
	v_cvt_pk_bf16_f32 v105, v134, v135
	v_cvt_pk_bf16_f32 v106, v140, v141
	v_cvt_pk_bf16_f32 v107, v136, v137
	v_add_f32_e32 v124, v124, v126
	global_store_dwordx4 v164, v[104:107], s[16:17] nt
	v_pk_mul_f32 v[130:131], v[152:153], v[136:137]
	s_nop 0
	v_add_f32_e32 v104, v125, v127
	v_add_f32_e32 v125, v124, v104
	ds_bpermute_b32 v129, v144, v125
	v_pk_mul_f32 v[104:105], v[158:159], v[138:139]
	v_pk_mul_f32 v[126:127], v[154:155], v[140:141]
	v_cvt_pk_bf16_f32 v124, v104, v105
	v_pk_mul_f32 v[106:107], v[156:157], v[134:135]
	s_waitcnt lgkmcnt(0)
	v_add_f32_e32 v104, v125, v129
	ds_bpermute_b32 v105, v145, v104
	v_cvt_pk_bf16_f32 v125, v106, v107
	v_cvt_pk_bf16_f32 v126, v126, v127
	v_cvt_pk_bf16_f32 v127, v130, v131
	global_store_dwordx4 v164, v[124:127], s[86:87]
	s_and_saveexec_b64 s[26:27], s[0:1]
	s_cbranch_execz .LBB0_1480
	v_or_b32_e32 v106, 32, v184
	v_mov_b32_e32 v107, v179
	v_lshl_add_u64 v[106:107], v[106:107], 2, s[14:15]
	s_waitcnt lgkmcnt(0)
	v_add_f32_e32 v104, v104, v105
	global_atomic_add_f32 v[106:107], v104, off
.LBB0_1480:
	s_or_b64 exec, exec, s[26:27]
	s_waitcnt vmcnt(5)
	v_lshlrev_b32_e32 v124, 16, v120
	v_and_b32_e32 v125, 0xffff0000, v120
	v_lshlrev_b32_e32 v120, 16, v121
	v_and_b32_e32 v121, 0xffff0000, v121
	v_lshlrev_b32_e32 v126, 16, v122
	v_and_b32_e32 v127, 0xffff0000, v122
	v_lshlrev_b32_e32 v122, 16, v123
	v_and_b32_e32 v123, 0xffff0000, v123
	v_pk_add_f32 v[78:79], v[78:79], v[102:103]
	v_pk_add_f32 v[76:77], v[76:77], v[100:101]
	v_pk_add_f32 v[74:75], v[74:75], v[94:95]
	v_pk_add_f32 v[72:73], v[72:73], v[92:93]
	s_waitcnt lgkmcnt(0)
	v_lshl_add_u64 v[104:105], s[16:17], 0, v[178:179]
	v_pk_fma_f32 v[78:79], v[118:119], v[78:79], v[120:121]
	v_pk_fma_f32 v[76:77], v[116:117], v[76:77], v[124:125]
	v_pk_fma_f32 v[120:121], v[110:111], v[74:75], v[122:123]
	v_pk_fma_f32 v[122:123], v[108:109], v[72:73], v[126:127]
	v_cvt_pk_bf16_f32 v72, v76, v77
	v_cvt_pk_bf16_f32 v73, v78, v79
	v_mov_b32_e32 v129, v179
	v_cvt_pk_bf16_f32 v74, v122, v123
	v_cvt_pk_bf16_f32 v75, v120, v121
	global_store_dwordx4 v[104:105], v[72:75], off nt
	v_pk_add_f32 v[70:71], v[70:71], v[98:99]
	v_pk_add_f32 v[68:69], v[68:69], v[96:97]
	v_mul_f32_e32 v72, v77, v77
	v_mul_f32_e32 v73, v79, v79
	v_fmac_f32_e32 v72, v76, v76
	v_fmac_f32_e32 v73, v78, v78
	v_add_f32_e32 v72, v72, v73
	v_mul_f32_e32 v73, v123, v123
	v_mul_f32_e32 v74, v121, v121
	v_fmac_f32_e32 v73, v122, v122
	v_fmac_f32_e32 v74, v120, v120
	v_add_f32_e32 v73, v73, v74
	v_add_f32_e32 v104, v72, v73
	v_pk_mul_f32 v[74:75], v[190:191], v[78:79]
	v_pk_mul_f32 v[72:73], v[192:193], v[76:77]
	v_pk_mul_f32 v[76:77], v[186:187], v[120:121]
	v_pk_mul_f32 v[78:79], v[188:189], v[122:123]
	v_cvt_pk_bf16_f32 v72, v72, v73
	v_cvt_pk_bf16_f32 v73, v74, v75
	v_pk_add_f32 v[64:65], v[64:65], v[84:85]
	v_cvt_pk_bf16_f32 v74, v78, v79
	v_cvt_pk_bf16_f32 v75, v76, v77
	v_lshl_add_u64 v[76:77], s[86:87], 0, v[178:179]
	global_store_dwordx4 v[76:77], v[72:75], off
	s_waitcnt vmcnt(6)
	v_lshlrev_b32_e32 v76, 16, v114
	v_and_b32_e32 v77, 0xffff0000, v114
	v_lshlrev_b32_e32 v72, 16, v112
	v_and_b32_e32 v73, 0xffff0000, v112
	v_lshlrev_b32_e32 v74, 16, v113
	v_and_b32_e32 v75, 0xffff0000, v113
	v_lshl_add_u64 v[106:107], s[16:17], 0, v[128:129]
	v_lshlrev_b32_e32 v78, 16, v115
	v_and_b32_e32 v79, 0xffff0000, v115
	v_pk_fma_f32 v[70:71], v[90:91], v[70:71], v[74:75]
	v_pk_fma_f32 v[68:69], v[88:89], v[68:69], v[72:73]
	v_pk_add_f32 v[66:67], v[66:67], v[86:87]
	v_pk_fma_f32 v[74:75], v[80:81], v[64:65], v[76:77]
	v_cvt_pk_bf16_f32 v64, v68, v69
	v_cvt_pk_bf16_f32 v65, v70, v71
	v_pk_fma_f32 v[72:73], v[82:83], v[66:67], v[78:79]
	v_cvt_pk_bf16_f32 v66, v74, v75
	s_nop 0
	v_cvt_pk_bf16_f32 v67, v72, v73
	global_store_dwordx4 v[106:107], v[64:67], off nt
	s_nop 1
	v_mul_f32_e32 v64, v69, v69
	v_mul_f32_e32 v65, v71, v71
	v_fmac_f32_e32 v64, v68, v68
	v_fmac_f32_e32 v65, v70, v70
	v_add_f32_e32 v64, v64, v65
	v_mul_f32_e32 v65, v75, v75
	v_mul_f32_e32 v66, v73, v73
	v_fmac_f32_e32 v65, v74, v74
	v_fmac_f32_e32 v66, v72, v72
	v_add_f32_e32 v65, v65, v66
	v_add_f32_e32 v64, v64, v65
	v_add_f32_e32 v76, v104, v64
	ds_bpermute_b32 v77, v144, v76
	v_pk_mul_f32 v[64:65], v[156:157], v[70:71]
	v_pk_mul_f32 v[66:67], v[158:159], v[68:69]
	v_pk_mul_f32 v[70:71], v[152:153], v[72:73]
	v_cvt_pk_bf16_f32 v66, v66, v67
	v_cvt_pk_bf16_f32 v67, v64, v65
	s_waitcnt lgkmcnt(0)
	v_add_f32_e32 v64, v76, v77
	ds_bpermute_b32 v65, v145, v64
	v_pk_mul_f32 v[68:69], v[154:155], v[74:75]
	s_nop 0
	v_cvt_pk_bf16_f32 v68, v68, v69
	v_cvt_pk_bf16_f32 v69, v70, v71
	v_lshl_add_u64 v[70:71], s[86:87], 0, v[128:129]
	global_store_dwordx4 v[70:71], v[66:69], off
	s_and_saveexec_b64 s[26:27], s[0:1]
	s_cbranch_execz .LBB0_1482
	v_or_b32_e32 v178, 48, v184
	v_lshl_add_u64 v[66:67], v[178:179], 2, s[14:15]
	s_waitcnt lgkmcnt(0)
	v_add_f32_e32 v64, v64, v65
	global_atomic_add_f32 v[66:67], v64, off
;     __device__ __forceinline__ void operator()(const f32x4 (&acc)[2][2][4][2], const Unit& u, int wr, int wc, int fr, int fq) const {
;     ...
;         for (int rg = 0; rg < 8 / RGB; ++rg) {
;             u32x4 braw[INPLACE ? RGB : 1][2]; f32x4 bb[INPLACE ? 1 : RGB][2][2];
; #pragma unroll
;             for (int mm = 0; mm < RGB; ++mm) { const int q = rg * RGB + mm, ai = q >> 2, m = q & 3;
; #pragma unroll
;                 for (int bj = 0; bj < 2; ++bj) { const unsigned e = e0 + (unsigned)((ai * 128 + m * 16) * D + bj * 128);
;                     if constexpr (INPLACE) braw[mm][bj] = *(const u32x4*)(Hc + (size_t)(e * 2u));
;                     else { bb[mm][bj][0] = *(const f32x4*)(bsc + (size_t)(e * 4u)); bb[mm][bj][1] = *(const f32x4*)(bsc + (size_t)(e * 4u + 16u)); } } }
; #pragma unroll
;             for (int mm = 0; mm < RGB; ++mm) { const int q = rg * RGB + mm, ai = q >> 2, m = q & 3; float ssum = 0.f;
; #pragma unroll
;                 for (int bj = 0; bj < 2; ++bj) { const unsigned e = e0 + (unsigned)((ai * 128 + m * 16) * D + bj * 128);
;                     f32x4 r0, r1;
;                     if constexpr (INPLACE) { const u32x4 q4 = braw[mm][bj];
;                         r0 = (f32x4){__uint_as_float(q4[0] << 16), __uint_as_float(q4[0] & 0xffff0000u), __uint_as_float(q4[1] << 16), __uint_as_float(q4[1] & 0xffff0000u)};
;                         r1 = (f32x4){__uint_as_float(q4[2] << 16), __uint_as_float(q4[2] & 0xffff0000u), __uint_as_float(q4[3] << 16), __uint_as_float(q4[3] & 0xffff0000u)}; }
;                     else { r0 = bb[mm][bj][0]; r1 = bb[mm][bj][1]; }
;                     const f32x4 h0 = r0 + gv[bj][0] * (acc[ai][bj][m][0] + bv[bj][0]), h1 = r1 + gv[bj][1] * (acc[ai][bj][m][1] + bv[bj][1]);
;                     { u32x4 w; w.x = cvt_pk_bf16(h0[0], h0[1]); w.y = cvt_pk_bf16(h0[2], h0[3]); w.z = cvt_pk_bf16(h1[0], h1[1]); w.w = cvt_pk_bf16(h1[2], h1[3]); ST16(1, Hc + (size_t)(e * 2u), w); }
;                     if (FUSE) { ssum += ((h0[0] * h0[0] + h0[1] * h0[1]) + (h0[2] * h0[2] + h0[3] * h0[3])) + ((h1[0] * h1[0] + h1[1] * h1[1]) + (h1[2] * h1[2] + h1[3] * h1[3]));
;                         const f32x4 z0 = h0 * wv[bj][0], z1 = h1 * wv[bj][1];
;                         u32x4 w; w.x = cvt_pk_bf16(z0[0], z0[1]); w.y = cvt_pk_bf16(z0[2], z0[3]); w.z = cvt_pk_bf16(z1[0], z1[1]); w.w = cvt_pk_bf16(z1[2], z1[3]);
.LBB0_1482:
	s_or_b64 exec, exec, s[26:27]
	s_waitcnt lgkmcnt(0)
	v_add_u32_e32 v65, 0x40000, v202
	v_add_u32_e32 v122, 0x40100, v202
	global_load_dwordx4 v[66:69], v65, s[16:17]
	global_load_dwordx4 v[70:73], v122, s[16:17]
	v_add_u32_e32 v178, 0x48000, v202
	v_add_u32_e32 v64, 0x48100, v202
	v_pk_add_f32 v[74:75], v[56:57], v[92:93]
	v_pk_add_f32 v[76:77], v[54:55], v[98:99]
	v_pk_add_f32 v[78:79], v[52:53], v[96:97]
	v_pk_add_f32 v[104:105], v[50:51], v[86:87]
	global_load_dwordx4 v[54:57], v178, s[16:17]
	global_load_dwordx4 v[50:53], v64, s[16:17]
	v_pk_add_f32 v[62:63], v[62:63], v[102:103]
	v_pk_add_f32 v[60:61], v[60:61], v[100:101]
	v_pk_add_f32 v[58:59], v[58:59], v[94:95]
	v_pk_add_f32 v[48:49], v[48:49], v[84:85]
	s_waitcnt vmcnt(3)
	v_lshlrev_b32_e32 v106, 16, v66
	v_and_b32_e32 v107, 0xffff0000, v66
	v_lshlrev_b32_e32 v66, 16, v67
	v_and_b32_e32 v67, 0xffff0000, v67
	v_lshlrev_b32_e32 v112, 16, v68
	v_and_b32_e32 v113, 0xffff0000, v68
	v_lshlrev_b32_e32 v68, 16, v69
	v_and_b32_e32 v69, 0xffff0000, v69
	s_waitcnt vmcnt(2)
	v_lshlrev_b32_e32 v114, 16, v70
	v_and_b32_e32 v115, 0xffff0000, v70
	v_lshlrev_b32_e32 v70, 16, v71
	v_and_b32_e32 v71, 0xffff0000, v71
	v_lshlrev_b32_e32 v120, 16, v72
	v_and_b32_e32 v121, 0xffff0000, v72
	v_lshlrev_b32_e32 v72, 16, v73
	v_and_b32_e32 v73, 0xffff0000, v73
	v_pk_fma_f32 v[62:63], v[118:119], v[62:63], v[66:67]
	v_pk_fma_f32 v[66:67], v[116:117], v[60:61], v[106:107]
	v_pk_fma_f32 v[68:69], v[110:111], v[58:59], v[68:69]
	v_pk_fma_f32 v[74:75], v[108:109], v[74:75], v[112:113]
	v_pk_fma_f32 v[70:71], v[90:91], v[76:77], v[70:71]
	v_pk_fma_f32 v[76:77], v[88:89], v[78:79], v[114:115]
	v_pk_fma_f32 v[72:73], v[82:83], v[104:105], v[72:73]
	v_pk_fma_f32 v[48:49], v[80:81], v[48:49], v[120:121]
	v_cvt_pk_bf16_f32 v58, v66, v67
	v_cvt_pk_bf16_f32 v59, v62, v63
	v_cvt_pk_bf16_f32 v60, v74, v75
	v_cvt_pk_bf16_f32 v61, v68, v69
	v_mul_f32_e32 v114, v67, v67
	v_mul_f32_e32 v115, v63, v63
	v_mul_f32_e32 v120, v75, v75
	v_mul_f32_e32 v121, v69, v69
	v_pk_mul_f32 v[78:79], v[190:191], v[62:63]
	v_pk_mul_f32 v[104:105], v[192:193], v[66:67]
	v_pk_mul_f32 v[106:107], v[186:187], v[68:69]
	v_pk_mul_f32 v[112:113], v[188:189], v[74:75]
	v_mul_f32_e32 v63, v77, v77
	v_mul_f32_e32 v67, v71, v71
	v_mul_f32_e32 v69, v49, v49
	v_mul_f32_e32 v75, v73, v73
	global_store_dwordx4 v65, v[58:61], s[16:17] nt
	v_fmac_f32_e32 v114, v66, v66
	v_fmac_f32_e32 v115, v62, v62
	v_fmac_f32_e32 v120, v74, v74
	v_fmac_f32_e32 v121, v68, v68
	v_cvt_pk_bf16_f32 v58, v104, v105
	v_fmac_f32_e32 v63, v76, v76
	v_fmac_f32_e32 v67, v70, v70
	v_fmac_f32_e32 v69, v48, v48
	v_fmac_f32_e32 v75, v72, v72
	v_cvt_pk_bf16_f32 v59, v78, v79
	v_cvt_pk_bf16_f32 v60, v112, v113
	v_cvt_pk_bf16_f32 v61, v106, v107
	v_add_f32_e32 v62, v114, v115
	v_add_f32_e32 v66, v120, v121
	global_store_dwordx4 v65, v[58:61], s[86:87]
	v_add_f32_e32 v63, v63, v67
	v_add_f32_e32 v65, v69, v75
	v_cvt_pk_bf16_f32 v58, v76, v77
	v_cvt_pk_bf16_f32 v59, v70, v71
	v_cvt_pk_bf16_f32 v60, v48, v49
	v_cvt_pk_bf16_f32 v61, v72, v73
	v_add_f32_e32 v62, v62, v66
	global_store_dwordx4 v122, v[58:61], s[16:17] nt
	v_pk_mul_f32 v[66:67], v[154:155], v[48:49]
	s_nop 0
	v_add_f32_e32 v58, v63, v65
	v_add_f32_e32 v65, v62, v58
	ds_bpermute_b32 v68, v144, v65
	v_pk_mul_f32 v[60:61], v[156:157], v[70:71]
	v_pk_mul_f32 v[58:59], v[158:159], v[76:77]
	v_pk_mul_f32 v[62:63], v[152:153], v[72:73]
	v_cvt_pk_bf16_f32 v58, v58, v59
	s_waitcnt lgkmcnt(0)
	v_add_f32_e32 v48, v65, v68
	ds_bpermute_b32 v49, v145, v48
	v_cvt_pk_bf16_f32 v59, v60, v61
	v_cvt_pk_bf16_f32 v60, v66, v67
	v_cvt_pk_bf16_f32 v61, v62, v63
	global_store_dwordx4 v122, v[58:61], s[86:87]
	s_and_saveexec_b64 s[26:27], s[0:1]
	s_cbranch_execz .LBB0_1484
	v_add_u32_e32 v58, 0x80, v184
	v_mov_b32_e32 v59, v179
	v_lshl_add_u64 v[58:59], v[58:59], 2, s[14:15]
	s_waitcnt lgkmcnt(0)
	v_add_f32_e32 v48, v48, v49
	global_atomic_add_f32 v[58:59], v48, off
.LBB0_1484:
	s_or_b64 exec, exec, s[26:27]
	s_waitcnt vmcnt(5)
	v_lshlrev_b32_e32 v60, 16, v54
	v_and_b32_e32 v61, 0xffff0000, v54
	v_lshlrev_b32_e32 v54, 16, v55
	v_and_b32_e32 v55, 0xffff0000, v55
	v_lshlrev_b32_e32 v62, 16, v56
	v_and_b32_e32 v63, 0xffff0000, v56
	v_lshlrev_b32_e32 v56, 16, v57
	v_and_b32_e32 v57, 0xffff0000, v57
	v_pk_add_f32 v[46:47], v[46:47], v[102:103]
	v_pk_add_f32 v[44:45], v[44:45], v[100:101]
	v_pk_add_f32 v[42:43], v[42:43], v[94:95]
	v_pk_add_f32 v[40:41], v[40:41], v[92:93]
	s_waitcnt lgkmcnt(0)
	v_lshl_add_u64 v[48:49], s[16:17], 0, v[178:179]
	v_pk_fma_f32 v[46:47], v[118:119], v[46:47], v[54:55]
	v_pk_fma_f32 v[44:45], v[116:117], v[44:45], v[60:61]
	v_pk_fma_f32 v[54:55], v[110:111], v[42:43], v[56:57]
	v_pk_fma_f32 v[56:57], v[108:109], v[40:41], v[62:63]
	v_cvt_pk_bf16_f32 v40, v44, v45
	v_cvt_pk_bf16_f32 v41, v46, v47
	v_mov_b32_e32 v65, v179
	v_cvt_pk_bf16_f32 v42, v56, v57
	v_cvt_pk_bf16_f32 v43, v54, v55
	global_store_dwordx4 v[48:49], v[40:43], off nt
	v_pk_add_f32 v[38:39], v[38:39], v[98:99]
	v_pk_add_f32 v[36:37], v[36:37], v[96:97]
	v_mul_f32_e32 v40, v45, v45
	v_mul_f32_e32 v41, v47, v47
	v_fmac_f32_e32 v40, v44, v44
	v_fmac_f32_e32 v41, v46, v46
	v_add_f32_e32 v40, v40, v41
	v_mul_f32_e32 v41, v57, v57
	v_mul_f32_e32 v42, v55, v55
	v_fmac_f32_e32 v41, v56, v56
	v_fmac_f32_e32 v42, v54, v54
	v_add_f32_e32 v41, v41, v42
	v_add_f32_e32 v48, v40, v41
	v_pk_mul_f32 v[42:43], v[190:191], v[46:47]
	v_pk_mul_f32 v[40:41], v[192:193], v[44:45]
	v_pk_mul_f32 v[44:45], v[186:187], v[54:55]
	v_pk_mul_f32 v[46:47], v[188:189], v[56:57]
	v_cvt_pk_bf16_f32 v40, v40, v41
	v_cvt_pk_bf16_f32 v41, v42, v43
	v_pk_add_f32 v[32:33], v[32:33], v[84:85]
	v_cvt_pk_bf16_f32 v42, v46, v47
	v_cvt_pk_bf16_f32 v43, v44, v45
	v_lshl_add_u64 v[44:45], s[86:87], 0, v[178:179]
	global_store_dwordx4 v[44:45], v[40:43], off
	s_waitcnt vmcnt(6)
;     __device__ __forceinline__ void operator()(const f32x4 (&acc)[2][2][4][2], const Unit& u, int wr, int wc, int fr, int fq) const {
;     ...
;         for (int rg = 0; rg < 8 / RGB; ++rg) {
;             u32x4 braw[INPLACE ? RGB : 1][2]; f32x4 bb[INPLACE ? 1 : RGB][2][2];
; #pragma unroll
;             for (int mm = 0; mm < RGB; ++mm) { const int q = rg * RGB + mm, ai = q >> 2, m = q & 3;
; #pragma unroll
;                 for (int bj = 0; bj < 2; ++bj) { const unsigned e = e0 + (unsigned)((ai * 128 + m * 16) * D + bj * 128);
;                     if constexpr (INPLACE) braw[mm][bj] = *(const u32x4*)(Hc + (size_t)(e * 2u));
;                     else { bb[mm][bj][0] = *(const f32x4*)(bsc + (size_t)(e * 4u)); bb[mm][bj][1] = *(const f32x4*)(bsc + (size_t)(e * 4u + 16u)); } } }
; #pragma unroll
;             for (int mm = 0; mm < RGB; ++mm) { const int q = rg * RGB + mm, ai = q >> 2, m = q & 3; float ssum = 0.f;
; #pragma unroll
;                 for (int bj = 0; bj < 2; ++bj) { const unsigned e = e0 + (unsigned)((ai * 128 + m * 16) * D + bj * 128);
;                     f32x4 r0, r1;
;                     if constexpr (INPLACE) { const u32x4 q4 = braw[mm][bj];
;                         r0 = (f32x4){__uint_as_float(q4[0] << 16), __uint_as_float(q4[0] & 0xffff0000u), __uint_as_float(q4[1] << 16), __uint_as_float(q4[1] & 0xffff0000u)};
;                         r1 = (f32x4){__uint_as_float(q4[2] << 16), __uint_as_float(q4[2] & 0xffff0000u), __uint_as_float(q4[3] << 16), __uint_as_float(q4[3] & 0xffff0000u)}; }
;                     else { r0 = bb[mm][bj][0]; r1 = bb[mm][bj][1]; }
;                     const f32x4 h0 = r0 + gv[bj][0] * (acc[ai][bj][m][0] + bv[bj][0]), h1 = r1 + gv[bj][1] * (acc[ai][bj][m][1] + bv[bj][1]);
;                     { u32x4 w; w.x = cvt_pk_bf16(h0[0], h0[1]); w.y = cvt_pk_bf16(h0[2], h0[3]); w.z = cvt_pk_bf16(h1[0], h1[1]); w.w = cvt_pk_bf16(h1[2], h1[3]); ST16(1, Hc + (size_t)(e * 2u), w); }
;                     if (FUSE) { ssum += ((h0[0] * h0[0] + h0[1] * h0[1]) + (h0[2] * h0[2] + h0[3] * h0[3])) + ((h1[0] * h1[0] + h1[1] * h1[1]) + (h1[2] * h1[2] + h1[3] * h1[3]));
;                         const f32x4 z0 = h0 * wv[bj][0], z1 = h1 * wv[bj][1];
;                         u32x4 w; w.x = cvt_pk_bf16(z0[0], z0[1]); w.y = cvt_pk_bf16(z0[2], z0[3]); w.z = cvt_pk_bf16(z1[0], z1[1]); w.w = cvt_pk_bf16(z1[2], z1[3]);
	v_lshlrev_b32_e32 v44, 16, v52
	v_and_b32_e32 v45, 0xffff0000, v52
	v_lshlrev_b32_e32 v40, 16, v50
	v_and_b32_e32 v41, 0xffff0000, v50
	v_lshlrev_b32_e32 v42, 16, v51
	v_and_b32_e32 v43, 0xffff0000, v51
	v_lshl_add_u64 v[58:59], s[16:17], 0, v[64:65]
	v_lshlrev_b32_e32 v46, 16, v53
	v_and_b32_e32 v47, 0xffff0000, v53
	v_pk_fma_f32 v[38:39], v[90:91], v[38:39], v[42:43]
	v_pk_fma_f32 v[36:37], v[88:89], v[36:37], v[40:41]
	v_pk_add_f32 v[34:35], v[34:35], v[86:87]
	v_pk_fma_f32 v[42:43], v[80:81], v[32:33], v[44:45]
	v_cvt_pk_bf16_f32 v32, v36, v37
	v_cvt_pk_bf16_f32 v33, v38, v39
	v_pk_fma_f32 v[40:41], v[82:83], v[34:35], v[46:47]
	v_cvt_pk_bf16_f32 v34, v42, v43
	s_nop 0
	v_cvt_pk_bf16_f32 v35, v40, v41
	global_store_dwordx4 v[58:59], v[32:35], off nt
	s_nop 1
	v_mul_f32_e32 v32, v37, v37
	v_mul_f32_e32 v33, v39, v39
	v_fmac_f32_e32 v32, v36, v36
	v_fmac_f32_e32 v33, v38, v38
	v_add_f32_e32 v32, v32, v33
	v_mul_f32_e32 v33, v43, v43
	v_mul_f32_e32 v34, v41, v41
	v_fmac_f32_e32 v33, v42, v42
	v_fmac_f32_e32 v34, v40, v40
	v_add_f32_e32 v33, v33, v34
	v_add_f32_e32 v32, v32, v33
	v_add_f32_e32 v44, v48, v32
	ds_bpermute_b32 v45, v144, v44
	v_pk_mul_f32 v[32:33], v[156:157], v[38:39]
	v_pk_mul_f32 v[34:35], v[158:159], v[36:37]
	v_pk_mul_f32 v[38:39], v[152:153], v[40:41]
	v_cvt_pk_bf16_f32 v34, v34, v35
	v_cvt_pk_bf16_f32 v35, v32, v33
	s_waitcnt lgkmcnt(0)
	v_add_f32_e32 v32, v44, v45
	ds_bpermute_b32 v33, v145, v32
	v_pk_mul_f32 v[36:37], v[154:155], v[42:43]
	s_nop 0
	v_cvt_pk_bf16_f32 v36, v36, v37
	v_cvt_pk_bf16_f32 v37, v38, v39
	v_lshl_add_u64 v[38:39], s[86:87], 0, v[64:65]
	global_store_dwordx4 v[38:39], v[34:37], off
	s_and_saveexec_b64 s[26:27], s[0:1]
	s_cbranch_execz .LBB0_1486
	v_add_u32_e32 v178, 0x90, v184
	v_lshl_add_u64 v[34:35], v[178:179], 2, s[14:15]
	s_waitcnt lgkmcnt(0)
	v_add_f32_e32 v32, v32, v33
	global_atomic_add_f32 v[34:35], v32, off
.LBB0_1486:
	s_or_b64 exec, exec, s[26:27]
	s_waitcnt lgkmcnt(0)
	v_add_u32_e32 v33, 0x50000, v202
	v_add_u32_e32 v58, 0x50100, v202
	global_load_dwordx4 v[34:37], v33, s[16:17]
	global_load_dwordx4 v[38:41], v58, s[16:17]
	v_add_u32_e32 v178, 0x58000, v202
	v_add_u32_e32 v32, 0x58100, v202
	v_pk_add_f32 v[42:43], v[24:25], v[92:93]
	v_pk_add_f32 v[44:45], v[22:23], v[98:99]
	v_pk_add_f32 v[46:47], v[20:21], v[96:97]
	v_pk_add_f32 v[48:49], v[18:19], v[86:87]
	global_load_dwordx4 v[22:25], v178, s[16:17]
	global_load_dwordx4 v[18:21], v32, s[16:17]
	v_pk_add_f32 v[30:31], v[30:31], v[102:103]
	v_pk_add_f32 v[28:29], v[28:29], v[100:101]
	v_pk_add_f32 v[26:27], v[26:27], v[94:95]
	v_pk_add_f32 v[16:17], v[16:17], v[84:85]
	s_waitcnt vmcnt(3)
	v_lshlrev_b32_e32 v50, 16, v34
	v_and_b32_e32 v51, 0xffff0000, v34
	v_lshlrev_b32_e32 v34, 16, v35
	v_and_b32_e32 v35, 0xffff0000, v35
	v_lshlrev_b32_e32 v52, 16, v36
	v_and_b32_e32 v53, 0xffff0000, v36
	v_lshlrev_b32_e32 v36, 16, v37
	v_and_b32_e32 v37, 0xffff0000, v37
	s_waitcnt vmcnt(2)
	v_lshlrev_b32_e32 v54, 16, v38
	v_and_b32_e32 v55, 0xffff0000, v38
	v_lshlrev_b32_e32 v38, 16, v39
	v_and_b32_e32 v39, 0xffff0000, v39
	v_lshlrev_b32_e32 v56, 16, v40
	v_and_b32_e32 v57, 0xffff0000, v40
	v_lshlrev_b32_e32 v40, 16, v41
	v_and_b32_e32 v41, 0xffff0000, v41
	v_pk_fma_f32 v[30:31], v[118:119], v[30:31], v[34:35]
	v_pk_fma_f32 v[34:35], v[116:117], v[28:29], v[50:51]
	v_pk_fma_f32 v[36:37], v[110:111], v[26:27], v[36:37]
	v_pk_fma_f32 v[42:43], v[108:109], v[42:43], v[52:53]
	v_pk_fma_f32 v[38:39], v[90:91], v[44:45], v[38:39]
	v_pk_fma_f32 v[44:45], v[88:89], v[46:47], v[54:55]
	v_pk_fma_f32 v[40:41], v[82:83], v[48:49], v[40:41]
	v_pk_fma_f32 v[16:17], v[80:81], v[16:17], v[56:57]
	v_cvt_pk_bf16_f32 v26, v34, v35
	v_cvt_pk_bf16_f32 v27, v30, v31
	v_cvt_pk_bf16_f32 v28, v42, v43
	v_cvt_pk_bf16_f32 v29, v36, v37
	v_mul_f32_e32 v54, v35, v35
	v_mul_f32_e32 v55, v31, v31
	v_mul_f32_e32 v56, v43, v43
	v_mul_f32_e32 v57, v37, v37
	v_pk_mul_f32 v[46:47], v[190:191], v[30:31]
	v_pk_mul_f32 v[48:49], v[192:193], v[34:35]
	v_pk_mul_f32 v[50:51], v[186:187], v[36:37]
	v_pk_mul_f32 v[52:53], v[188:189], v[42:43]
	v_mul_f32_e32 v31, v45, v45
	v_mul_f32_e32 v35, v39, v39
	v_mul_f32_e32 v37, v17, v17
	v_mul_f32_e32 v43, v41, v41
	global_store_dwordx4 v33, v[26:29], s[16:17] nt
	v_fmac_f32_e32 v54, v34, v34
	v_fmac_f32_e32 v55, v30, v30
	v_fmac_f32_e32 v56, v42, v42
	v_fmac_f32_e32 v57, v36, v36
	v_cvt_pk_bf16_f32 v26, v48, v49
	v_fmac_f32_e32 v31, v44, v44
	v_fmac_f32_e32 v35, v38, v38
	v_fmac_f32_e32 v37, v16, v16
	v_fmac_f32_e32 v43, v40, v40
	v_cvt_pk_bf16_f32 v27, v46, v47
	v_cvt_pk_bf16_f32 v28, v52, v53
	v_cvt_pk_bf16_f32 v29, v50, v51
	v_add_f32_e32 v30, v54, v55
	v_add_f32_e32 v34, v56, v57
	global_store_dwordx4 v33, v[26:29], s[86:87]
	v_add_f32_e32 v31, v31, v35
	v_add_f32_e32 v33, v37, v43
	v_cvt_pk_bf16_f32 v26, v44, v45
	v_cvt_pk_bf16_f32 v27, v38, v39
	v_cvt_pk_bf16_f32 v28, v16, v17
	v_cvt_pk_bf16_f32 v29, v40, v41
	v_add_f32_e32 v30, v30, v34
	global_store_dwordx4 v58, v[26:29], s[16:17] nt
	v_pk_mul_f32 v[34:35], v[154:155], v[16:17]
	s_nop 0
	v_add_f32_e32 v26, v31, v33
	v_add_f32_e32 v33, v30, v26
	ds_bpermute_b32 v36, v144, v33
	v_pk_mul_f32 v[28:29], v[156:157], v[38:39]
	v_pk_mul_f32 v[26:27], v[158:159], v[44:45]
	v_pk_mul_f32 v[30:31], v[152:153], v[40:41]
	v_cvt_pk_bf16_f32 v26, v26, v27
	s_waitcnt lgkmcnt(0)
	v_add_f32_e32 v16, v33, v36
	ds_bpermute_b32 v17, v145, v16
	v_cvt_pk_bf16_f32 v27, v28, v29
	v_cvt_pk_bf16_f32 v28, v34, v35
	v_cvt_pk_bf16_f32 v29, v30, v31
	global_store_dwordx4 v58, v[26:29], s[86:87]
	s_and_saveexec_b64 s[26:27], s[0:1]
	s_cbranch_execz .LBB0_1488
	v_add_u32_e32 v26, 0xa0, v184
	v_mov_b32_e32 v27, v179
	v_lshl_add_u64 v[26:27], v[26:27], 2, s[14:15]
	s_waitcnt lgkmcnt(0)
	v_add_f32_e32 v16, v16, v17
	global_atomic_add_f32 v[26:27], v16, off
; __device__ __forceinline__ unsigned cvt_pk_bf16(float lo, float hi) { unsigned r; asm volatile("v_cvt_pk_bf16_f32 %0, %1, %2" : "=v"(r) : "v"(lo), "v"(hi)); return r; }
; #define ST16(grp, p, v) do { if ((NTG >> (grp)) & 1) NT16(p, v); else PL16(p, v); } while (0)
;     __device__ __forceinline__ void operator()(const f32x4 (&acc)[2][2][4][2], const Unit& u, int wr, int wc, int fr, int fq) const {
;     ...
;             for (int mm = 0; mm < RGB; ++mm) { const int q = rg * RGB + mm, ai = q >> 2, m = q & 3; float ssum = 0.f;
; #pragma unroll
;                 for (int bj = 0; bj < 2; ++bj) { const unsigned e = e0 + (unsigned)((ai * 128 + m * 16) * D + bj * 128);
;                     f32x4 r0, r1;
;                     if constexpr (INPLACE) { const u32x4 q4 = braw[mm][bj];
;                         r0 = (f32x4){__uint_as_float(q4[0] << 16), __uint_as_float(q4[0] & 0xffff0000u), __uint_as_float(q4[1] << 16), __uint_as_float(q4[1] & 0xffff0000u)};
;                         r1 = (f32x4){__uint_as_float(q4[2] << 16), __uint_as_float(q4[2] & 0xffff0000u), __uint_as_float(q4[3] << 16), __uint_as_float(q4[3] & 0xffff0000u)}; }
;                     else { r0 = bb[mm][bj][0]; r1 = bb[mm][bj][1]; }
;                     const f32x4 h0 = r0 + gv[bj][0] * (acc[ai][bj][m][0] + bv[bj][0]), h1 = r1 + gv[bj][1] * (acc[ai][bj][m][1] + bv[bj][1]);
;                     { u32x4 w; w.x = cvt_pk_bf16(h0[0], h0[1]); w.y = cvt_pk_bf16(h0[2], h0[3]); w.z = cvt_pk_bf16(h1[0], h1[1]); w.w = cvt_pk_bf16(h1[2], h1[3]); ST16(1, Hc + (size_t)(e * 2u), w); }
;                     if (FUSE) { ssum += ((h0[0] * h0[0] + h0[1] * h0[1]) + (h0[2] * h0[2] + h0[3] * h0[3])) + ((h1[0] * h1[0] + h1[1] * h1[1]) + (h1[2] * h1[2] + h1[3] * h1[3]));
;                         const f32x4 z0 = h0 * wv[bj][0], z1 = h1 * wv[bj][1];
;                         u32x4 w; w.x = cvt_pk_bf16(z0[0], z0[1]); w.y = cvt_pk_bf16(z0[2], z0[3]); w.z = cvt_pk_bf16(z1[0], z1[1]); w.w = cvt_pk_bf16(z1[2], z1[3]);
;                         ST16(2, HBc + (size_t)(e * 2u), w); } }
;                 if (FUSE) { ssum += __shfl_xor(ssum, 16); ssum += __shfl_xor(ssum, 32); if (fq == 0) unsafeAtomicAdd(SSn + (unsigned)(row0 + ai * 128 + m * 16), ssum); } }
;             asm volatile("" ::: "memory"); }
.LBB0_1488:
	s_or_b64 exec, exec, s[26:27]
	s_waitcnt vmcnt(5)
	v_lshlrev_b32_e32 v28, 16, v22
	v_and_b32_e32 v29, 0xffff0000, v22
	v_lshlrev_b32_e32 v22, 16, v23
	v_and_b32_e32 v23, 0xffff0000, v23
	v_lshlrev_b32_e32 v30, 16, v24
	v_and_b32_e32 v31, 0xffff0000, v24
	v_lshlrev_b32_e32 v24, 16, v25
	v_and_b32_e32 v25, 0xffff0000, v25
	v_pk_add_f32 v[14:15], v[14:15], v[102:103]
	v_pk_add_f32 v[12:13], v[12:13], v[100:101]
	v_pk_add_f32 v[10:11], v[10:11], v[94:95]
	v_pk_add_f32 v[8:9], v[8:9], v[92:93]
	s_waitcnt lgkmcnt(0)
	v_lshl_add_u64 v[16:17], s[16:17], 0, v[178:179]
	v_pk_fma_f32 v[14:15], v[118:119], v[14:15], v[22:23]
	v_pk_fma_f32 v[12:13], v[116:117], v[12:13], v[28:29]
	v_pk_fma_f32 v[22:23], v[110:111], v[10:11], v[24:25]
	v_pk_fma_f32 v[24:25], v[108:109], v[8:9], v[30:31]
	v_cvt_pk_bf16_f32 v8, v12, v13
	v_cvt_pk_bf16_f32 v9, v14, v15
	v_mov_b32_e32 v33, v179
	v_cvt_pk_bf16_f32 v10, v24, v25
	v_cvt_pk_bf16_f32 v11, v22, v23
	global_store_dwordx4 v[16:17], v[8:11], off nt
	v_pk_add_f32 v[6:7], v[6:7], v[98:99]
	v_pk_add_f32 v[4:5], v[4:5], v[96:97]
	v_mul_f32_e32 v8, v13, v13
	v_mul_f32_e32 v9, v15, v15
	v_fmac_f32_e32 v8, v12, v12
	v_fmac_f32_e32 v9, v14, v14
	v_add_f32_e32 v8, v8, v9
	v_mul_f32_e32 v9, v25, v25
	v_mul_f32_e32 v10, v23, v23
	v_fmac_f32_e32 v9, v24, v24
	v_fmac_f32_e32 v10, v22, v22
	v_add_f32_e32 v9, v9, v10
	v_add_f32_e32 v16, v8, v9
	v_pk_mul_f32 v[10:11], v[190:191], v[14:15]
	v_pk_mul_f32 v[8:9], v[192:193], v[12:13]
	v_pk_mul_f32 v[12:13], v[186:187], v[22:23]
	v_pk_mul_f32 v[14:15], v[188:189], v[24:25]
	v_cvt_pk_bf16_f32 v8, v8, v9
	v_cvt_pk_bf16_f32 v9, v10, v11
	v_pk_add_f32 v[0:1], v[0:1], v[84:85]
	v_cvt_pk_bf16_f32 v10, v14, v15
	v_cvt_pk_bf16_f32 v11, v12, v13
	v_lshl_add_u64 v[12:13], s[86:87], 0, v[178:179]
	global_store_dwordx4 v[12:13], v[8:11], off
	s_waitcnt vmcnt(6)
	v_lshlrev_b32_e32 v12, 16, v20
	v_and_b32_e32 v13, 0xffff0000, v20
	v_lshlrev_b32_e32 v8, 16, v18
	v_and_b32_e32 v9, 0xffff0000, v18
	v_lshlrev_b32_e32 v10, 16, v19
	v_and_b32_e32 v11, 0xffff0000, v19
	v_lshl_add_u64 v[26:27], s[16:17], 0, v[32:33]
	v_lshlrev_b32_e32 v14, 16, v21
	v_and_b32_e32 v15, 0xffff0000, v21
	v_pk_fma_f32 v[6:7], v[90:91], v[6:7], v[10:11]
	v_pk_fma_f32 v[4:5], v[88:89], v[4:5], v[8:9]
	v_pk_add_f32 v[2:3], v[2:3], v[86:87]
	v_pk_fma_f32 v[10:11], v[80:81], v[0:1], v[12:13]
	v_cvt_pk_bf16_f32 v0, v4, v5
	v_cvt_pk_bf16_f32 v1, v6, v7
	v_pk_fma_f32 v[8:9], v[82:83], v[2:3], v[14:15]
	v_cvt_pk_bf16_f32 v2, v10, v11
	s_nop 0
	v_cvt_pk_bf16_f32 v3, v8, v9
	global_store_dwordx4 v[26:27], v[0:3], off nt
	s_nop 1
	v_mul_f32_e32 v0, v5, v5
	v_mul_f32_e32 v1, v7, v7
	v_fmac_f32_e32 v0, v4, v4
	v_fmac_f32_e32 v1, v6, v6
	v_add_f32_e32 v0, v0, v1
	v_mul_f32_e32 v1, v11, v11
	v_mul_f32_e32 v2, v9, v9
	v_fmac_f32_e32 v1, v10, v10
	v_fmac_f32_e32 v2, v8, v8
	v_add_f32_e32 v1, v1, v2
	v_add_f32_e32 v0, v0, v1
	v_add_f32_e32 v12, v16, v0
	ds_bpermute_b32 v13, v144, v12
	v_pk_mul_f32 v[0:1], v[156:157], v[6:7]
	v_pk_mul_f32 v[2:3], v[158:159], v[4:5]
	v_pk_mul_f32 v[6:7], v[152:153], v[8:9]
	v_cvt_pk_bf16_f32 v2, v2, v3
	v_cvt_pk_bf16_f32 v3, v0, v1
	s_waitcnt lgkmcnt(0)
	v_add_f32_e32 v0, v12, v13
	ds_bpermute_b32 v1, v145, v0
	v_pk_mul_f32 v[4:5], v[154:155], v[10:11]
	s_nop 0
	v_cvt_pk_bf16_f32 v4, v4, v5
	v_cvt_pk_bf16_f32 v5, v6, v7
	v_lshl_add_u64 v[6:7], s[86:87], 0, v[32:33]
	global_store_dwordx4 v[6:7], v[2:5], off
	s_and_saveexec_b64 s[26:27], s[0:1]
	s_cbranch_execz .LBB0_1490
	v_add_u32_e32 v178, 0xb0, v184
	v_lshl_add_u64 v[2:3], v[178:179], 2, s[14:15]
	s_waitcnt lgkmcnt(0)
	v_add_f32_e32 v0, v0, v1
	global_atomic_add_f32 v[2:3], v0, off
